# v21 plus: K-loop load segments issue the LDS-DMA loads (and their M0/address set-up) before the ds_reads
# baseline (speedup 1.0000x reference)
; #define PG8_STAGE(bufoff, gbase, voff) do { _Pragma("unroll") for (int _i = 0; _i < 2; ++_i) \
;         __builtin_amdgcn_global_load_lds((const unsigned*)((const char*)(gbase) + (voff)[_i]), (PG8_LAS unsigned*)(lds + (bufoff) + ldsw + _i * 8192), 16, 0, 0); } while (0)
; #define PG8_LDA(dst, b, h) do { _Pragma("unroll") for (int m = 0; m < 4; ++m) _Pragma("unroll") for (int k = 0; k < 2; ++k) dst[m][k] = *(const PG8_LAS bf16x8*)(lds + PG8_SA(b, h) + aoff + m * 2048 + k * 1024); } while (0)
; #define PG8_LDB(dst, b, h) do { _Pragma("unroll") for (int n = 0; n < 2; ++n) _Pragma("unroll") for (int k = 0; k < 2; ++k) dst[n][k] = *(const PG8_LAS bf16x8*)(lds + PG8_SB(b, h) + boff + n * 2048 + k * 1024); } while (0)
; #define PG8_MMA(ai, bj, At, Bt) do { __builtin_amdgcn_s_setprio(1); _Pragma("unroll") for (int m = 0; m < 4; ++m) _Pragma("unroll") for (int n = 0; n < 2; ++n) _Pragma("unroll") for (int k = 0; k < 2; ++k) \
;         acc[ai][bj][m][n] = __builtin_amdgcn_mfma_f32_16x16x32_bf16(Bt[n][k], At[m][k], acc[ai][bj][m][n], 0, 0, 0); __builtin_amdgcn_s_setprio(0); } while (0)
; #define PG8_WAIT_V(n) asm volatile("s_waitcnt vmcnt(" #n ")" ::: "memory")
; #define PG8_WAIT_L(n) asm volatile("s_waitcnt lgkmcnt(" #n ")" ::: "memory")
; #define PG8_BAR __builtin_amdgcn_s_barrier()
; #define PG8_SCHED __builtin_amdgcn_sched_barrier(0)
; template <class Epi, class Sched, bool ALIGN_EPI = false, bool SP2 = false>
; __device__ __forceinline__ void gemm_phase(PG8_LAS unsigned char* lds, const Gemm g, const Sched& S, const Epi& E, const int tid_in) {
;     ...
;             PG8_LDB(B0, 0, 0); PG8_LDB(B1, 0, 1); PG8_SCHED; PG8_LDA(At, 0, 0); PG8_STAGE(PG8_SA(1, 1), a1 + hstepA, voffA);
;             PG8_WAIT_V(8); PG8_WAIT_L(0); PG8_BAR; PG8_MMA(0, 0, At, B0); PG8_MMA(0, 1, At, B1); PG8_BAR; PG8_SCHED;
;             PG8_LDA(At, 0, 1); PG8_STAGE(PG8_SB(0, 0), b2, voffB); PG8_STAGE(PG8_SB(0, 1), b2 + hstepB, voffB); PG8_STAGE(PG8_SA(0, 0), a2, voffA);
;             PG8_WAIT_V(8); PG8_WAIT_L(0); PG8_BAR; PG8_MMA(1, 0, At, B0); PG8_MMA(1, 1, At, B1); PG8_BAR; PG8_SCHED;
.LBB0_476:
	s_add_u32 s22, s52, 0xfff80080
	s_addc_u32 s23, s53, -1
	s_add_i32 s45, 0, 0x10000
	s_cmp_eq_u32 s43, 28
	s_cselect_b32 s55, s6, s23
	s_cselect_b32 s54, s11, s22
	s_cselect_b32 s23, s12, s35
	s_cselect_b32 s22, s33, s34
	s_add_i32 s47, 0, 0x14000
	s_add_i32 m0, s21, 0xc000
	s_nop 0
	global_load_lds_dwordx4 v134, s[52:53]
	s_add_i32 m0, s21, 0xe000
	s_nop 0
	global_load_lds_dwordx4 v136, s[52:53]
	ds_read_b128 v[138:141], v249
	ds_read_b128 v[150:153], v249 offset:1024
	ds_read_b128 v[154:157], v249 offset:2048
	ds_read_b128 v[158:161], v249 offset:3072
	ds_read_b128 v[162:165], v249 offset:16384
	ds_read_b128 v[166:169], v249 offset:17408
	ds_read_b128 v[190:193], v249 offset:18432
	ds_read_b128 v[194:197], v249 offset:19456
	ds_read_b128 v[198:201], v148
	ds_read_b128 v[202:205], v148 offset:1024
	ds_read_b128 v[206:209], v148 offset:2048
	ds_read_b128 v[210:213], v148 offset:3072
	ds_read_b128 v[224:227], v148 offset:4096
	ds_read_b128 v[228:231], v148 offset:5120
	ds_read_b128 v[232:235], v148 offset:6144
	ds_read_b128 v[236:239], v148 offset:7168
	s_waitcnt vmcnt(8) lgkmcnt(0)
	s_barrier
	v_mfma_f32_16x16x32_bf16 v[124:127], v[138:141], v[198:201], v[124:127]
	v_mfma_f32_16x16x32_bf16 v[120:123], v[154:157], v[198:201], v[120:123]
	v_mfma_f32_16x16x32_bf16 v[108:111], v[138:141], v[206:209], v[108:111]
	v_mfma_f32_16x16x32_bf16 v[104:107], v[154:157], v[206:209], v[104:107]
	v_mfma_f32_16x16x32_bf16 v[92:95], v[138:141], v[224:227], v[92:95]
	v_mfma_f32_16x16x32_bf16 v[88:91], v[154:157], v[224:227], v[88:91]
	v_mfma_f32_16x16x32_bf16 v[76:79], v[138:141], v[232:235], v[76:79]
	v_mfma_f32_16x16x32_bf16 v[72:75], v[154:157], v[232:235], v[72:75]
	v_mfma_f32_16x16x32_bf16 v[124:127], v[150:153], v[202:205], v[124:127]
	v_mfma_f32_16x16x32_bf16 v[120:123], v[158:161], v[202:205], v[120:123]
	v_mfma_f32_16x16x32_bf16 v[108:111], v[150:153], v[210:213], v[108:111]
	v_mfma_f32_16x16x32_bf16 v[104:107], v[158:161], v[210:213], v[104:107]
	v_mfma_f32_16x16x32_bf16 v[92:95], v[150:153], v[228:231], v[92:95]
	v_mfma_f32_16x16x32_bf16 v[88:91], v[158:161], v[228:231], v[88:91]
	v_mfma_f32_16x16x32_bf16 v[76:79], v[150:153], v[236:239], v[76:79]
	v_mfma_f32_16x16x32_bf16 v[72:75], v[158:161], v[236:239], v[72:75]
	v_mfma_f32_16x16x32_bf16 v[116:119], v[162:165], v[198:201], v[116:119]
	v_mfma_f32_16x16x32_bf16 v[112:115], v[190:193], v[198:201], v[112:115]
	v_mfma_f32_16x16x32_bf16 v[100:103], v[162:165], v[206:209], v[100:103]
	v_mfma_f32_16x16x32_bf16 v[96:99], v[190:193], v[206:209], v[96:99]
	v_mfma_f32_16x16x32_bf16 v[84:87], v[162:165], v[224:227], v[84:87]
	v_mfma_f32_16x16x32_bf16 v[80:83], v[190:193], v[224:227], v[80:83]
	v_mfma_f32_16x16x32_bf16 v[68:71], v[162:165], v[232:235], v[68:71]
	v_mfma_f32_16x16x32_bf16 v[64:67], v[190:193], v[232:235], v[64:67]
	v_mfma_f32_16x16x32_bf16 v[116:119], v[166:169], v[202:205], v[116:119]
	v_mfma_f32_16x16x32_bf16 v[112:115], v[194:197], v[202:205], v[112:115]
	v_mfma_f32_16x16x32_bf16 v[100:103], v[166:169], v[210:213], v[100:103]
	v_mfma_f32_16x16x32_bf16 v[96:99], v[194:197], v[210:213], v[96:99]
	v_mfma_f32_16x16x32_bf16 v[84:87], v[166:169], v[228:231], v[84:87]
	v_mfma_f32_16x16x32_bf16 v[80:83], v[194:197], v[228:231], v[80:83]
	v_mfma_f32_16x16x32_bf16 v[68:71], v[166:169], v[236:239], v[68:71]
	v_mfma_f32_16x16x32_bf16 v[64:67], v[194:197], v[236:239], v[64:67]
	s_barrier
	s_add_i32 s45, s45, s20
	s_mov_b32 m0, s45
	s_nop 0
	global_load_lds_dwordx4 v172, s[22:23]
	s_add_i32 m0, s45, 0x2000
	s_add_u32 s60, s22, 0x80000
	s_addc_u32 s61, s23, 0
	s_add_i32 s45, s47, s20
	global_load_lds_dwordx4 v132, s[22:23]
	s_mov_b32 m0, s45
	s_nop 0
	global_load_lds_dwordx4 v172, s[60:61]
	s_add_i32 m0, s45, 0x2000
	s_nop 0
	global_load_lds_dwordx4 v132, s[60:61]
	s_mov_b32 m0, s21
	s_nop 0
	global_load_lds_dwordx4 v128, s[54:55]
	s_mov_b32 m0, s30
	s_nop 0
	global_load_lds_dwordx4 v130, s[54:55]
	ds_read_b128 v[198:201], v148 offset:16384
	ds_read_b128 v[202:205], v148 offset:17408
	ds_read_b128 v[206:209], v148 offset:18432
	ds_read_b128 v[210:213], v148 offset:19456
	ds_read_b128 v[224:227], v148 offset:20480
	ds_read_b128 v[228:231], v148 offset:21504
	ds_read_b128 v[232:235], v148 offset:22528
	ds_read_b128 v[236:239], v148 offset:23552
	s_waitcnt vmcnt(8) lgkmcnt(0)
	s_barrier
	v_mfma_f32_16x16x32_bf16 v[60:63], v[138:141], v[198:201], v[60:63]
	v_mfma_f32_16x16x32_bf16 v[56:59], v[154:157], v[198:201], v[56:59]
	v_mfma_f32_16x16x32_bf16 v[44:47], v[138:141], v[206:209], v[44:47]
	v_mfma_f32_16x16x32_bf16 v[40:43], v[154:157], v[206:209], v[40:43]
	v_mfma_f32_16x16x32_bf16 v[28:31], v[138:141], v[224:227], v[28:31]
	v_mfma_f32_16x16x32_bf16 v[24:27], v[154:157], v[224:227], v[24:27]
	v_mfma_f32_16x16x32_bf16 v[12:15], v[138:141], v[232:235], v[12:15]
	v_mfma_f32_16x16x32_bf16 v[8:11], v[154:157], v[232:235], v[8:11]
	v_mfma_f32_16x16x32_bf16 v[60:63], v[150:153], v[202:205], v[60:63]
	v_mfma_f32_16x16x32_bf16 v[56:59], v[158:161], v[202:205], v[56:59]
	v_mfma_f32_16x16x32_bf16 v[44:47], v[150:153], v[210:213], v[44:47]
	v_mfma_f32_16x16x32_bf16 v[40:43], v[158:161], v[210:213], v[40:43]
	v_mfma_f32_16x16x32_bf16 v[28:31], v[150:153], v[228:231], v[28:31]
	v_mfma_f32_16x16x32_bf16 v[24:27], v[158:161], v[228:231], v[24:27]
	v_mfma_f32_16x16x32_bf16 v[12:15], v[150:153], v[236:239], v[12:15]
	v_mfma_f32_16x16x32_bf16 v[8:11], v[158:161], v[236:239], v[8:11]
	v_mfma_f32_16x16x32_bf16 v[52:55], v[162:165], v[198:201], v[52:55]
	v_mfma_f32_16x16x32_bf16 v[48:51], v[190:193], v[198:201], v[48:51]
	v_mfma_f32_16x16x32_bf16 v[36:39], v[162:165], v[206:209], v[36:39]
	v_mfma_f32_16x16x32_bf16 v[32:35], v[190:193], v[206:209], v[32:35]
	v_mfma_f32_16x16x32_bf16 v[20:23], v[162:165], v[224:227], v[20:23]
	v_mfma_f32_16x16x32_bf16 v[16:19], v[190:193], v[224:227], v[16:19]
	v_mfma_f32_16x16x32_bf16 v[4:7], v[162:165], v[232:235], v[4:7]
	v_mfma_f32_16x16x32_bf16 v[0:3], v[190:193], v[232:235], v[0:3]
	v_mfma_f32_16x16x32_bf16 v[52:55], v[166:169], v[202:205], v[52:55]
	v_mfma_f32_16x16x32_bf16 v[48:51], v[194:197], v[202:205], v[48:51]
	v_mfma_f32_16x16x32_bf16 v[36:39], v[166:169], v[210:213], v[36:39]
	v_mfma_f32_16x16x32_bf16 v[32:35], v[194:197], v[210:213], v[32:35]
	v_mfma_f32_16x16x32_bf16 v[20:23], v[166:169], v[228:231], v[20:23]
	v_mfma_f32_16x16x32_bf16 v[16:19], v[194:197], v[228:231], v[16:19]
	v_mfma_f32_16x16x32_bf16 v[4:7], v[166:169], v[236:239], v[4:7]
	v_mfma_f32_16x16x32_bf16 v[0:3], v[194:197], v[236:239], v[0:3]
	s_barrier
; #define PG8_STAGE(bufoff, gbase, voff) do { _Pragma("unroll") for (int _i = 0; _i < 2; ++_i) \
;         __builtin_amdgcn_global_load_lds((const unsigned*)((const char*)(gbase) + (voff)[_i]), (PG8_LAS unsigned*)(lds + (bufoff) + ldsw + _i * 8192), 16, 0, 0); } while (0)
; #define PG8_LDA(dst, b, h) do { _Pragma("unroll") for (int m = 0; m < 4; ++m) _Pragma("unroll") for (int k = 0; k < 2; ++k) dst[m][k] = *(const PG8_LAS bf16x8*)(lds + PG8_SA(b, h) + aoff + m * 2048 + k * 1024); } while (0)
; #define PG8_LDB(dst, b, h) do { _Pragma("unroll") for (int n = 0; n < 2; ++n) _Pragma("unroll") for (int k = 0; k < 2; ++k) dst[n][k] = *(const PG8_LAS bf16x8*)(lds + PG8_SB(b, h) + boff + n * 2048 + k * 1024); } while (0)
; #define PG8_MMA(ai, bj, At, Bt) do { __builtin_amdgcn_s_setprio(1); _Pragma("unroll") for (int m = 0; m < 4; ++m) _Pragma("unroll") for (int n = 0; n < 2; ++n) _Pragma("unroll") for (int k = 0; k < 2; ++k) \
;         acc[ai][bj][m][n] = __builtin_amdgcn_mfma_f32_16x16x32_bf16(Bt[n][k], At[m][k], acc[ai][bj][m][n], 0, 0, 0); __builtin_amdgcn_s_setprio(0); } while (0)
; #define PG8_WAIT_V(n) asm volatile("s_waitcnt vmcnt(" #n ")" ::: "memory")
; #define PG8_WAIT_L(n) asm volatile("s_waitcnt lgkmcnt(" #n ")" ::: "memory")
; #define PG8_BAR __builtin_amdgcn_s_barrier()
; #define PG8_SCHED __builtin_amdgcn_sched_barrier(0)
; template <class Epi, class Sched, bool ALIGN_EPI = false, bool SP2 = false>
; __device__ __forceinline__ void gemm_phase(PG8_LAS unsigned char* lds, const Gemm g, const Sched& S, const Epi& E, const int tid_in) {
;     ...
;             PG8_LDB(B0, 1, 0); PG8_LDB(B1, 1, 1); PG8_SCHED; PG8_LDA(At, 1, 0); PG8_STAGE(PG8_SA(0, 1), a2 + hstepA, voffA);
;             PG8_WAIT_V(8); PG8_WAIT_L(0); PG8_BAR; PG8_MMA(0, 0, At, B0); PG8_MMA(0, 1, At, B1); PG8_BAR; PG8_SCHED;
;             PG8_LDA(At, 1, 1); PG8_STAGE(PG8_SB(1, 0), b3, voffB); PG8_STAGE(PG8_SB(1, 1), b3 + hstepB, voffB); PG8_STAGE(PG8_SA(1, 0), a3, voffA);
;             PG8_WAIT_V(8); PG8_WAIT_L(0); PG8_BAR; PG8_MMA(1, 0, At, B0); PG8_MMA(1, 1, At, B1); PG8_BAR; PG8_SCHED;
	s_add_i32 s45, 0, 0x18000
	s_add_i32 s47, 0, 0x1c000
	s_add_u32 s54, s54, 0x80000
	s_addc_u32 s55, s55, 0
	s_mov_b32 m0, s31
	s_nop 0
	global_load_lds_dwordx4 v128, s[54:55]
	s_mov_b32 m0, s37
	s_nop 0
	global_load_lds_dwordx4 v130, s[54:55]
	ds_read_b128 v[138:141], v249 offset:32768
	ds_read_b128 v[150:153], v249 offset:33792
	ds_read_b128 v[154:157], v249 offset:34816
	ds_read_b128 v[158:161], v249 offset:35840
	ds_read_b128 v[162:165], v249 offset:49152
	ds_read_b128 v[166:169], v249 offset:50176
	ds_read_b128 v[190:193], v249 offset:51200
	ds_read_b128 v[194:197], v249 offset:52224
	ds_read_b128 v[198:201], v148 offset:32768
	ds_read_b128 v[202:205], v148 offset:33792
	ds_read_b128 v[206:209], v148 offset:34816
	ds_read_b128 v[210:213], v148 offset:35840
	ds_read_b128 v[224:227], v148 offset:36864
	ds_read_b128 v[228:231], v148 offset:37888
	ds_read_b128 v[232:235], v148 offset:38912
	ds_read_b128 v[236:239], v148 offset:39936
	s_waitcnt vmcnt(8) lgkmcnt(0)
	s_barrier
	v_mfma_f32_16x16x32_bf16 v[124:127], v[138:141], v[198:201], v[124:127]
	v_mfma_f32_16x16x32_bf16 v[120:123], v[154:157], v[198:201], v[120:123]
	v_mfma_f32_16x16x32_bf16 v[108:111], v[138:141], v[206:209], v[108:111]
	v_mfma_f32_16x16x32_bf16 v[104:107], v[154:157], v[206:209], v[104:107]
	v_mfma_f32_16x16x32_bf16 v[92:95], v[138:141], v[224:227], v[92:95]
	v_mfma_f32_16x16x32_bf16 v[88:91], v[154:157], v[224:227], v[88:91]
	v_mfma_f32_16x16x32_bf16 v[76:79], v[138:141], v[232:235], v[76:79]
	v_mfma_f32_16x16x32_bf16 v[72:75], v[154:157], v[232:235], v[72:75]
	v_mfma_f32_16x16x32_bf16 v[124:127], v[150:153], v[202:205], v[124:127]
	v_mfma_f32_16x16x32_bf16 v[120:123], v[158:161], v[202:205], v[120:123]
	v_mfma_f32_16x16x32_bf16 v[108:111], v[150:153], v[210:213], v[108:111]
	v_mfma_f32_16x16x32_bf16 v[104:107], v[158:161], v[210:213], v[104:107]
	v_mfma_f32_16x16x32_bf16 v[92:95], v[150:153], v[228:231], v[92:95]
	v_mfma_f32_16x16x32_bf16 v[88:91], v[158:161], v[228:231], v[88:91]
	v_mfma_f32_16x16x32_bf16 v[76:79], v[150:153], v[236:239], v[76:79]
	v_mfma_f32_16x16x32_bf16 v[72:75], v[158:161], v[236:239], v[72:75]
	v_mfma_f32_16x16x32_bf16 v[116:119], v[162:165], v[198:201], v[116:119]
	v_mfma_f32_16x16x32_bf16 v[112:115], v[190:193], v[198:201], v[112:115]
	v_mfma_f32_16x16x32_bf16 v[100:103], v[162:165], v[206:209], v[100:103]
	v_mfma_f32_16x16x32_bf16 v[96:99], v[190:193], v[206:209], v[96:99]
	v_mfma_f32_16x16x32_bf16 v[84:87], v[162:165], v[224:227], v[84:87]
	v_mfma_f32_16x16x32_bf16 v[80:83], v[190:193], v[224:227], v[80:83]
	v_mfma_f32_16x16x32_bf16 v[68:71], v[162:165], v[232:235], v[68:71]
	v_mfma_f32_16x16x32_bf16 v[64:67], v[190:193], v[232:235], v[64:67]
	v_mfma_f32_16x16x32_bf16 v[116:119], v[166:169], v[202:205], v[116:119]
	v_mfma_f32_16x16x32_bf16 v[112:115], v[194:197], v[202:205], v[112:115]
	v_mfma_f32_16x16x32_bf16 v[100:103], v[166:169], v[210:213], v[100:103]
	v_mfma_f32_16x16x32_bf16 v[96:99], v[194:197], v[210:213], v[96:99]
	v_mfma_f32_16x16x32_bf16 v[84:87], v[166:169], v[228:231], v[84:87]
	v_mfma_f32_16x16x32_bf16 v[80:83], v[194:197], v[228:231], v[80:83]
	v_mfma_f32_16x16x32_bf16 v[68:71], v[166:169], v[236:239], v[68:71]
	v_mfma_f32_16x16x32_bf16 v[64:67], v[194:197], v[236:239], v[64:67]
	s_barrier
	s_add_i32 s45, s45, s20
	s_mov_b32 m0, s45
	s_add_u32 s100, s22, 0x80
	s_addc_u32 s101, s23, 0
	global_load_lds_dwordx4 v172, s[100:101]
	s_add_i32 m0, s45, 0x2000
	s_add_u32 s22, s22, 0x80080
	s_addc_u32 s23, s23, 0
	s_add_i32 s45, s47, s20
	global_load_lds_dwordx4 v132, s[100:101]
	s_mov_b32 m0, s45
	s_nop 0
	global_load_lds_dwordx4 v172, s[22:23]
	s_add_i32 m0, s45, 0x2000
	s_nop 0
	global_load_lds_dwordx4 v132, s[22:23]
	s_mov_b32 m0, s38
	s_nop 0
	s_add_u32 s100, s54, 0xfff80080
	s_addc_u32 s101, s55, -1
	global_load_lds_dwordx4 v128, s[100:101]
	s_mov_b32 m0, s56
	s_nop 0
	global_load_lds_dwordx4 v130, s[100:101]
	ds_read_b128 v[198:201], v148 offset:49152
	ds_read_b128 v[202:205], v148 offset:50176
	ds_read_b128 v[206:209], v148 offset:51200
	ds_read_b128 v[210:213], v148 offset:52224
	ds_read_b128 v[224:227], v148 offset:53248
	ds_read_b128 v[228:231], v148 offset:54272
	ds_read_b128 v[232:235], v148 offset:55296
	ds_read_b128 v[236:239], v148 offset:56320
	s_waitcnt vmcnt(8) lgkmcnt(0)
	s_barrier
	v_mfma_f32_16x16x32_bf16 v[60:63], v[138:141], v[198:201], v[60:63]
	v_mfma_f32_16x16x32_bf16 v[56:59], v[154:157], v[198:201], v[56:59]
	v_mfma_f32_16x16x32_bf16 v[44:47], v[138:141], v[206:209], v[44:47]
	v_mfma_f32_16x16x32_bf16 v[40:43], v[154:157], v[206:209], v[40:43]
	v_mfma_f32_16x16x32_bf16 v[28:31], v[138:141], v[224:227], v[28:31]
	v_mfma_f32_16x16x32_bf16 v[24:27], v[154:157], v[224:227], v[24:27]
	v_mfma_f32_16x16x32_bf16 v[12:15], v[138:141], v[232:235], v[12:15]
	v_mfma_f32_16x16x32_bf16 v[8:11], v[154:157], v[232:235], v[8:11]
	v_mfma_f32_16x16x32_bf16 v[60:63], v[150:153], v[202:205], v[60:63]
	v_mfma_f32_16x16x32_bf16 v[56:59], v[158:161], v[202:205], v[56:59]
	v_mfma_f32_16x16x32_bf16 v[44:47], v[150:153], v[210:213], v[44:47]
	v_mfma_f32_16x16x32_bf16 v[40:43], v[158:161], v[210:213], v[40:43]
	v_mfma_f32_16x16x32_bf16 v[28:31], v[150:153], v[228:231], v[28:31]
	v_mfma_f32_16x16x32_bf16 v[24:27], v[158:161], v[228:231], v[24:27]
	v_mfma_f32_16x16x32_bf16 v[12:15], v[150:153], v[236:239], v[12:15]
	v_mfma_f32_16x16x32_bf16 v[8:11], v[158:161], v[236:239], v[8:11]
	v_mfma_f32_16x16x32_bf16 v[52:55], v[162:165], v[198:201], v[52:55]
	v_mfma_f32_16x16x32_bf16 v[48:51], v[190:193], v[198:201], v[48:51]
	v_mfma_f32_16x16x32_bf16 v[36:39], v[162:165], v[206:209], v[36:39]
	v_mfma_f32_16x16x32_bf16 v[32:35], v[190:193], v[206:209], v[32:35]
	v_mfma_f32_16x16x32_bf16 v[20:23], v[162:165], v[224:227], v[20:23]
	v_mfma_f32_16x16x32_bf16 v[16:19], v[190:193], v[224:227], v[16:19]
	v_mfma_f32_16x16x32_bf16 v[4:7], v[162:165], v[232:235], v[4:7]
	v_mfma_f32_16x16x32_bf16 v[0:3], v[190:193], v[232:235], v[0:3]
	v_mfma_f32_16x16x32_bf16 v[52:55], v[166:169], v[202:205], v[52:55]
	v_mfma_f32_16x16x32_bf16 v[48:51], v[194:197], v[202:205], v[48:51]
	v_mfma_f32_16x16x32_bf16 v[36:39], v[166:169], v[210:213], v[36:39]
	v_mfma_f32_16x16x32_bf16 v[32:35], v[194:197], v[210:213], v[32:35]
	v_mfma_f32_16x16x32_bf16 v[20:23], v[166:169], v[228:231], v[20:23]
	v_mfma_f32_16x16x32_bf16 v[16:19], v[194:197], v[228:231], v[16:19]
	v_mfma_f32_16x16x32_bf16 v[4:7], v[166:169], v[236:239], v[4:7]
	v_mfma_f32_16x16x32_bf16 v[0:3], v[194:197], v[236:239], v[0:3]
	s_barrier
	s_add_i32 s43, s43, 2
	s_add_u32 s52, s52, 0x100
	s_addc_u32 s53, s53, 0
	s_add_u32 s34, s34, 0x100
	s_addc_u32 s35, s35, 0
	s_cmp_gt_u32 s43, 29
	s_cbranch_scc0 .LBB0_476
	s_and_b64 vcc, exec, s[28:29]
	s_cbranch_vccz .LBB0_479
	s_barrier

; #define PG8_STAGE(bufoff, gbase, voff) do { _Pragma("unroll") for (int _i = 0; _i < 2; ++_i) \
;         __builtin_amdgcn_global_load_lds((const unsigned*)((const char*)(gbase) + (voff)[_i]), (PG8_LAS unsigned*)(lds + (bufoff) + ldsw + _i * 8192), 16, 0, 0); } while (0)
; #define PG8_LDA(dst, b, h) do { _Pragma("unroll") for (int m = 0; m < 4; ++m) _Pragma("unroll") for (int k = 0; k < 2; ++k) dst[m][k] = *(const PG8_LAS bf16x8*)(lds + PG8_SA(b, h) + aoff + m * 2048 + k * 1024); } while (0)
; #define PG8_LDB(dst, b, h) do { _Pragma("unroll") for (int n = 0; n < 2; ++n) _Pragma("unroll") for (int k = 0; k < 2; ++k) dst[n][k] = *(const PG8_LAS bf16x8*)(lds + PG8_SB(b, h) + boff + n * 2048 + k * 1024); } while (0)
; #define PG8_MMA(ai, bj, At, Bt) do { __builtin_amdgcn_s_setprio(1); _Pragma("unroll") for (int m = 0; m < 4; ++m) _Pragma("unroll") for (int n = 0; n < 2; ++n) _Pragma("unroll") for (int k = 0; k < 2; ++k) \
;         acc[ai][bj][m][n] = __builtin_amdgcn_mfma_f32_16x16x32_bf16(Bt[n][k], At[m][k], acc[ai][bj][m][n], 0, 0, 0); __builtin_amdgcn_s_setprio(0); } while (0)
; #define PG8_WAIT_V(n) asm volatile("s_waitcnt vmcnt(" #n ")" ::: "memory")
; #define PG8_WAIT_L(n) asm volatile("s_waitcnt lgkmcnt(" #n ")" ::: "memory")
; #define PG8_BAR __builtin_amdgcn_s_barrier()
; #define PG8_SCHED __builtin_amdgcn_sched_barrier(0)
; template <class Epi, class Sched, bool ALIGN_EPI = false, bool SP2 = false>
; __device__ __forceinline__ void gemm_phase(PG8_LAS unsigned char* lds, const Gemm g, const Sched& S, const Epi& E, const int tid_in) {
;     ...
;             PG8_LDB(B0, 0, 0); PG8_LDB(B1, 0, 1); PG8_SCHED; PG8_LDA(At, 0, 0); PG8_STAGE(PG8_SA(1, 1), a1 + hstepA, voffA);
;             PG8_WAIT_V(8); PG8_WAIT_L(0); PG8_BAR; PG8_MMA(0, 0, At, B0); PG8_MMA(0, 1, At, B1); PG8_BAR; PG8_SCHED;
;             PG8_LDA(At, 0, 1); PG8_STAGE(PG8_SB(0, 0), b2, voffB); PG8_STAGE(PG8_SB(0, 1), b2 + hstepB, voffB); PG8_STAGE(PG8_SA(0, 0), a2, voffA);
;             PG8_WAIT_V(8); PG8_WAIT_L(0); PG8_BAR; PG8_MMA(1, 0, At, B0); PG8_MMA(1, 1, At, B1); PG8_BAR; PG8_SCHED;
.LBB0_756:
	s_add_u32 s22, s36, 0x100
	s_addc_u32 s23, s37, 0
	s_add_i32 s34, 0, 0x10000
	s_cmp_eq_u32 s33, 2
	s_cselect_b32 s45, s73, s23
	s_cselect_b32 s44, s72, s22
	s_cselect_b32 s43, s77, s21
	s_cselect_b32 s42, s76, s12
	s_add_i32 s46, 0, 0x14000
	s_add_i32 m0, s74, 0xc000
	s_nop 0
	global_load_lds_dwordx4 v142, s[36:37]
	s_add_i32 m0, s74, 0xe000
	s_nop 0
	global_load_lds_dwordx4 v144, s[36:37]
	ds_read_b128 v[88:91], v249
	ds_read_b128 v[92:95], v249 offset:1024
	ds_read_b128 v[96:99], v249 offset:2048
	ds_read_b128 v[146:149], v249 offset:3072
	ds_read_b128 v[150:153], v249 offset:16384
	ds_read_b128 v[154:157], v249 offset:17408
	ds_read_b128 v[158:161], v249 offset:18432
	ds_read_b128 v[162:165], v249 offset:19456
	ds_read_b128 v[166:169], v192
	ds_read_b128 v[194:197], v192 offset:1024
	ds_read_b128 v[198:201], v192 offset:2048
	ds_read_b128 v[202:205], v192 offset:3072
	ds_read_b128 v[206:209], v192 offset:4096
	ds_read_b128 v[210:213], v192 offset:5120
	ds_read_b128 v[224:227], v192 offset:6144
	ds_read_b128 v[228:231], v192 offset:7168
	s_waitcnt vmcnt(8) lgkmcnt(0)
	s_barrier
	v_mfma_f32_16x16x32_bf16 v[136:139], v[88:91], v[166:169], v[136:139]
	v_mfma_f32_16x16x32_bf16 v[60:63], v[96:99], v[166:169], v[60:63]
	v_mfma_f32_16x16x32_bf16 v[128:131], v[88:91], v[198:201], v[128:131]
	v_mfma_f32_16x16x32_bf16 v[52:55], v[96:99], v[198:201], v[52:55]
	v_mfma_f32_16x16x32_bf16 v[120:123], v[88:91], v[206:209], v[120:123]
	v_mfma_f32_16x16x32_bf16 v[44:47], v[96:99], v[206:209], v[44:47]
	v_mfma_f32_16x16x32_bf16 v[112:115], v[88:91], v[224:227], v[112:115]
	v_mfma_f32_16x16x32_bf16 v[36:39], v[96:99], v[224:227], v[36:39]
	v_mfma_f32_16x16x32_bf16 v[136:139], v[92:95], v[194:197], v[136:139]
	v_mfma_f32_16x16x32_bf16 v[60:63], v[146:149], v[194:197], v[60:63]
	v_mfma_f32_16x16x32_bf16 v[128:131], v[92:95], v[202:205], v[128:131]
	v_mfma_f32_16x16x32_bf16 v[52:55], v[146:149], v[202:205], v[52:55]
	v_mfma_f32_16x16x32_bf16 v[120:123], v[92:95], v[210:213], v[120:123]
	v_mfma_f32_16x16x32_bf16 v[44:47], v[146:149], v[210:213], v[44:47]
	v_mfma_f32_16x16x32_bf16 v[112:115], v[92:95], v[228:231], v[112:115]
	v_mfma_f32_16x16x32_bf16 v[36:39], v[146:149], v[228:231], v[36:39]
	v_mfma_f32_16x16x32_bf16 v[132:135], v[150:153], v[166:169], v[132:135]
	v_mfma_f32_16x16x32_bf16 v[56:59], v[158:161], v[166:169], v[56:59]
	v_mfma_f32_16x16x32_bf16 v[124:127], v[150:153], v[198:201], v[124:127]
	v_mfma_f32_16x16x32_bf16 v[48:51], v[158:161], v[198:201], v[48:51]
	v_mfma_f32_16x16x32_bf16 v[116:119], v[150:153], v[206:209], v[116:119]
	v_mfma_f32_16x16x32_bf16 v[40:43], v[158:161], v[206:209], v[40:43]
	v_mfma_f32_16x16x32_bf16 v[108:111], v[150:153], v[224:227], v[108:111]
	v_mfma_f32_16x16x32_bf16 v[32:35], v[158:161], v[224:227], v[32:35]
	v_mfma_f32_16x16x32_bf16 v[132:135], v[154:157], v[194:197], v[132:135]
	v_mfma_f32_16x16x32_bf16 v[56:59], v[162:165], v[194:197], v[56:59]
	v_mfma_f32_16x16x32_bf16 v[124:127], v[154:157], v[202:205], v[124:127]
	v_mfma_f32_16x16x32_bf16 v[48:51], v[162:165], v[202:205], v[48:51]
	v_mfma_f32_16x16x32_bf16 v[116:119], v[154:157], v[210:213], v[116:119]
	v_mfma_f32_16x16x32_bf16 v[40:43], v[162:165], v[210:213], v[40:43]
	v_mfma_f32_16x16x32_bf16 v[108:111], v[154:157], v[228:231], v[108:111]
	v_mfma_f32_16x16x32_bf16 v[32:35], v[162:165], v[228:231], v[32:35]
	s_barrier
	s_add_i32 s34, s34, s38
	s_mov_b32 m0, s34
	s_nop 0
	global_load_lds_dwordx4 v172, s[42:43]
	s_add_i32 m0, s34, 0x2000
	s_add_u32 s34, s42, 0xa0000
	s_addc_u32 s35, s43, 0
	s_add_i32 s36, s46, s38
	global_load_lds_dwordx4 v140, s[42:43]
	s_mov_b32 m0, s36
	s_nop 0
	global_load_lds_dwordx4 v172, s[34:35]
	s_add_i32 m0, s36, 0x2000
	s_nop 0
	global_load_lds_dwordx4 v140, s[34:35]
	s_mov_b32 m0, s74
	s_nop 0
	global_load_lds_dwordx4 v172, s[44:45]
	s_mov_b32 m0, s75
	s_nop 0
	global_load_lds_dwordx4 v140, s[44:45]
	ds_read_b128 v[166:169], v192 offset:16384
	ds_read_b128 v[194:197], v192 offset:17408
	ds_read_b128 v[198:201], v192 offset:18432
	ds_read_b128 v[202:205], v192 offset:19456
	ds_read_b128 v[206:209], v192 offset:20480
	ds_read_b128 v[210:213], v192 offset:21504
	ds_read_b128 v[224:227], v192 offset:22528
	ds_read_b128 v[228:231], v192 offset:23552
	s_waitcnt vmcnt(8) lgkmcnt(0)
	s_barrier
	v_mfma_f32_16x16x32_bf16 v[104:107], v[88:91], v[166:169], v[104:107]
	v_mfma_f32_16x16x32_bf16 v[28:31], v[96:99], v[166:169], v[28:31]
	v_mfma_f32_16x16x32_bf16 v[84:87], v[88:91], v[198:201], v[84:87]
	v_mfma_f32_16x16x32_bf16 v[20:23], v[96:99], v[198:201], v[20:23]
	v_mfma_f32_16x16x32_bf16 v[76:79], v[88:91], v[206:209], v[76:79]
	v_mfma_f32_16x16x32_bf16 v[12:15], v[96:99], v[206:209], v[12:15]
	v_mfma_f32_16x16x32_bf16 v[68:71], v[88:91], v[224:227], v[68:71]
	v_mfma_f32_16x16x32_bf16 v[4:7], v[96:99], v[224:227], v[4:7]
	v_mfma_f32_16x16x32_bf16 v[104:107], v[92:95], v[194:197], v[104:107]
	v_mfma_f32_16x16x32_bf16 v[28:31], v[146:149], v[194:197], v[28:31]
	v_mfma_f32_16x16x32_bf16 v[84:87], v[92:95], v[202:205], v[84:87]
	v_mfma_f32_16x16x32_bf16 v[20:23], v[146:149], v[202:205], v[20:23]
	v_mfma_f32_16x16x32_bf16 v[76:79], v[92:95], v[210:213], v[76:79]
	v_mfma_f32_16x16x32_bf16 v[12:15], v[146:149], v[210:213], v[12:15]
	v_mfma_f32_16x16x32_bf16 v[68:71], v[92:95], v[228:231], v[68:71]
	v_mfma_f32_16x16x32_bf16 v[4:7], v[146:149], v[228:231], v[4:7]
	v_mfma_f32_16x16x32_bf16 v[24:27], v[158:161], v[166:169], v[24:27]
	v_mfma_f32_16x16x32_bf16 v[80:83], v[150:153], v[198:201], v[80:83]
	v_mfma_f32_16x16x32_bf16 v[16:19], v[158:161], v[198:201], v[16:19]
	v_mfma_f32_16x16x32_bf16 v[72:75], v[150:153], v[206:209], v[72:75]
	v_mfma_f32_16x16x32_bf16 v[8:11], v[158:161], v[206:209], v[8:11]
	v_mfma_f32_16x16x32_bf16 v[64:67], v[150:153], v[224:227], v[64:67]
	v_mfma_f32_16x16x32_bf16 v[0:3], v[158:161], v[224:227], v[0:3]
	v_mfma_f32_16x16x32_bf16 v[88:91], v[150:153], v[166:169], v[100:103]
	v_mfma_f32_16x16x32_bf16 v[24:27], v[162:165], v[194:197], v[24:27]
	v_mfma_f32_16x16x32_bf16 v[80:83], v[154:157], v[202:205], v[80:83]
	v_mfma_f32_16x16x32_bf16 v[16:19], v[162:165], v[202:205], v[16:19]
	v_mfma_f32_16x16x32_bf16 v[72:75], v[154:157], v[210:213], v[72:75]
	v_mfma_f32_16x16x32_bf16 v[8:11], v[162:165], v[210:213], v[8:11]
	v_mfma_f32_16x16x32_bf16 v[64:67], v[154:157], v[228:231], v[64:67]
	v_mfma_f32_16x16x32_bf16 v[0:3], v[162:165], v[228:231], v[0:3]
	v_mfma_f32_16x16x32_bf16 v[88:91], v[154:157], v[194:197], v[88:91]
	s_barrier
; #define PG8_STAGE(bufoff, gbase, voff) do { _Pragma("unroll") for (int _i = 0; _i < 2; ++_i) \
;         __builtin_amdgcn_global_load_lds((const unsigned*)((const char*)(gbase) + (voff)[_i]), (PG8_LAS unsigned*)(lds + (bufoff) + ldsw + _i * 8192), 16, 0, 0); } while (0)
; #define PG8_LDA(dst, b, h) do { _Pragma("unroll") for (int m = 0; m < 4; ++m) _Pragma("unroll") for (int k = 0; k < 2; ++k) dst[m][k] = *(const PG8_LAS bf16x8*)(lds + PG8_SA(b, h) + aoff + m * 2048 + k * 1024); } while (0)
; #define PG8_LDB(dst, b, h) do { _Pragma("unroll") for (int n = 0; n < 2; ++n) _Pragma("unroll") for (int k = 0; k < 2; ++k) dst[n][k] = *(const PG8_LAS bf16x8*)(lds + PG8_SB(b, h) + boff + n * 2048 + k * 1024); } while (0)
; #define PG8_MMA(ai, bj, At, Bt) do { __builtin_amdgcn_s_setprio(1); _Pragma("unroll") for (int m = 0; m < 4; ++m) _Pragma("unroll") for (int n = 0; n < 2; ++n) _Pragma("unroll") for (int k = 0; k < 2; ++k) \
;         acc[ai][bj][m][n] = __builtin_amdgcn_mfma_f32_16x16x32_bf16(Bt[n][k], At[m][k], acc[ai][bj][m][n], 0, 0, 0); __builtin_amdgcn_s_setprio(0); } while (0)
; #define PG8_WAIT_V(n) asm volatile("s_waitcnt vmcnt(" #n ")" ::: "memory")
; #define PG8_WAIT_L(n) asm volatile("s_waitcnt lgkmcnt(" #n ")" ::: "memory")
; #define PG8_BAR __builtin_amdgcn_s_barrier()
; #define PG8_SCHED __builtin_amdgcn_sched_barrier(0)
; template <class Epi, class Sched, bool ALIGN_EPI = false, bool SP2 = false>
; __device__ __forceinline__ void gemm_phase(PG8_LAS unsigned char* lds, const Gemm g, const Sched& S, const Epi& E, const int tid_in) {
;     ...
;             PG8_LDB(B0, 1, 0); PG8_LDB(B1, 1, 1); PG8_SCHED; PG8_LDA(At, 1, 0); PG8_STAGE(PG8_SA(0, 1), a2 + hstepA, voffA);
;             PG8_WAIT_V(8); PG8_WAIT_L(0); PG8_BAR; PG8_MMA(0, 0, At, B0); PG8_MMA(0, 1, At, B1); PG8_BAR; PG8_SCHED;
;             PG8_LDA(At, 1, 1); PG8_STAGE(PG8_SB(1, 0), b3, voffB); PG8_STAGE(PG8_SB(1, 1), b3 + hstepB, voffB); PG8_STAGE(PG8_SA(1, 0), a3, voffA);
;             PG8_WAIT_V(8); PG8_WAIT_L(0); PG8_BAR; PG8_MMA(1, 0, At, B0); PG8_MMA(1, 1, At, B1); PG8_BAR; PG8_SCHED;
;     ...
;         if constexpr (ALIGN_EPI) { if (wr == 0) PG8_BAR; }
	s_add_i32 s36, 0, 0x18000
	s_add_i32 s37, 0, 0x1c000
	s_add_u32 s34, s44, 0xa0000
	s_addc_u32 s35, s45, 0
	s_mov_b32 m0, s60
	s_nop 0
	global_load_lds_dwordx4 v172, s[34:35]
	s_mov_b32 m0, s61
	s_nop 0
	global_load_lds_dwordx4 v140, s[34:35]
	ds_read_b128 v[92:95], v249 offset:32768
	ds_read_b128 v[96:99], v249 offset:33792
	ds_read_b128 v[100:103], v249 offset:34816
	ds_read_b128 v[146:149], v249 offset:35840
	ds_read_b128 v[150:153], v249 offset:49152
	ds_read_b128 v[154:157], v249 offset:50176
	ds_read_b128 v[158:161], v249 offset:51200
	ds_read_b128 v[162:165], v249 offset:52224
	ds_read_b128 v[166:169], v192 offset:32768
	ds_read_b128 v[194:197], v192 offset:33792
	ds_read_b128 v[198:201], v192 offset:34816
	ds_read_b128 v[202:205], v192 offset:35840
	ds_read_b128 v[206:209], v192 offset:36864
	ds_read_b128 v[210:213], v192 offset:37888
	ds_read_b128 v[224:227], v192 offset:38912
	ds_read_b128 v[228:231], v192 offset:39936
	s_waitcnt vmcnt(8) lgkmcnt(0)
	s_barrier
	v_mfma_f32_16x16x32_bf16 v[136:139], v[92:95], v[166:169], v[136:139]
	v_mfma_f32_16x16x32_bf16 v[60:63], v[100:103], v[166:169], v[60:63]
	v_mfma_f32_16x16x32_bf16 v[128:131], v[92:95], v[198:201], v[128:131]
	v_mfma_f32_16x16x32_bf16 v[52:55], v[100:103], v[198:201], v[52:55]
	v_mfma_f32_16x16x32_bf16 v[120:123], v[92:95], v[206:209], v[120:123]
	v_mfma_f32_16x16x32_bf16 v[44:47], v[100:103], v[206:209], v[44:47]
	v_mfma_f32_16x16x32_bf16 v[112:115], v[92:95], v[224:227], v[112:115]
	v_mfma_f32_16x16x32_bf16 v[36:39], v[100:103], v[224:227], v[36:39]
	v_mfma_f32_16x16x32_bf16 v[136:139], v[96:99], v[194:197], v[136:139]
	v_mfma_f32_16x16x32_bf16 v[60:63], v[146:149], v[194:197], v[60:63]
	v_mfma_f32_16x16x32_bf16 v[128:131], v[96:99], v[202:205], v[128:131]
	v_mfma_f32_16x16x32_bf16 v[52:55], v[146:149], v[202:205], v[52:55]
	v_mfma_f32_16x16x32_bf16 v[120:123], v[96:99], v[210:213], v[120:123]
	v_mfma_f32_16x16x32_bf16 v[44:47], v[146:149], v[210:213], v[44:47]
	v_mfma_f32_16x16x32_bf16 v[112:115], v[96:99], v[228:231], v[112:115]
	v_mfma_f32_16x16x32_bf16 v[36:39], v[146:149], v[228:231], v[36:39]
	v_mfma_f32_16x16x32_bf16 v[132:135], v[150:153], v[166:169], v[132:135]
	v_mfma_f32_16x16x32_bf16 v[56:59], v[158:161], v[166:169], v[56:59]
	v_mfma_f32_16x16x32_bf16 v[124:127], v[150:153], v[198:201], v[124:127]
	v_mfma_f32_16x16x32_bf16 v[48:51], v[158:161], v[198:201], v[48:51]
	v_mfma_f32_16x16x32_bf16 v[116:119], v[150:153], v[206:209], v[116:119]
	v_mfma_f32_16x16x32_bf16 v[40:43], v[158:161], v[206:209], v[40:43]
	v_mfma_f32_16x16x32_bf16 v[108:111], v[150:153], v[224:227], v[108:111]
	v_mfma_f32_16x16x32_bf16 v[32:35], v[158:161], v[224:227], v[32:35]
	v_mfma_f32_16x16x32_bf16 v[132:135], v[154:157], v[194:197], v[132:135]
	v_mfma_f32_16x16x32_bf16 v[56:59], v[162:165], v[194:197], v[56:59]
	v_mfma_f32_16x16x32_bf16 v[124:127], v[154:157], v[202:205], v[124:127]
	v_mfma_f32_16x16x32_bf16 v[48:51], v[162:165], v[202:205], v[48:51]
	v_mfma_f32_16x16x32_bf16 v[116:119], v[154:157], v[210:213], v[116:119]
	v_mfma_f32_16x16x32_bf16 v[40:43], v[162:165], v[210:213], v[40:43]
	v_mfma_f32_16x16x32_bf16 v[108:111], v[154:157], v[228:231], v[108:111]
	v_mfma_f32_16x16x32_bf16 v[32:35], v[162:165], v[228:231], v[32:35]
	s_barrier
	s_add_i32 s34, s36, s38
	s_mov_b32 m0, s34
	s_add_u32 s100, s42, 0x80
	s_addc_u32 s101, s43, 0
	global_load_lds_dwordx4 v172, s[100:101]
	s_add_i32 m0, s34, 0x2000
	s_add_u32 s34, s42, 0xa0080
	s_addc_u32 s35, s43, 0
	s_add_i32 s36, s37, s38
	global_load_lds_dwordx4 v140, s[100:101]
	s_mov_b32 m0, s36
	s_nop 0
	global_load_lds_dwordx4 v172, s[34:35]
	s_add_i32 m0, s36, 0x2000
	s_nop 0
	global_load_lds_dwordx4 v140, s[34:35]
	s_mov_b32 m0, s58
	s_nop 0
	s_add_u32 s100, s44, 0x80
	s_addc_u32 s101, s45, 0
	global_load_lds_dwordx4 v172, s[100:101]
	s_mov_b32 m0, s59
	s_nop 0
	global_load_lds_dwordx4 v140, s[100:101]
	ds_read_b128 v[166:169], v192 offset:49152
	ds_read_b128 v[194:197], v192 offset:50176
	ds_read_b128 v[198:201], v192 offset:51200
	ds_read_b128 v[202:205], v192 offset:52224
	ds_read_b128 v[206:209], v192 offset:53248
	ds_read_b128 v[210:213], v192 offset:54272
	ds_read_b128 v[224:227], v192 offset:55296
	ds_read_b128 v[228:231], v192 offset:56320
	s_waitcnt vmcnt(8) lgkmcnt(0)
	s_barrier
	v_mfma_f32_16x16x32_bf16 v[104:107], v[92:95], v[166:169], v[104:107]
	v_mfma_f32_16x16x32_bf16 v[28:31], v[100:103], v[166:169], v[28:31]
	v_mfma_f32_16x16x32_bf16 v[84:87], v[92:95], v[198:201], v[84:87]
	v_mfma_f32_16x16x32_bf16 v[20:23], v[100:103], v[198:201], v[20:23]
	v_mfma_f32_16x16x32_bf16 v[76:79], v[92:95], v[206:209], v[76:79]
	v_mfma_f32_16x16x32_bf16 v[12:15], v[100:103], v[206:209], v[12:15]
	v_mfma_f32_16x16x32_bf16 v[68:71], v[92:95], v[224:227], v[68:71]
	v_mfma_f32_16x16x32_bf16 v[4:7], v[100:103], v[224:227], v[4:7]
	v_mfma_f32_16x16x32_bf16 v[104:107], v[96:99], v[194:197], v[104:107]
	v_mfma_f32_16x16x32_bf16 v[28:31], v[146:149], v[194:197], v[28:31]
	v_mfma_f32_16x16x32_bf16 v[84:87], v[96:99], v[202:205], v[84:87]
	v_mfma_f32_16x16x32_bf16 v[20:23], v[146:149], v[202:205], v[20:23]
	v_mfma_f32_16x16x32_bf16 v[76:79], v[96:99], v[210:213], v[76:79]
	v_mfma_f32_16x16x32_bf16 v[12:15], v[146:149], v[210:213], v[12:15]
	v_mfma_f32_16x16x32_bf16 v[68:71], v[96:99], v[228:231], v[68:71]
	v_mfma_f32_16x16x32_bf16 v[4:7], v[146:149], v[228:231], v[4:7]
	v_mfma_f32_16x16x32_bf16 v[88:91], v[150:153], v[166:169], v[88:91]
	v_mfma_f32_16x16x32_bf16 v[24:27], v[158:161], v[166:169], v[24:27]
	v_mfma_f32_16x16x32_bf16 v[80:83], v[150:153], v[198:201], v[80:83]
	v_mfma_f32_16x16x32_bf16 v[16:19], v[158:161], v[198:201], v[16:19]
	v_mfma_f32_16x16x32_bf16 v[72:75], v[150:153], v[206:209], v[72:75]
	v_mfma_f32_16x16x32_bf16 v[8:11], v[158:161], v[206:209], v[8:11]
	v_mfma_f32_16x16x32_bf16 v[64:67], v[150:153], v[224:227], v[64:67]
	v_mfma_f32_16x16x32_bf16 v[0:3], v[158:161], v[224:227], v[0:3]
	v_mfma_f32_16x16x32_bf16 v[100:103], v[154:157], v[194:197], v[88:91]
	v_mfma_f32_16x16x32_bf16 v[24:27], v[162:165], v[194:197], v[24:27]
	v_mfma_f32_16x16x32_bf16 v[80:83], v[154:157], v[202:205], v[80:83]
	v_mfma_f32_16x16x32_bf16 v[16:19], v[162:165], v[202:205], v[16:19]
	v_mfma_f32_16x16x32_bf16 v[72:75], v[154:157], v[210:213], v[72:75]
	v_mfma_f32_16x16x32_bf16 v[8:11], v[162:165], v[210:213], v[8:11]
	v_mfma_f32_16x16x32_bf16 v[64:67], v[154:157], v[228:231], v[64:67]
	v_mfma_f32_16x16x32_bf16 v[0:3], v[162:165], v[228:231], v[0:3]
	s_barrier
	s_add_i32 s33, s33, 2
	s_add_u32 s12, s12, 0x100
	s_addc_u32 s21, s21, 0
	s_cmp_gt_u32 s33, 3
	s_mov_b64 s[36:37], s[22:23]
	s_cbranch_scc0 .LBB0_756
	s_and_b64 vcc, exec, s[70:71]
	s_cbranch_vccz .LBB0_759
	s_barrier

;     __device__ __forceinline__ void a_ready(const Unit& u) const { wait_panel(cnt, u.pm, need, tmo, wave); }
;     __device__ __forceinline__ void a_ready(const Unit& u) const { wait_panel(cnt, u.pm, need, tmo, wave); }
; #define PG8_STAGE(bufoff, gbase, voff) do { _Pragma("unroll") for (int _i = 0; _i < 2; ++_i) \
;         __builtin_amdgcn_global_load_lds((const unsigned*)((const char*)(gbase) + (voff)[_i]), (PG8_LAS unsigned*)(lds + (bufoff) + ldsw + _i * 8192), 16, 0, 0); } while (0)
; #define PG8_LDA(dst, b, h) do { _Pragma("unroll") for (int m = 0; m < 4; ++m) _Pragma("unroll") for (int k = 0; k < 2; ++k) dst[m][k] = *(const PG8_LAS bf16x8*)(lds + PG8_SA(b, h) + aoff + m * 2048 + k * 1024); } while (0)
; #define PG8_LDB(dst, b, h) do { _Pragma("unroll") for (int n = 0; n < 2; ++n) _Pragma("unroll") for (int k = 0; k < 2; ++k) dst[n][k] = *(const PG8_LAS bf16x8*)(lds + PG8_SB(b, h) + boff + n * 2048 + k * 1024); } while (0)
; #define PG8_WAIT_V(n) asm volatile("s_waitcnt vmcnt(" #n ")" ::: "memory")
; #define PG8_WAIT_L(n) asm volatile("s_waitcnt lgkmcnt(" #n ")" ::: "memory")
; #define PG8_BAR __builtin_amdgcn_s_barrier()
; #define PG8_SCHED __builtin_amdgcn_sched_barrier(0)
; template <class Epi, class Sched, bool ALIGN_EPI = false, bool SP2 = false>
; __device__ __forceinline__ void gemm_phase(PG8_LAS unsigned char* lds, const Gemm g, const Sched& S, const Epi& E, const int tid_in) {
;     ...
;             const bool last = (t == nt - 2);
;             const char* a1 = cA + (size_t)(t + 1) * kstep;
;             const char* a2 = last ? nA : cA + (size_t)(t + 2) * kstep; const char* b2 = last ? nB : cB + (size_t)(t + 2) * kstep;
;             const char* a3 = a2 + kstep; const char* b3 = b2 + kstep;
;             if (last && has_next) S.a_ready(nxt);
;             if constexpr (SP2) {
;             PG8_LDB(B0, 0, 0); PG8_LDB(B1, 0, 1); PG8_SCHED; PG8_LDA(At, 0, 0); PG8_STAGE(PG8_SA(1, 1), a1 + hstepA, voffA);
;             PG8_WAIT_V(8); PG8_WAIT_L(0); PG8_BAR; PG8_MMA(0, 0, At, B0); PG8_MMA(0, 1, At, B1); PG8_BAR; PG8_SCHED;
;             PG8_LDA(At, 0, 1); PG8_STAGE(PG8_SB(0, 0), b2, voffB); PG8_STAGE(PG8_SB(0, 1), b2 + hstepB, voffB); PG8_STAGE(PG8_SA(0, 0), a2, voffA);
;             PG8_WAIT_V(8); PG8_WAIT_L(0); PG8_BAR; PG8_MMA(1, 0, At, B0); PG8_MMA(1, 1, At, B1); PG8_BAR; PG8_SCHED;
.LBB0_1268:
	s_add_u32 s22, s50, 0x100
	s_addc_u32 s23, s51, 0
	s_add_i32 s63, 0, 0x10000
	s_cmp_eq_u32 s62, 36
	s_cselect_b32 s55, s43, s23
	s_cselect_b32 s54, s42, s22
	s_cselect_b32 s53, s49, s61
	s_cselect_b32 s52, s48, s60
	s_add_i32 s64, 0, 0x14000
	s_add_i32 m0, s30, 0xc000
	s_nop 0
	global_load_lds_dwordx4 v170, s[50:51]
	s_add_i32 m0, s30, 0xe000
	s_nop 0
	global_load_lds_dwordx4 v190, s[50:51]
	ds_read_b128 v[104:107], v249
	ds_read_b128 v[108:111], v249 offset:1024
	ds_read_b128 v[112:115], v249 offset:2048
	ds_read_b128 v[116:119], v249 offset:3072
	ds_read_b128 v[144:147], v249 offset:16384
	ds_read_b128 v[148:151], v249 offset:17408
	ds_read_b128 v[152:155], v249 offset:18432
	ds_read_b128 v[156:159], v249 offset:19456
	ds_read_b128 v[160:163], v204
	ds_read_b128 v[192:195], v204 offset:1024
	ds_read_b128 v[196:199], v204 offset:2048
	ds_read_b128 v[206:209], v204 offset:3072
	ds_read_b128 v[210:213], v204 offset:4096
	ds_read_b128 v[224:227], v204 offset:5120
	ds_read_b128 v[228:231], v204 offset:6144
	ds_read_b128 v[232:235], v204 offset:7168
	s_waitcnt vmcnt(8) lgkmcnt(0)
	s_barrier
	v_mfma_f32_16x16x32_bf16 v[140:143], v[104:107], v[160:163], v[140:143]
	v_mfma_f32_16x16x32_bf16 v[136:139], v[112:115], v[160:163], v[136:139]
	v_mfma_f32_16x16x32_bf16 v[124:127], v[104:107], v[196:199], v[124:127]
	v_mfma_f32_16x16x32_bf16 v[120:123], v[112:115], v[196:199], v[120:123]
	v_mfma_f32_16x16x32_bf16 v[92:95], v[104:107], v[210:213], v[92:95]
	v_mfma_f32_16x16x32_bf16 v[88:91], v[112:115], v[210:213], v[88:91]
	v_mfma_f32_16x16x32_bf16 v[76:79], v[104:107], v[228:231], v[76:79]
	v_mfma_f32_16x16x32_bf16 v[72:75], v[112:115], v[228:231], v[72:75]
	v_mfma_f32_16x16x32_bf16 v[140:143], v[108:111], v[192:195], v[140:143]
	v_mfma_f32_16x16x32_bf16 v[136:139], v[116:119], v[192:195], v[136:139]
	v_mfma_f32_16x16x32_bf16 v[124:127], v[108:111], v[206:209], v[124:127]
	v_mfma_f32_16x16x32_bf16 v[120:123], v[116:119], v[206:209], v[120:123]
	v_mfma_f32_16x16x32_bf16 v[92:95], v[108:111], v[224:227], v[92:95]
	v_mfma_f32_16x16x32_bf16 v[88:91], v[116:119], v[224:227], v[88:91]
	v_mfma_f32_16x16x32_bf16 v[76:79], v[108:111], v[232:235], v[76:79]
	v_mfma_f32_16x16x32_bf16 v[72:75], v[116:119], v[232:235], v[72:75]
	v_mfma_f32_16x16x32_bf16 v[132:135], v[144:147], v[160:163], v[132:135]
	v_mfma_f32_16x16x32_bf16 v[128:131], v[152:155], v[160:163], v[128:131]
	v_mfma_f32_16x16x32_bf16 v[100:103], v[144:147], v[196:199], v[100:103]
	v_mfma_f32_16x16x32_bf16 v[96:99], v[152:155], v[196:199], v[96:99]
	v_mfma_f32_16x16x32_bf16 v[84:87], v[144:147], v[210:213], v[84:87]
	v_mfma_f32_16x16x32_bf16 v[80:83], v[152:155], v[210:213], v[80:83]
	v_mfma_f32_16x16x32_bf16 v[68:71], v[144:147], v[228:231], v[68:71]
	v_mfma_f32_16x16x32_bf16 v[64:67], v[152:155], v[228:231], v[64:67]
	v_mfma_f32_16x16x32_bf16 v[132:135], v[148:151], v[192:195], v[132:135]
	v_mfma_f32_16x16x32_bf16 v[128:131], v[156:159], v[192:195], v[128:131]
	v_mfma_f32_16x16x32_bf16 v[100:103], v[148:151], v[206:209], v[100:103]
	v_mfma_f32_16x16x32_bf16 v[96:99], v[156:159], v[206:209], v[96:99]
	v_mfma_f32_16x16x32_bf16 v[84:87], v[148:151], v[224:227], v[84:87]
	v_mfma_f32_16x16x32_bf16 v[80:83], v[156:159], v[224:227], v[80:83]
	v_mfma_f32_16x16x32_bf16 v[68:71], v[148:151], v[232:235], v[68:71]
	v_mfma_f32_16x16x32_bf16 v[64:67], v[156:159], v[232:235], v[64:67]
	s_barrier
	s_add_i32 s50, s63, s21
	s_mov_b32 m0, s50
	s_nop 0
	global_load_lds_dwordx4 v172, s[52:53]
	s_add_i32 m0, s50, 0x2000
	s_add_u32 s50, s52, 0xa0000
	s_addc_u32 s51, s53, 0
	s_add_u32 vcc_lo, s52, 0x80
	s_addc_u32 vcc_hi, s53, 0
	s_add_i32 s63, s64, s21
	global_load_lds_dwordx4 v168, s[52:53]
	s_mov_b32 m0, s63
	s_nop 0
	global_load_lds_dwordx4 v172, s[50:51]
	s_add_i32 m0, s63, 0x2000
	s_nop 0
	global_load_lds_dwordx4 v168, s[50:51]
	s_mov_b32 m0, s30
	s_nop 0
	global_load_lds_dwordx4 v164, s[54:55]
	s_mov_b32 m0, s31
	s_nop 0
	global_load_lds_dwordx4 v166, s[54:55]
	ds_read_b128 v[160:163], v204 offset:16384
	ds_read_b128 v[192:195], v204 offset:17408
	ds_read_b128 v[196:199], v204 offset:18432
	ds_read_b128 v[206:209], v204 offset:19456
	ds_read_b128 v[210:213], v204 offset:20480
	ds_read_b128 v[224:227], v204 offset:21504
	ds_read_b128 v[228:231], v204 offset:22528
	ds_read_b128 v[232:235], v204 offset:23552
	s_waitcnt vmcnt(8) lgkmcnt(0)
	s_barrier
	v_mfma_f32_16x16x32_bf16 v[60:63], v[104:107], v[160:163], v[60:63]
	v_mfma_f32_16x16x32_bf16 v[56:59], v[112:115], v[160:163], v[56:59]
	v_mfma_f32_16x16x32_bf16 v[44:47], v[104:107], v[196:199], v[44:47]
	v_mfma_f32_16x16x32_bf16 v[40:43], v[112:115], v[196:199], v[40:43]
	v_mfma_f32_16x16x32_bf16 v[28:31], v[104:107], v[210:213], v[28:31]
	v_mfma_f32_16x16x32_bf16 v[24:27], v[112:115], v[210:213], v[24:27]
	v_mfma_f32_16x16x32_bf16 v[12:15], v[104:107], v[228:231], v[12:15]
	v_mfma_f32_16x16x32_bf16 v[8:11], v[112:115], v[228:231], v[8:11]
	v_mfma_f32_16x16x32_bf16 v[60:63], v[108:111], v[192:195], v[60:63]
	v_mfma_f32_16x16x32_bf16 v[56:59], v[116:119], v[192:195], v[56:59]
	v_mfma_f32_16x16x32_bf16 v[44:47], v[108:111], v[206:209], v[44:47]
	v_mfma_f32_16x16x32_bf16 v[40:43], v[116:119], v[206:209], v[40:43]
	v_mfma_f32_16x16x32_bf16 v[28:31], v[108:111], v[224:227], v[28:31]
	v_mfma_f32_16x16x32_bf16 v[24:27], v[116:119], v[224:227], v[24:27]
	v_mfma_f32_16x16x32_bf16 v[12:15], v[108:111], v[232:235], v[12:15]
	v_mfma_f32_16x16x32_bf16 v[8:11], v[116:119], v[232:235], v[8:11]
	v_mfma_f32_16x16x32_bf16 v[52:55], v[144:147], v[160:163], v[52:55]
	v_mfma_f32_16x16x32_bf16 v[48:51], v[152:155], v[160:163], v[48:51]
	v_mfma_f32_16x16x32_bf16 v[36:39], v[144:147], v[196:199], v[36:39]
	v_mfma_f32_16x16x32_bf16 v[32:35], v[152:155], v[196:199], v[32:35]
	v_mfma_f32_16x16x32_bf16 v[20:23], v[144:147], v[210:213], v[20:23]
	v_mfma_f32_16x16x32_bf16 v[16:19], v[152:155], v[210:213], v[16:19]
	v_mfma_f32_16x16x32_bf16 v[4:7], v[144:147], v[228:231], v[4:7]
	v_mfma_f32_16x16x32_bf16 v[0:3], v[152:155], v[228:231], v[0:3]
	v_mfma_f32_16x16x32_bf16 v[52:55], v[148:151], v[192:195], v[52:55]
	v_mfma_f32_16x16x32_bf16 v[48:51], v[156:159], v[192:195], v[48:51]
	v_mfma_f32_16x16x32_bf16 v[36:39], v[148:151], v[206:209], v[36:39]
	v_mfma_f32_16x16x32_bf16 v[32:35], v[156:159], v[206:209], v[32:35]
	v_mfma_f32_16x16x32_bf16 v[20:23], v[148:151], v[224:227], v[20:23]
	v_mfma_f32_16x16x32_bf16 v[16:19], v[156:159], v[224:227], v[16:19]
	v_mfma_f32_16x16x32_bf16 v[4:7], v[148:151], v[232:235], v[4:7]
	v_mfma_f32_16x16x32_bf16 v[0:3], v[156:159], v[232:235], v[0:3]
	s_barrier
; #define PG8_STAGE(bufoff, gbase, voff) do { _Pragma("unroll") for (int _i = 0; _i < 2; ++_i) \
;         __builtin_amdgcn_global_load_lds((const unsigned*)((const char*)(gbase) + (voff)[_i]), (PG8_LAS unsigned*)(lds + (bufoff) + ldsw + _i * 8192), 16, 0, 0); } while (0)
; #define PG8_LDA(dst, b, h) do { _Pragma("unroll") for (int m = 0; m < 4; ++m) _Pragma("unroll") for (int k = 0; k < 2; ++k) dst[m][k] = *(const PG8_LAS bf16x8*)(lds + PG8_SA(b, h) + aoff + m * 2048 + k * 1024); } while (0)
; #define PG8_LDB(dst, b, h) do { _Pragma("unroll") for (int n = 0; n < 2; ++n) _Pragma("unroll") for (int k = 0; k < 2; ++k) dst[n][k] = *(const PG8_LAS bf16x8*)(lds + PG8_SB(b, h) + boff + n * 2048 + k * 1024); } while (0)
; #define PG8_MMA(ai, bj, At, Bt) do { __builtin_amdgcn_s_setprio(1); _Pragma("unroll") for (int m = 0; m < 4; ++m) _Pragma("unroll") for (int n = 0; n < 2; ++n) _Pragma("unroll") for (int k = 0; k < 2; ++k) \
;         acc[ai][bj][m][n] = __builtin_amdgcn_mfma_f32_16x16x32_bf16(Bt[n][k], At[m][k], acc[ai][bj][m][n], 0, 0, 0); __builtin_amdgcn_s_setprio(0); } while (0)
; #define PG8_WAIT_V(n) asm volatile("s_waitcnt vmcnt(" #n ")" ::: "memory")
; #define PG8_WAIT_L(n) asm volatile("s_waitcnt lgkmcnt(" #n ")" ::: "memory")
; #define PG8_BAR __builtin_amdgcn_s_barrier()
; #define PG8_SCHED __builtin_amdgcn_sched_barrier(0)
; template <class Epi, class Sched, bool ALIGN_EPI = false, bool SP2 = false>
; __device__ __forceinline__ void gemm_phase(PG8_LAS unsigned char* lds, const Gemm g, const Sched& S, const Epi& E, const int tid_in) {
;     ...
;             PG8_LDB(B0, 1, 0); PG8_LDB(B1, 1, 1); PG8_SCHED; PG8_LDA(At, 1, 0); PG8_STAGE(PG8_SA(0, 1), a2 + hstepA, voffA);
;             PG8_WAIT_V(8); PG8_WAIT_L(0); PG8_BAR; PG8_MMA(0, 0, At, B0); PG8_MMA(0, 1, At, B1); PG8_BAR; PG8_SCHED;
;             PG8_LDA(At, 1, 1); PG8_STAGE(PG8_SB(1, 0), b3, voffB); PG8_STAGE(PG8_SB(1, 1), b3 + hstepB, voffB); PG8_STAGE(PG8_SA(1, 0), a3, voffA);
;             PG8_WAIT_V(8); PG8_WAIT_L(0); PG8_BAR; PG8_MMA(1, 0, At, B0); PG8_MMA(1, 1, At, B1); PG8_BAR; PG8_SCHED;
;     ...
;         if constexpr (ALIGN_EPI) { if (wr == 0) PG8_BAR; }
	s_add_i32 s63, 0, 0x18000
	s_add_i32 s64, 0, 0x1c000
	s_add_u32 s50, s54, 0xa0000
	s_addc_u32 s51, s55, 0
	s_mov_b32 m0, s6
	s_nop 0
	global_load_lds_dwordx4 v164, s[50:51]
	s_mov_b32 m0, s38
	s_nop 0
	global_load_lds_dwordx4 v166, s[50:51]
	ds_read_b128 v[104:107], v249 offset:32768
	ds_read_b128 v[108:111], v249 offset:33792
	ds_read_b128 v[112:115], v249 offset:34816
	ds_read_b128 v[116:119], v249 offset:35840
	ds_read_b128 v[144:147], v249 offset:49152
	ds_read_b128 v[148:151], v249 offset:50176
	ds_read_b128 v[152:155], v249 offset:51200
	ds_read_b128 v[156:159], v249 offset:52224
	ds_read_b128 v[160:163], v204 offset:32768
	ds_read_b128 v[192:195], v204 offset:33792
	ds_read_b128 v[196:199], v204 offset:34816
	ds_read_b128 v[206:209], v204 offset:35840
	ds_read_b128 v[210:213], v204 offset:36864
	ds_read_b128 v[224:227], v204 offset:37888
	ds_read_b128 v[228:231], v204 offset:38912
	ds_read_b128 v[232:235], v204 offset:39936
	s_waitcnt vmcnt(8) lgkmcnt(0)
	s_barrier
	v_mfma_f32_16x16x32_bf16 v[140:143], v[104:107], v[160:163], v[140:143]
	v_mfma_f32_16x16x32_bf16 v[136:139], v[112:115], v[160:163], v[136:139]
	v_mfma_f32_16x16x32_bf16 v[124:127], v[104:107], v[196:199], v[124:127]
	v_mfma_f32_16x16x32_bf16 v[120:123], v[112:115], v[196:199], v[120:123]
	v_mfma_f32_16x16x32_bf16 v[92:95], v[104:107], v[210:213], v[92:95]
	v_mfma_f32_16x16x32_bf16 v[88:91], v[112:115], v[210:213], v[88:91]
	v_mfma_f32_16x16x32_bf16 v[76:79], v[104:107], v[228:231], v[76:79]
	v_mfma_f32_16x16x32_bf16 v[72:75], v[112:115], v[228:231], v[72:75]
	v_mfma_f32_16x16x32_bf16 v[140:143], v[108:111], v[192:195], v[140:143]
	v_mfma_f32_16x16x32_bf16 v[136:139], v[116:119], v[192:195], v[136:139]
	v_mfma_f32_16x16x32_bf16 v[124:127], v[108:111], v[206:209], v[124:127]
	v_mfma_f32_16x16x32_bf16 v[120:123], v[116:119], v[206:209], v[120:123]
	v_mfma_f32_16x16x32_bf16 v[92:95], v[108:111], v[224:227], v[92:95]
	v_mfma_f32_16x16x32_bf16 v[88:91], v[116:119], v[224:227], v[88:91]
	v_mfma_f32_16x16x32_bf16 v[76:79], v[108:111], v[232:235], v[76:79]
	v_mfma_f32_16x16x32_bf16 v[72:75], v[116:119], v[232:235], v[72:75]
	v_mfma_f32_16x16x32_bf16 v[132:135], v[144:147], v[160:163], v[132:135]
	v_mfma_f32_16x16x32_bf16 v[128:131], v[152:155], v[160:163], v[128:131]
	v_mfma_f32_16x16x32_bf16 v[100:103], v[144:147], v[196:199], v[100:103]
	v_mfma_f32_16x16x32_bf16 v[96:99], v[152:155], v[196:199], v[96:99]
	v_mfma_f32_16x16x32_bf16 v[84:87], v[144:147], v[210:213], v[84:87]
	v_mfma_f32_16x16x32_bf16 v[80:83], v[152:155], v[210:213], v[80:83]
	v_mfma_f32_16x16x32_bf16 v[68:71], v[144:147], v[228:231], v[68:71]
	v_mfma_f32_16x16x32_bf16 v[64:67], v[152:155], v[228:231], v[64:67]
	v_mfma_f32_16x16x32_bf16 v[132:135], v[148:151], v[192:195], v[132:135]
	v_mfma_f32_16x16x32_bf16 v[128:131], v[156:159], v[192:195], v[128:131]
	v_mfma_f32_16x16x32_bf16 v[100:103], v[148:151], v[206:209], v[100:103]
	v_mfma_f32_16x16x32_bf16 v[96:99], v[156:159], v[206:209], v[96:99]
	v_mfma_f32_16x16x32_bf16 v[84:87], v[148:151], v[224:227], v[84:87]
	v_mfma_f32_16x16x32_bf16 v[80:83], v[156:159], v[224:227], v[80:83]
	v_mfma_f32_16x16x32_bf16 v[68:71], v[148:151], v[232:235], v[68:71]
	v_mfma_f32_16x16x32_bf16 v[64:67], v[156:159], v[232:235], v[64:67]
	s_barrier
	s_add_i32 s50, s63, s21
	s_mov_b32 m0, s50
	s_add_u32 s100, s52, 0x80
	s_addc_u32 s101, s53, 0
	global_load_lds_dwordx4 v172, s[100:101]
	s_add_i32 m0, s50, 0x2000
	s_add_u32 s50, s52, 0xa0080
	s_addc_u32 s51, s53, 0
	s_add_i32 s52, s64, s21
	global_load_lds_dwordx4 v168, vcc
	s_mov_b32 m0, s52
	s_nop 0
	global_load_lds_dwordx4 v172, s[50:51]
	s_add_i32 m0, s52, 0x2000
	s_nop 0
	global_load_lds_dwordx4 v168, s[50:51]
	s_mov_b32 m0, s33
	s_nop 0
	s_add_u32 s100, s54, 0x80
	s_addc_u32 s101, s55, 0
	global_load_lds_dwordx4 v164, s[100:101]
	s_mov_b32 m0, s35
	s_nop 0
	global_load_lds_dwordx4 v166, s[100:101]
	ds_read_b128 v[160:163], v204 offset:49152
	ds_read_b128 v[192:195], v204 offset:50176
	ds_read_b128 v[196:199], v204 offset:51200
	ds_read_b128 v[206:209], v204 offset:52224
	ds_read_b128 v[210:213], v204 offset:53248
	ds_read_b128 v[224:227], v204 offset:54272
	ds_read_b128 v[228:231], v204 offset:55296
	ds_read_b128 v[232:235], v204 offset:56320
	s_waitcnt vmcnt(8) lgkmcnt(0)
	s_barrier
	v_mfma_f32_16x16x32_bf16 v[60:63], v[104:107], v[160:163], v[60:63]
	v_mfma_f32_16x16x32_bf16 v[56:59], v[112:115], v[160:163], v[56:59]
	v_mfma_f32_16x16x32_bf16 v[44:47], v[104:107], v[196:199], v[44:47]
	v_mfma_f32_16x16x32_bf16 v[40:43], v[112:115], v[196:199], v[40:43]
	v_mfma_f32_16x16x32_bf16 v[28:31], v[104:107], v[210:213], v[28:31]
	v_mfma_f32_16x16x32_bf16 v[24:27], v[112:115], v[210:213], v[24:27]
	v_mfma_f32_16x16x32_bf16 v[12:15], v[104:107], v[228:231], v[12:15]
	v_mfma_f32_16x16x32_bf16 v[8:11], v[112:115], v[228:231], v[8:11]
	v_mfma_f32_16x16x32_bf16 v[60:63], v[108:111], v[192:195], v[60:63]
	v_mfma_f32_16x16x32_bf16 v[56:59], v[116:119], v[192:195], v[56:59]
	v_mfma_f32_16x16x32_bf16 v[44:47], v[108:111], v[206:209], v[44:47]
	v_mfma_f32_16x16x32_bf16 v[40:43], v[116:119], v[206:209], v[40:43]
	v_mfma_f32_16x16x32_bf16 v[28:31], v[108:111], v[224:227], v[28:31]
	v_mfma_f32_16x16x32_bf16 v[24:27], v[116:119], v[224:227], v[24:27]
	v_mfma_f32_16x16x32_bf16 v[12:15], v[108:111], v[232:235], v[12:15]
	v_mfma_f32_16x16x32_bf16 v[8:11], v[116:119], v[232:235], v[8:11]
	v_mfma_f32_16x16x32_bf16 v[52:55], v[144:147], v[160:163], v[52:55]
	v_mfma_f32_16x16x32_bf16 v[48:51], v[152:155], v[160:163], v[48:51]
	v_mfma_f32_16x16x32_bf16 v[36:39], v[144:147], v[196:199], v[36:39]
	v_mfma_f32_16x16x32_bf16 v[32:35], v[152:155], v[196:199], v[32:35]
	v_mfma_f32_16x16x32_bf16 v[20:23], v[144:147], v[210:213], v[20:23]
	v_mfma_f32_16x16x32_bf16 v[16:19], v[152:155], v[210:213], v[16:19]
	v_mfma_f32_16x16x32_bf16 v[4:7], v[144:147], v[228:231], v[4:7]
	v_mfma_f32_16x16x32_bf16 v[0:3], v[152:155], v[228:231], v[0:3]
	v_mfma_f32_16x16x32_bf16 v[52:55], v[148:151], v[192:195], v[52:55]
	v_mfma_f32_16x16x32_bf16 v[48:51], v[156:159], v[192:195], v[48:51]
	v_mfma_f32_16x16x32_bf16 v[36:39], v[148:151], v[206:209], v[36:39]
	v_mfma_f32_16x16x32_bf16 v[32:35], v[156:159], v[206:209], v[32:35]
	v_mfma_f32_16x16x32_bf16 v[20:23], v[148:151], v[224:227], v[20:23]
	v_mfma_f32_16x16x32_bf16 v[16:19], v[156:159], v[224:227], v[16:19]
	v_mfma_f32_16x16x32_bf16 v[4:7], v[148:151], v[232:235], v[4:7]
	v_mfma_f32_16x16x32_bf16 v[0:3], v[156:159], v[232:235], v[0:3]
	s_barrier
	s_add_i32 s62, s62, 2
	s_add_u32 s60, s60, 0x100
	s_addc_u32 s61, s61, 0
	s_cmp_gt_u32 s62, 37
	s_mov_b64 s[50:51], s[22:23]
	s_cbranch_scc0 .LBB0_1268
	s_and_b64 vcc, exec, s[46:47]
	s_cbranch_vccz .LBB0_1271
	s_barrier

;     __device__ __forceinline__ void a_ready(const Unit& u) const { wait_panel(cnt, u.pm, need, tmo, wave); }
;     __device__ __forceinline__ void a_ready(const Unit& u) const { wait_panel(cnt, u.pm, need, tmo, wave); }
; #define PG8_STAGE(bufoff, gbase, voff) do { _Pragma("unroll") for (int _i = 0; _i < 2; ++_i) \
;         __builtin_amdgcn_global_load_lds((const unsigned*)((const char*)(gbase) + (voff)[_i]), (PG8_LAS unsigned*)(lds + (bufoff) + ldsw + _i * 8192), 16, 0, 0); } while (0)
; #define PG8_LDA(dst, b, h) do { _Pragma("unroll") for (int m = 0; m < 4; ++m) _Pragma("unroll") for (int k = 0; k < 2; ++k) dst[m][k] = *(const PG8_LAS bf16x8*)(lds + PG8_SA(b, h) + aoff + m * 2048 + k * 1024); } while (0)
; #define PG8_LDB(dst, b, h) do { _Pragma("unroll") for (int n = 0; n < 2; ++n) _Pragma("unroll") for (int k = 0; k < 2; ++k) dst[n][k] = *(const PG8_LAS bf16x8*)(lds + PG8_SB(b, h) + boff + n * 2048 + k * 1024); } while (0)
; #define PG8_WAIT_V(n) asm volatile("s_waitcnt vmcnt(" #n ")" ::: "memory")
; #define PG8_WAIT_L(n) asm volatile("s_waitcnt lgkmcnt(" #n ")" ::: "memory")
; #define PG8_BAR __builtin_amdgcn_s_barrier()
; #define PG8_SCHED __builtin_amdgcn_sched_barrier(0)
; template <class Epi, class Sched, bool ALIGN_EPI = false, bool SP2 = false>
; __device__ __forceinline__ void gemm_phase(PG8_LAS unsigned char* lds, const Gemm g, const Sched& S, const Epi& E, const int tid_in) {
;     ...
;             const bool last = (t == nt - 2);
;             const char* a1 = cA + (size_t)(t + 1) * kstep;
;             const char* a2 = last ? nA : cA + (size_t)(t + 2) * kstep; const char* b2 = last ? nB : cB + (size_t)(t + 2) * kstep;
;             const char* a3 = a2 + kstep; const char* b3 = b2 + kstep;
;             if (last && has_next) S.a_ready(nxt);
;             if constexpr (SP2) {
;             PG8_LDB(B0, 0, 0); PG8_LDB(B1, 0, 1); PG8_SCHED; PG8_LDA(At, 0, 0); PG8_STAGE(PG8_SA(1, 1), a1 + hstepA, voffA);
;             PG8_WAIT_V(8); PG8_WAIT_L(0); PG8_BAR; PG8_MMA(0, 0, At, B0); PG8_MMA(0, 1, At, B1); PG8_BAR; PG8_SCHED;
;             PG8_LDA(At, 0, 1); PG8_STAGE(PG8_SB(0, 0), b2, voffB); PG8_STAGE(PG8_SB(0, 1), b2 + hstepB, voffB); PG8_STAGE(PG8_SA(0, 0), a2, voffA);
;             PG8_WAIT_V(8); PG8_WAIT_L(0); PG8_BAR; PG8_MMA(1, 0, At, B0); PG8_MMA(1, 1, At, B1); PG8_BAR; PG8_SCHED;
.LBB0_1286:
	s_add_u32 s22, s62, 0x100
	s_addc_u32 s23, s63, 0
	s_add_i32 s68, 0, 0x10000
	s_cmp_eq_u32 s61, 4
	s_cselect_b32 s67, s57, s23
	s_cselect_b32 s66, s56, s22
	s_cselect_b32 s65, s55, s60
	s_cselect_b32 s64, s54, s59
	s_add_i32 s69, 0, 0x14000
	s_add_i32 m0, s12, 0xc000
	s_nop 0
	global_load_lds_dwordx4 v148, s[62:63]
	s_add_i32 m0, s12, 0xe000
	s_nop 0
	global_load_lds_dwordx4 v146, s[62:63]
	ds_read_b128 v[64:67], v249
	ds_read_b128 v[68:71], v249 offset:1024
	ds_read_b128 v[72:75], v249 offset:2048
	ds_read_b128 v[76:79], v249 offset:3072
	ds_read_b128 v[80:83], v249 offset:16384
	ds_read_b128 v[84:87], v249 offset:17408
	ds_read_b128 v[88:91], v249 offset:18432
	ds_read_b128 v[92:95], v249 offset:19456
	ds_read_b128 v[96:99], v154
	ds_read_b128 v[100:103], v154 offset:1024
	ds_read_b128 v[104:107], v154 offset:2048
	ds_read_b128 v[108:111], v154 offset:3072
	ds_read_b128 v[112:115], v154 offset:4096
	ds_read_b128 v[116:119], v154 offset:5120
	ds_read_b128 v[120:123], v154 offset:6144
	ds_read_b128 v[124:127], v154 offset:7168
	s_waitcnt vmcnt(8) lgkmcnt(0)
	s_barrier
	v_mfma_f32_16x16x32_bf16 v[60:63], v[64:67], v[96:99], v[60:63]
	v_mfma_f32_16x16x32_bf16 v[56:59], v[72:75], v[96:99], v[56:59]
	v_mfma_f32_16x16x32_bf16 v[48:51], v[64:67], v[104:107], v[48:51]
	v_mfma_f32_16x16x32_bf16 v[40:43], v[72:75], v[104:107], v[40:43]
	v_mfma_f32_16x16x32_bf16 v[32:35], v[64:67], v[112:115], v[32:35]
	v_mfma_f32_16x16x32_bf16 v[24:27], v[72:75], v[112:115], v[24:27]
	v_mfma_f32_16x16x32_bf16 v[16:19], v[64:67], v[120:123], v[16:19]
	v_mfma_f32_16x16x32_bf16 v[8:11], v[72:75], v[120:123], v[8:11]
	v_mfma_f32_16x16x32_bf16 v[60:63], v[68:71], v[100:103], v[60:63]
	v_mfma_f32_16x16x32_bf16 v[56:59], v[76:79], v[100:103], v[56:59]
	v_mfma_f32_16x16x32_bf16 v[48:51], v[68:71], v[108:111], v[48:51]
	v_mfma_f32_16x16x32_bf16 v[40:43], v[76:79], v[108:111], v[40:43]
	v_mfma_f32_16x16x32_bf16 v[32:35], v[68:71], v[116:119], v[32:35]
	v_mfma_f32_16x16x32_bf16 v[24:27], v[76:79], v[116:119], v[24:27]
	v_mfma_f32_16x16x32_bf16 v[16:19], v[68:71], v[124:127], v[16:19]
	v_mfma_f32_16x16x32_bf16 v[8:11], v[76:79], v[124:127], v[8:11]
	v_mfma_f32_16x16x32_bf16 v[52:55], v[80:83], v[96:99], v[52:55]
	v_mfma_f32_16x16x32_bf16 v[44:47], v[88:91], v[96:99], v[44:47]
	v_mfma_f32_16x16x32_bf16 v[36:39], v[80:83], v[104:107], v[36:39]
	v_mfma_f32_16x16x32_bf16 v[28:31], v[88:91], v[104:107], v[28:31]
	v_mfma_f32_16x16x32_bf16 v[20:23], v[80:83], v[112:115], v[20:23]
	v_mfma_f32_16x16x32_bf16 v[12:15], v[88:91], v[112:115], v[12:15]
	v_mfma_f32_16x16x32_bf16 v[4:7], v[80:83], v[120:123], v[4:7]
	v_mfma_f32_16x16x32_bf16 v[0:3], v[88:91], v[120:123], v[0:3]
	v_mfma_f32_16x16x32_bf16 v[52:55], v[84:87], v[100:103], v[52:55]
	v_mfma_f32_16x16x32_bf16 v[44:47], v[92:95], v[100:103], v[44:47]
	v_mfma_f32_16x16x32_bf16 v[36:39], v[84:87], v[108:111], v[36:39]
	v_mfma_f32_16x16x32_bf16 v[28:31], v[92:95], v[108:111], v[28:31]
	v_mfma_f32_16x16x32_bf16 v[20:23], v[84:87], v[116:119], v[20:23]
	v_mfma_f32_16x16x32_bf16 v[12:15], v[92:95], v[116:119], v[12:15]
	v_mfma_f32_16x16x32_bf16 v[4:7], v[84:87], v[124:127], v[4:7]
	v_mfma_f32_16x16x32_bf16 v[0:3], v[92:95], v[124:127], v[0:3]
	s_barrier
	s_add_i32 s62, s68, s6
	s_mov_b32 m0, s62
	s_add_u32 vcc_lo, s64, 0x80
	s_addc_u32 vcc_hi, s65, 0
	global_load_lds_dwordx4 v172, s[64:65]
	s_add_i32 m0, s62, 0x2000
	s_add_u32 s62, s64, 0xa0000
	s_addc_u32 s63, s65, 0
	s_add_i32 s68, s69, s6
	global_load_lds_dwordx4 v128, s[64:65]
	s_mov_b32 m0, s68
	s_nop 0
	global_load_lds_dwordx4 v172, s[62:63]
	s_add_i32 m0, s68, 0x2000
	s_nop 0
	global_load_lds_dwordx4 v128, s[62:63]
	s_mov_b32 m0, s12
	s_nop 0
	global_load_lds_dwordx4 v172, s[66:67]
	s_mov_b32 m0, s20
	s_nop 0
	global_load_lds_dwordx4 v128, s[66:67]
	s_waitcnt vmcnt(8) lgkmcnt(0)
	s_barrier
	s_barrier
; #define PG8_STAGE(bufoff, gbase, voff) do { _Pragma("unroll") for (int _i = 0; _i < 2; ++_i) \
;         __builtin_amdgcn_global_load_lds((const unsigned*)((const char*)(gbase) + (voff)[_i]), (PG8_LAS unsigned*)(lds + (bufoff) + ldsw + _i * 8192), 16, 0, 0); } while (0)
; #define PG8_LDA(dst, b, h) do { _Pragma("unroll") for (int m = 0; m < 4; ++m) _Pragma("unroll") for (int k = 0; k < 2; ++k) dst[m][k] = *(const PG8_LAS bf16x8*)(lds + PG8_SA(b, h) + aoff + m * 2048 + k * 1024); } while (0)
; #define PG8_LDB(dst, b, h) do { _Pragma("unroll") for (int n = 0; n < 2; ++n) _Pragma("unroll") for (int k = 0; k < 2; ++k) dst[n][k] = *(const PG8_LAS bf16x8*)(lds + PG8_SB(b, h) + boff + n * 2048 + k * 1024); } while (0)
; #define PG8_MMA(ai, bj, At, Bt) do { __builtin_amdgcn_s_setprio(1); _Pragma("unroll") for (int m = 0; m < 4; ++m) _Pragma("unroll") for (int n = 0; n < 2; ++n) _Pragma("unroll") for (int k = 0; k < 2; ++k) \
;         acc[ai][bj][m][n] = __builtin_amdgcn_mfma_f32_16x16x32_bf16(Bt[n][k], At[m][k], acc[ai][bj][m][n], 0, 0, 0); __builtin_amdgcn_s_setprio(0); } while (0)
; #define PG8_WAIT_V(n) asm volatile("s_waitcnt vmcnt(" #n ")" ::: "memory")
; #define PG8_WAIT_L(n) asm volatile("s_waitcnt lgkmcnt(" #n ")" ::: "memory")
; #define PG8_BAR __builtin_amdgcn_s_barrier()
; #define PG8_SCHED __builtin_amdgcn_sched_barrier(0)
; template <class Epi, class Sched, bool ALIGN_EPI = false, bool SP2 = false>
; __device__ __forceinline__ void gemm_phase(PG8_LAS unsigned char* lds, const Gemm g, const Sched& S, const Epi& E, const int tid_in) {
;     ...
;             PG8_LDB(B0, 1, 0); PG8_LDB(B1, 1, 1); PG8_SCHED; PG8_LDA(At, 1, 0); PG8_STAGE(PG8_SA(0, 1), a2 + hstepA, voffA);
;             PG8_WAIT_V(8); PG8_WAIT_L(0); PG8_BAR; PG8_MMA(0, 0, At, B0); PG8_MMA(0, 1, At, B1); PG8_BAR; PG8_SCHED;
;             PG8_LDA(At, 1, 1); PG8_STAGE(PG8_SB(1, 0), b3, voffB); PG8_STAGE(PG8_SB(1, 1), b3 + hstepB, voffB); PG8_STAGE(PG8_SA(1, 0), a3, voffA);
;             PG8_WAIT_V(8); PG8_WAIT_L(0); PG8_BAR; PG8_MMA(1, 0, At, B0); PG8_MMA(1, 1, At, B1); PG8_BAR; PG8_SCHED;
;     ...
;         if constexpr (ALIGN_EPI) { if (wr == 0) PG8_BAR; }
	s_add_i32 s68, 0, 0x18000
	s_add_i32 s69, 0, 0x1c000
	s_add_u32 s62, s66, 0xa0000
	s_addc_u32 s63, s67, 0
	s_mov_b32 m0, s21
	s_nop 0
	global_load_lds_dwordx4 v172, s[62:63]
	s_mov_b32 m0, s30
	s_nop 0
	global_load_lds_dwordx4 v128, s[62:63]
	ds_read_b128 v[64:67], v249 offset:32768
	ds_read_b128 v[68:71], v249 offset:33792
	ds_read_b128 v[72:75], v249 offset:34816
	ds_read_b128 v[76:79], v249 offset:35840
	ds_read_b128 v[80:83], v249 offset:49152
	ds_read_b128 v[84:87], v249 offset:50176
	ds_read_b128 v[88:91], v249 offset:51200
	ds_read_b128 v[92:95], v249 offset:52224
	ds_read_b128 v[96:99], v154 offset:32768
	ds_read_b128 v[100:103], v154 offset:33792
	ds_read_b128 v[104:107], v154 offset:34816
	ds_read_b128 v[108:111], v154 offset:35840
	ds_read_b128 v[112:115], v154 offset:36864
	ds_read_b128 v[116:119], v154 offset:37888
	ds_read_b128 v[120:123], v154 offset:38912
	ds_read_b128 v[124:127], v154 offset:39936
	s_waitcnt vmcnt(8) lgkmcnt(0)
	s_barrier
	v_mfma_f32_16x16x32_bf16 v[60:63], v[64:67], v[96:99], v[60:63]
	v_mfma_f32_16x16x32_bf16 v[56:59], v[72:75], v[96:99], v[56:59]
	v_mfma_f32_16x16x32_bf16 v[48:51], v[64:67], v[104:107], v[48:51]
	v_mfma_f32_16x16x32_bf16 v[40:43], v[72:75], v[104:107], v[40:43]
	v_mfma_f32_16x16x32_bf16 v[32:35], v[64:67], v[112:115], v[32:35]
	v_mfma_f32_16x16x32_bf16 v[24:27], v[72:75], v[112:115], v[24:27]
	v_mfma_f32_16x16x32_bf16 v[16:19], v[64:67], v[120:123], v[16:19]
	v_mfma_f32_16x16x32_bf16 v[8:11], v[72:75], v[120:123], v[8:11]
	v_mfma_f32_16x16x32_bf16 v[60:63], v[68:71], v[100:103], v[60:63]
	v_mfma_f32_16x16x32_bf16 v[56:59], v[76:79], v[100:103], v[56:59]
	v_mfma_f32_16x16x32_bf16 v[48:51], v[68:71], v[108:111], v[48:51]
	v_mfma_f32_16x16x32_bf16 v[40:43], v[76:79], v[108:111], v[40:43]
	v_mfma_f32_16x16x32_bf16 v[32:35], v[68:71], v[116:119], v[32:35]
	v_mfma_f32_16x16x32_bf16 v[24:27], v[76:79], v[116:119], v[24:27]
	v_mfma_f32_16x16x32_bf16 v[16:19], v[68:71], v[124:127], v[16:19]
	v_mfma_f32_16x16x32_bf16 v[8:11], v[76:79], v[124:127], v[8:11]
	v_mfma_f32_16x16x32_bf16 v[52:55], v[80:83], v[96:99], v[52:55]
	v_mfma_f32_16x16x32_bf16 v[44:47], v[88:91], v[96:99], v[44:47]
	v_mfma_f32_16x16x32_bf16 v[36:39], v[80:83], v[104:107], v[36:39]
	v_mfma_f32_16x16x32_bf16 v[28:31], v[88:91], v[104:107], v[28:31]
	v_mfma_f32_16x16x32_bf16 v[20:23], v[80:83], v[112:115], v[20:23]
	v_mfma_f32_16x16x32_bf16 v[12:15], v[88:91], v[112:115], v[12:15]
	v_mfma_f32_16x16x32_bf16 v[4:7], v[80:83], v[120:123], v[4:7]
	v_mfma_f32_16x16x32_bf16 v[0:3], v[88:91], v[120:123], v[0:3]
	v_mfma_f32_16x16x32_bf16 v[52:55], v[84:87], v[100:103], v[52:55]
	v_mfma_f32_16x16x32_bf16 v[44:47], v[92:95], v[100:103], v[44:47]
	v_mfma_f32_16x16x32_bf16 v[36:39], v[84:87], v[108:111], v[36:39]
	v_mfma_f32_16x16x32_bf16 v[28:31], v[92:95], v[108:111], v[28:31]
	v_mfma_f32_16x16x32_bf16 v[20:23], v[84:87], v[116:119], v[20:23]
	v_mfma_f32_16x16x32_bf16 v[12:15], v[92:95], v[116:119], v[12:15]
	v_mfma_f32_16x16x32_bf16 v[4:7], v[84:87], v[124:127], v[4:7]
	v_mfma_f32_16x16x32_bf16 v[0:3], v[92:95], v[124:127], v[0:3]
	s_barrier
	s_add_i32 s62, s68, s6
	s_mov_b32 m0, s62
	s_nop 0
	s_add_u32 s100, s64, 0x80
	s_addc_u32 s101, s65, 0
	global_load_lds_dwordx4 v172, s[100:101]
	s_add_i32 m0, s62, 0x2000
	s_add_u32 s62, s64, 0xa0080
	s_addc_u32 s63, s65, 0
	s_add_i32 s64, s69, s6
	global_load_lds_dwordx4 v128, vcc
	s_mov_b32 m0, s64
	s_nop 0
	global_load_lds_dwordx4 v172, s[62:63]
	s_add_i32 m0, s64, 0x2000
	s_nop 0
	global_load_lds_dwordx4 v128, s[62:63]
	s_mov_b32 m0, s31
	s_nop 0
	s_add_u32 s100, s66, 0x80
	s_addc_u32 s101, s67, 0
	global_load_lds_dwordx4 v172, s[100:101]
	s_mov_b32 m0, s33
	s_nop 0
	global_load_lds_dwordx4 v128, s[100:101]
	s_waitcnt vmcnt(8) lgkmcnt(0)
	s_barrier
	s_barrier
	s_add_i32 s61, s61, 2
	s_add_u32 s59, s59, 0x100
	s_addc_u32 s60, s60, 0
	s_cmp_gt_u32 s61, 5
	s_mov_b64 s[62:63], s[22:23]
	s_cbranch_scc0 .LBB0_1286
	s_and_b64 vcc, exec, s[28:29]
	s_cbranch_vccz .LBB0_1289
	s_barrier

;     __device__ __forceinline__ void a_ready(const Unit& u) const { wait_panel(cnt, u.pm, need, tmo, wave); }
;     __device__ __forceinline__ void a_ready(const Unit& u) const { wait_panel(cnt, u.pm, need, tmo, wave); }
; #define PG8_STAGE(bufoff, gbase, voff) do { _Pragma("unroll") for (int _i = 0; _i < 2; ++_i) \
;         __builtin_amdgcn_global_load_lds((const unsigned*)((const char*)(gbase) + (voff)[_i]), (PG8_LAS unsigned*)(lds + (bufoff) + ldsw + _i * 8192), 16, 0, 0); } while (0)
; #define PG8_LDA(dst, b, h) do { _Pragma("unroll") for (int m = 0; m < 4; ++m) _Pragma("unroll") for (int k = 0; k < 2; ++k) dst[m][k] = *(const PG8_LAS bf16x8*)(lds + PG8_SA(b, h) + aoff + m * 2048 + k * 1024); } while (0)
; #define PG8_LDB(dst, b, h) do { _Pragma("unroll") for (int n = 0; n < 2; ++n) _Pragma("unroll") for (int k = 0; k < 2; ++k) dst[n][k] = *(const PG8_LAS bf16x8*)(lds + PG8_SB(b, h) + boff + n * 2048 + k * 1024); } while (0)
; #define PG8_WAIT_V(n) asm volatile("s_waitcnt vmcnt(" #n ")" ::: "memory")
; #define PG8_WAIT_L(n) asm volatile("s_waitcnt lgkmcnt(" #n ")" ::: "memory")
; #define PG8_BAR __builtin_amdgcn_s_barrier()
; #define PG8_SCHED __builtin_amdgcn_sched_barrier(0)
; template <class Epi, class Sched, bool ALIGN_EPI = false, bool SP2 = false>
; __device__ __forceinline__ void gemm_phase(PG8_LAS unsigned char* lds, const Gemm g, const Sched& S, const Epi& E, const int tid_in) {
;     ...
;             const bool last = (t == nt - 2);
;             const char* a1 = cA + (size_t)(t + 1) * kstep;
;             const char* a2 = last ? nA : cA + (size_t)(t + 2) * kstep; const char* b2 = last ? nB : cB + (size_t)(t + 2) * kstep;
;             const char* a3 = a2 + kstep; const char* b3 = b2 + kstep;
;             if (last && has_next) S.a_ready(nxt);
;             if constexpr (SP2) {
;             PG8_LDB(B0, 0, 0); PG8_LDB(B1, 0, 1); PG8_SCHED; PG8_LDA(At, 0, 0); PG8_STAGE(PG8_SA(1, 1), a1 + hstepA, voffA);
;             PG8_WAIT_V(8); PG8_WAIT_L(0); PG8_BAR; PG8_MMA(0, 0, At, B0); PG8_MMA(0, 1, At, B1); PG8_BAR; PG8_SCHED;
;             PG8_LDA(At, 0, 1); PG8_STAGE(PG8_SB(0, 0), b2, voffB); PG8_STAGE(PG8_SB(0, 1), b2 + hstepB, voffB); PG8_STAGE(PG8_SA(0, 0), a2, voffA);
;             PG8_WAIT_V(8); PG8_WAIT_L(0); PG8_BAR; PG8_MMA(1, 0, At, B0); PG8_MMA(1, 1, At, B1); PG8_BAR; PG8_SCHED;
.LBB0_1444:
	s_add_u32 s22, s52, 0xfff80080
	s_addc_u32 s23, s53, -1
	s_add_i32 s58, 0, 0x10000
	s_cmp_eq_u32 s57, 28
	s_cselect_b32 s55, s35, s23
	s_cselect_b32 s54, s38, s22
	s_cselect_b32 s23, s43, s56
	s_cselect_b32 s22, s45, s51
	s_add_i32 s60, 0, 0x14000
	s_add_i32 m0, s18, 0xc000
	s_nop 0
	global_load_lds_dwordx4 v134, s[52:53]
	s_add_i32 m0, s18, 0xe000
	s_nop 0
	global_load_lds_dwordx4 v136, s[52:53]
	ds_read_b128 v[140:143], v249
	ds_read_b128 v[148:151], v249 offset:1024
	ds_read_b128 v[152:155], v249 offset:2048
	ds_read_b128 v[156:159], v249 offset:3072
	ds_read_b128 v[160:163], v249 offset:16384
	ds_read_b128 v[164:167], v249 offset:17408
	ds_read_b128 v[168:171], v249 offset:18432
	ds_read_b128 v[190:193], v249 offset:19456
	ds_read_b128 v[194:197], v147
	ds_read_b128 v[198:201], v147 offset:1024
	ds_read_b128 v[202:205], v147 offset:2048
	ds_read_b128 v[206:209], v147 offset:3072
	ds_read_b128 v[210:213], v147 offset:4096
	ds_read_b128 v[224:227], v147 offset:5120
	ds_read_b128 v[228:231], v147 offset:6144
	ds_read_b128 v[232:235], v147 offset:7168
	s_waitcnt vmcnt(8) lgkmcnt(0)
	s_barrier
	v_mfma_f32_16x16x32_bf16 v[124:127], v[140:143], v[194:197], v[124:127]
	v_mfma_f32_16x16x32_bf16 v[120:123], v[152:155], v[194:197], v[120:123]
	v_mfma_f32_16x16x32_bf16 v[112:115], v[140:143], v[202:205], v[112:115]
	v_mfma_f32_16x16x32_bf16 v[104:107], v[152:155], v[202:205], v[104:107]
	v_mfma_f32_16x16x32_bf16 v[96:99], v[140:143], v[210:213], v[96:99]
	v_mfma_f32_16x16x32_bf16 v[88:91], v[152:155], v[210:213], v[88:91]
	v_mfma_f32_16x16x32_bf16 v[80:83], v[140:143], v[228:231], v[80:83]
	v_mfma_f32_16x16x32_bf16 v[72:75], v[152:155], v[228:231], v[72:75]
	v_mfma_f32_16x16x32_bf16 v[124:127], v[148:151], v[198:201], v[124:127]
	v_mfma_f32_16x16x32_bf16 v[120:123], v[156:159], v[198:201], v[120:123]
	v_mfma_f32_16x16x32_bf16 v[112:115], v[148:151], v[206:209], v[112:115]
	v_mfma_f32_16x16x32_bf16 v[104:107], v[156:159], v[206:209], v[104:107]
	v_mfma_f32_16x16x32_bf16 v[96:99], v[148:151], v[224:227], v[96:99]
	v_mfma_f32_16x16x32_bf16 v[88:91], v[156:159], v[224:227], v[88:91]
	v_mfma_f32_16x16x32_bf16 v[80:83], v[148:151], v[232:235], v[80:83]
	v_mfma_f32_16x16x32_bf16 v[72:75], v[156:159], v[232:235], v[72:75]
	v_mfma_f32_16x16x32_bf16 v[116:119], v[160:163], v[194:197], v[116:119]
	v_mfma_f32_16x16x32_bf16 v[108:111], v[168:171], v[194:197], v[108:111]
	v_mfma_f32_16x16x32_bf16 v[100:103], v[160:163], v[202:205], v[100:103]
	v_mfma_f32_16x16x32_bf16 v[92:95], v[168:171], v[202:205], v[92:95]
	v_mfma_f32_16x16x32_bf16 v[84:87], v[160:163], v[210:213], v[84:87]
	v_mfma_f32_16x16x32_bf16 v[76:79], v[168:171], v[210:213], v[76:79]
	v_mfma_f32_16x16x32_bf16 v[68:71], v[160:163], v[228:231], v[68:71]
	v_mfma_f32_16x16x32_bf16 v[64:67], v[168:171], v[228:231], v[64:67]
	v_mfma_f32_16x16x32_bf16 v[116:119], v[164:167], v[198:201], v[116:119]
	v_mfma_f32_16x16x32_bf16 v[108:111], v[190:193], v[198:201], v[108:111]
	v_mfma_f32_16x16x32_bf16 v[100:103], v[164:167], v[206:209], v[100:103]
	v_mfma_f32_16x16x32_bf16 v[92:95], v[190:193], v[206:209], v[92:95]
	v_mfma_f32_16x16x32_bf16 v[84:87], v[164:167], v[224:227], v[84:87]
	v_mfma_f32_16x16x32_bf16 v[76:79], v[190:193], v[224:227], v[76:79]
	v_mfma_f32_16x16x32_bf16 v[68:71], v[164:167], v[232:235], v[68:71]
	v_mfma_f32_16x16x32_bf16 v[64:67], v[190:193], v[232:235], v[64:67]
	s_barrier
	s_add_i32 s58, s58, s17
	s_mov_b32 m0, s58
	s_nop 0
	global_load_lds_dwordx4 v172, s[22:23]
	s_add_i32 m0, s58, 0x2000
	s_add_u32 s58, s22, 0x80000
	s_addc_u32 s59, s23, 0
	s_add_i32 s60, s60, s17
	global_load_lds_dwordx4 v132, s[22:23]
	s_mov_b32 m0, s60
	s_nop 0
	global_load_lds_dwordx4 v172, s[58:59]
	s_add_i32 m0, s60, 0x2000
	s_nop 0
	global_load_lds_dwordx4 v132, s[58:59]
	s_add_u32 vcc_lo, s54, 0x80
	s_addc_u32 vcc_hi, s55, 0
	s_mov_b32 m0, s18
	s_nop 0
	global_load_lds_dwordx4 v128, s[54:55]
	s_mov_b32 m0, s19
	s_nop 0
	global_load_lds_dwordx4 v130, s[54:55]
	ds_read_b128 v[194:197], v147 offset:16384
	ds_read_b128 v[198:201], v147 offset:17408
	ds_read_b128 v[202:205], v147 offset:18432
	ds_read_b128 v[206:209], v147 offset:19456
	ds_read_b128 v[210:213], v147 offset:20480
	ds_read_b128 v[224:227], v147 offset:21504
	ds_read_b128 v[228:231], v147 offset:22528
	ds_read_b128 v[232:235], v147 offset:23552
	s_waitcnt vmcnt(8) lgkmcnt(0)
	s_barrier
	v_mfma_f32_16x16x32_bf16 v[60:63], v[140:143], v[194:197], v[60:63]
	v_mfma_f32_16x16x32_bf16 v[56:59], v[152:155], v[194:197], v[56:59]
	v_mfma_f32_16x16x32_bf16 v[48:51], v[140:143], v[202:205], v[48:51]
	v_mfma_f32_16x16x32_bf16 v[40:43], v[152:155], v[202:205], v[40:43]
	v_mfma_f32_16x16x32_bf16 v[32:35], v[140:143], v[210:213], v[32:35]
	v_mfma_f32_16x16x32_bf16 v[24:27], v[152:155], v[210:213], v[24:27]
	v_mfma_f32_16x16x32_bf16 v[16:19], v[140:143], v[228:231], v[16:19]
	v_mfma_f32_16x16x32_bf16 v[8:11], v[152:155], v[228:231], v[8:11]
	v_mfma_f32_16x16x32_bf16 v[60:63], v[148:151], v[198:201], v[60:63]
	v_mfma_f32_16x16x32_bf16 v[56:59], v[156:159], v[198:201], v[56:59]
	v_mfma_f32_16x16x32_bf16 v[48:51], v[148:151], v[206:209], v[48:51]
	v_mfma_f32_16x16x32_bf16 v[40:43], v[156:159], v[206:209], v[40:43]
	v_mfma_f32_16x16x32_bf16 v[32:35], v[148:151], v[224:227], v[32:35]
	v_mfma_f32_16x16x32_bf16 v[24:27], v[156:159], v[224:227], v[24:27]
	v_mfma_f32_16x16x32_bf16 v[16:19], v[148:151], v[232:235], v[16:19]
	v_mfma_f32_16x16x32_bf16 v[8:11], v[156:159], v[232:235], v[8:11]
	v_mfma_f32_16x16x32_bf16 v[52:55], v[160:163], v[194:197], v[52:55]
	v_mfma_f32_16x16x32_bf16 v[44:47], v[168:171], v[194:197], v[44:47]
	v_mfma_f32_16x16x32_bf16 v[36:39], v[160:163], v[202:205], v[36:39]
	v_mfma_f32_16x16x32_bf16 v[28:31], v[168:171], v[202:205], v[28:31]
	v_mfma_f32_16x16x32_bf16 v[20:23], v[160:163], v[210:213], v[20:23]
	v_mfma_f32_16x16x32_bf16 v[12:15], v[168:171], v[210:213], v[12:15]
	v_mfma_f32_16x16x32_bf16 v[4:7], v[160:163], v[228:231], v[4:7]
	v_mfma_f32_16x16x32_bf16 v[0:3], v[168:171], v[228:231], v[0:3]
	v_mfma_f32_16x16x32_bf16 v[52:55], v[164:167], v[198:201], v[52:55]
	v_mfma_f32_16x16x32_bf16 v[44:47], v[190:193], v[198:201], v[44:47]
	v_mfma_f32_16x16x32_bf16 v[36:39], v[164:167], v[206:209], v[36:39]
	v_mfma_f32_16x16x32_bf16 v[28:31], v[190:193], v[206:209], v[28:31]
	v_mfma_f32_16x16x32_bf16 v[20:23], v[164:167], v[224:227], v[20:23]
	v_mfma_f32_16x16x32_bf16 v[12:15], v[190:193], v[224:227], v[12:15]
	v_mfma_f32_16x16x32_bf16 v[4:7], v[164:167], v[232:235], v[4:7]
	v_mfma_f32_16x16x32_bf16 v[0:3], v[190:193], v[232:235], v[0:3]
	s_barrier
; #define PG8_STAGE(bufoff, gbase, voff) do { _Pragma("unroll") for (int _i = 0; _i < 2; ++_i) \
;         __builtin_amdgcn_global_load_lds((const unsigned*)((const char*)(gbase) + (voff)[_i]), (PG8_LAS unsigned*)(lds + (bufoff) + ldsw + _i * 8192), 16, 0, 0); } while (0)
; #define PG8_LDA(dst, b, h) do { _Pragma("unroll") for (int m = 0; m < 4; ++m) _Pragma("unroll") for (int k = 0; k < 2; ++k) dst[m][k] = *(const PG8_LAS bf16x8*)(lds + PG8_SA(b, h) + aoff + m * 2048 + k * 1024); } while (0)
; #define PG8_LDB(dst, b, h) do { _Pragma("unroll") for (int n = 0; n < 2; ++n) _Pragma("unroll") for (int k = 0; k < 2; ++k) dst[n][k] = *(const PG8_LAS bf16x8*)(lds + PG8_SB(b, h) + boff + n * 2048 + k * 1024); } while (0)
; #define PG8_MMA(ai, bj, At, Bt) do { __builtin_amdgcn_s_setprio(1); _Pragma("unroll") for (int m = 0; m < 4; ++m) _Pragma("unroll") for (int n = 0; n < 2; ++n) _Pragma("unroll") for (int k = 0; k < 2; ++k) \
;         acc[ai][bj][m][n] = __builtin_amdgcn_mfma_f32_16x16x32_bf16(Bt[n][k], At[m][k], acc[ai][bj][m][n], 0, 0, 0); __builtin_amdgcn_s_setprio(0); } while (0)
; #define PG8_WAIT_V(n) asm volatile("s_waitcnt vmcnt(" #n ")" ::: "memory")
; #define PG8_WAIT_L(n) asm volatile("s_waitcnt lgkmcnt(" #n ")" ::: "memory")
; #define PG8_BAR __builtin_amdgcn_s_barrier()
; #define PG8_SCHED __builtin_amdgcn_sched_barrier(0)
; template <class Epi, class Sched, bool ALIGN_EPI = false, bool SP2 = false>
; __device__ __forceinline__ void gemm_phase(PG8_LAS unsigned char* lds, const Gemm g, const Sched& S, const Epi& E, const int tid_in) {
;     ...
;             PG8_LDB(B0, 1, 0); PG8_LDB(B1, 1, 1); PG8_SCHED; PG8_LDA(At, 1, 0); PG8_STAGE(PG8_SA(0, 1), a2 + hstepA, voffA);
;             PG8_WAIT_V(8); PG8_WAIT_L(0); PG8_BAR; PG8_MMA(0, 0, At, B0); PG8_MMA(0, 1, At, B1); PG8_BAR; PG8_SCHED;
;             PG8_LDA(At, 1, 1); PG8_STAGE(PG8_SB(1, 0), b3, voffB); PG8_STAGE(PG8_SB(1, 1), b3 + hstepB, voffB); PG8_STAGE(PG8_SA(1, 0), a3, voffA);
;             PG8_WAIT_V(8); PG8_WAIT_L(0); PG8_BAR; PG8_MMA(1, 0, At, B0); PG8_MMA(1, 1, At, B1); PG8_BAR; PG8_SCHED;
;     ...
;         if constexpr (ALIGN_EPI) { if (wr == 0) PG8_BAR; }
	s_add_i32 s58, 0, 0x18000
	s_add_i32 s59, 0, 0x1c000
	s_add_u32 s54, s54, 0x80000
	s_addc_u32 s55, s55, 0
	s_mov_b32 m0, s20
	s_nop 0
	global_load_lds_dwordx4 v128, s[54:55]
	s_mov_b32 m0, s21
	s_nop 0
	global_load_lds_dwordx4 v130, s[54:55]
	ds_read_b128 v[140:143], v249 offset:32768
	ds_read_b128 v[148:151], v249 offset:33792
	ds_read_b128 v[152:155], v249 offset:34816
	ds_read_b128 v[156:159], v249 offset:35840
	ds_read_b128 v[160:163], v249 offset:49152
	ds_read_b128 v[164:167], v249 offset:50176
	ds_read_b128 v[168:171], v249 offset:51200
	ds_read_b128 v[190:193], v249 offset:52224
	ds_read_b128 v[194:197], v147 offset:32768
	ds_read_b128 v[198:201], v147 offset:33792
	ds_read_b128 v[202:205], v147 offset:34816
	ds_read_b128 v[206:209], v147 offset:35840
	ds_read_b128 v[210:213], v147 offset:36864
	ds_read_b128 v[224:227], v147 offset:37888
	ds_read_b128 v[228:231], v147 offset:38912
	ds_read_b128 v[232:235], v147 offset:39936
	s_waitcnt vmcnt(8) lgkmcnt(0)
	s_barrier
	v_mfma_f32_16x16x32_bf16 v[124:127], v[140:143], v[194:197], v[124:127]
	v_mfma_f32_16x16x32_bf16 v[120:123], v[152:155], v[194:197], v[120:123]
	v_mfma_f32_16x16x32_bf16 v[112:115], v[140:143], v[202:205], v[112:115]
	v_mfma_f32_16x16x32_bf16 v[104:107], v[152:155], v[202:205], v[104:107]
	v_mfma_f32_16x16x32_bf16 v[96:99], v[140:143], v[210:213], v[96:99]
	v_mfma_f32_16x16x32_bf16 v[88:91], v[152:155], v[210:213], v[88:91]
	v_mfma_f32_16x16x32_bf16 v[80:83], v[140:143], v[228:231], v[80:83]
	v_mfma_f32_16x16x32_bf16 v[72:75], v[152:155], v[228:231], v[72:75]
	v_mfma_f32_16x16x32_bf16 v[124:127], v[148:151], v[198:201], v[124:127]
	v_mfma_f32_16x16x32_bf16 v[120:123], v[156:159], v[198:201], v[120:123]
	v_mfma_f32_16x16x32_bf16 v[112:115], v[148:151], v[206:209], v[112:115]
	v_mfma_f32_16x16x32_bf16 v[104:107], v[156:159], v[206:209], v[104:107]
	v_mfma_f32_16x16x32_bf16 v[96:99], v[148:151], v[224:227], v[96:99]
	v_mfma_f32_16x16x32_bf16 v[88:91], v[156:159], v[224:227], v[88:91]
	v_mfma_f32_16x16x32_bf16 v[80:83], v[148:151], v[232:235], v[80:83]
	v_mfma_f32_16x16x32_bf16 v[72:75], v[156:159], v[232:235], v[72:75]
	v_mfma_f32_16x16x32_bf16 v[116:119], v[160:163], v[194:197], v[116:119]
	v_mfma_f32_16x16x32_bf16 v[108:111], v[168:171], v[194:197], v[108:111]
	v_mfma_f32_16x16x32_bf16 v[100:103], v[160:163], v[202:205], v[100:103]
	v_mfma_f32_16x16x32_bf16 v[92:95], v[168:171], v[202:205], v[92:95]
	v_mfma_f32_16x16x32_bf16 v[84:87], v[160:163], v[210:213], v[84:87]
	v_mfma_f32_16x16x32_bf16 v[76:79], v[168:171], v[210:213], v[76:79]
	v_mfma_f32_16x16x32_bf16 v[68:71], v[160:163], v[228:231], v[68:71]
	v_mfma_f32_16x16x32_bf16 v[64:67], v[168:171], v[228:231], v[64:67]
	v_mfma_f32_16x16x32_bf16 v[116:119], v[164:167], v[198:201], v[116:119]
	v_mfma_f32_16x16x32_bf16 v[108:111], v[190:193], v[198:201], v[108:111]
	v_mfma_f32_16x16x32_bf16 v[100:103], v[164:167], v[206:209], v[100:103]
	v_mfma_f32_16x16x32_bf16 v[92:95], v[190:193], v[206:209], v[92:95]
	v_mfma_f32_16x16x32_bf16 v[84:87], v[164:167], v[224:227], v[84:87]
	v_mfma_f32_16x16x32_bf16 v[76:79], v[190:193], v[224:227], v[76:79]
	v_mfma_f32_16x16x32_bf16 v[68:71], v[164:167], v[232:235], v[68:71]
	v_mfma_f32_16x16x32_bf16 v[64:67], v[190:193], v[232:235], v[64:67]
	s_barrier
	s_add_i32 s54, s58, s17
	s_mov_b32 m0, s54
	s_add_u32 s100, s22, 0x80
	s_addc_u32 s101, s23, 0
	global_load_lds_dwordx4 v172, s[100:101]
	s_add_i32 m0, s54, 0x2000
	s_add_u32 s22, s22, 0x80080
	s_addc_u32 s23, s23, 0
	s_add_i32 s54, s59, s17
	global_load_lds_dwordx4 v132, s[100:101]
	s_mov_b32 m0, s54
	s_nop 0
	global_load_lds_dwordx4 v172, s[22:23]
	s_add_i32 m0, s54, 0x2000
	s_nop 0
	global_load_lds_dwordx4 v132, s[22:23]
	s_mov_b32 m0, s29
	s_nop 0
	global_load_lds_dwordx4 v128, vcc
	s_mov_b32 m0, s30
	s_nop 0
	global_load_lds_dwordx4 v130, vcc
	ds_read_b128 v[194:197], v147 offset:49152
	ds_read_b128 v[198:201], v147 offset:50176
	ds_read_b128 v[202:205], v147 offset:51200
	ds_read_b128 v[206:209], v147 offset:52224
	ds_read_b128 v[210:213], v147 offset:53248
	ds_read_b128 v[224:227], v147 offset:54272
	ds_read_b128 v[228:231], v147 offset:55296
	ds_read_b128 v[232:235], v147 offset:56320
	s_waitcnt vmcnt(8) lgkmcnt(0)
	s_barrier
	v_mfma_f32_16x16x32_bf16 v[60:63], v[140:143], v[194:197], v[60:63]
	v_mfma_f32_16x16x32_bf16 v[56:59], v[152:155], v[194:197], v[56:59]
	v_mfma_f32_16x16x32_bf16 v[48:51], v[140:143], v[202:205], v[48:51]
	v_mfma_f32_16x16x32_bf16 v[40:43], v[152:155], v[202:205], v[40:43]
	v_mfma_f32_16x16x32_bf16 v[32:35], v[140:143], v[210:213], v[32:35]
	v_mfma_f32_16x16x32_bf16 v[24:27], v[152:155], v[210:213], v[24:27]
	v_mfma_f32_16x16x32_bf16 v[16:19], v[140:143], v[228:231], v[16:19]
	v_mfma_f32_16x16x32_bf16 v[8:11], v[152:155], v[228:231], v[8:11]
	v_mfma_f32_16x16x32_bf16 v[60:63], v[148:151], v[198:201], v[60:63]
	v_mfma_f32_16x16x32_bf16 v[56:59], v[156:159], v[198:201], v[56:59]
	v_mfma_f32_16x16x32_bf16 v[48:51], v[148:151], v[206:209], v[48:51]
	v_mfma_f32_16x16x32_bf16 v[40:43], v[156:159], v[206:209], v[40:43]
	v_mfma_f32_16x16x32_bf16 v[32:35], v[148:151], v[224:227], v[32:35]
	v_mfma_f32_16x16x32_bf16 v[24:27], v[156:159], v[224:227], v[24:27]
	v_mfma_f32_16x16x32_bf16 v[16:19], v[148:151], v[232:235], v[16:19]
	v_mfma_f32_16x16x32_bf16 v[8:11], v[156:159], v[232:235], v[8:11]
	v_mfma_f32_16x16x32_bf16 v[52:55], v[160:163], v[194:197], v[52:55]
	v_mfma_f32_16x16x32_bf16 v[44:47], v[168:171], v[194:197], v[44:47]
	v_mfma_f32_16x16x32_bf16 v[36:39], v[160:163], v[202:205], v[36:39]
	v_mfma_f32_16x16x32_bf16 v[28:31], v[168:171], v[202:205], v[28:31]
	v_mfma_f32_16x16x32_bf16 v[20:23], v[160:163], v[210:213], v[20:23]
	v_mfma_f32_16x16x32_bf16 v[12:15], v[168:171], v[210:213], v[12:15]
	v_mfma_f32_16x16x32_bf16 v[4:7], v[160:163], v[228:231], v[4:7]
	v_mfma_f32_16x16x32_bf16 v[0:3], v[168:171], v[228:231], v[0:3]
	v_mfma_f32_16x16x32_bf16 v[52:55], v[164:167], v[198:201], v[52:55]
	v_mfma_f32_16x16x32_bf16 v[44:47], v[190:193], v[198:201], v[44:47]
	v_mfma_f32_16x16x32_bf16 v[36:39], v[164:167], v[206:209], v[36:39]
	v_mfma_f32_16x16x32_bf16 v[28:31], v[190:193], v[206:209], v[28:31]
	v_mfma_f32_16x16x32_bf16 v[20:23], v[164:167], v[224:227], v[20:23]
	v_mfma_f32_16x16x32_bf16 v[12:15], v[190:193], v[224:227], v[12:15]
	v_mfma_f32_16x16x32_bf16 v[4:7], v[164:167], v[232:235], v[4:7]
	v_mfma_f32_16x16x32_bf16 v[0:3], v[190:193], v[232:235], v[0:3]
	s_barrier
	s_add_i32 s57, s57, 2
	s_add_u32 s52, s52, 0x100
	s_addc_u32 s53, s53, 0
	s_add_u32 s51, s51, 0x100
	s_addc_u32 s56, s56, 0
	s_cmp_gt_u32 s57, 29
	s_cbranch_scc0 .LBB0_1444
	s_and_b64 vcc, exec, s[36:37]
	s_cbranch_vccz .LBB0_1447
	s_barrier

;     __device__ __forceinline__ void a_ready(const Unit& u) const { wait_panel(cnt, u.pm, need, tmo, wave); }
;     __device__ __forceinline__ void a_ready(const Unit& u) const { wait_panel(cnt, u.pm, need, tmo, wave); }
; #define PG8_STAGE(bufoff, gbase, voff) do { _Pragma("unroll") for (int _i = 0; _i < 2; ++_i) \
;         __builtin_amdgcn_global_load_lds((const unsigned*)((const char*)(gbase) + (voff)[_i]), (PG8_LAS unsigned*)(lds + (bufoff) + ldsw + _i * 8192), 16, 0, 0); } while (0)
; #define PG8_LDA(dst, b, h) do { _Pragma("unroll") for (int m = 0; m < 4; ++m) _Pragma("unroll") for (int k = 0; k < 2; ++k) dst[m][k] = *(const PG8_LAS bf16x8*)(lds + PG8_SA(b, h) + aoff + m * 2048 + k * 1024); } while (0)
; #define PG8_LDB(dst, b, h) do { _Pragma("unroll") for (int n = 0; n < 2; ++n) _Pragma("unroll") for (int k = 0; k < 2; ++k) dst[n][k] = *(const PG8_LAS bf16x8*)(lds + PG8_SB(b, h) + boff + n * 2048 + k * 1024); } while (0)
; #define PG8_WAIT_V(n) asm volatile("s_waitcnt vmcnt(" #n ")" ::: "memory")
; #define PG8_WAIT_L(n) asm volatile("s_waitcnt lgkmcnt(" #n ")" ::: "memory")
; #define PG8_BAR __builtin_amdgcn_s_barrier()
; #define PG8_SCHED __builtin_amdgcn_sched_barrier(0)
; template <class Epi, class Sched, bool ALIGN_EPI = false, bool SP2 = false>
; __device__ __forceinline__ void gemm_phase(PG8_LAS unsigned char* lds, const Gemm g, const Sched& S, const Epi& E, const int tid_in) {
;     ...
;             const bool last = (t == nt - 2);
;             const char* a1 = cA + (size_t)(t + 1) * kstep;
;             const char* a2 = last ? nA : cA + (size_t)(t + 2) * kstep; const char* b2 = last ? nB : cB + (size_t)(t + 2) * kstep;
;             const char* a3 = a2 + kstep; const char* b3 = b2 + kstep;
;             if (last && has_next) S.a_ready(nxt);
;             if constexpr (SP2) {
;             PG8_LDB(B0, 0, 0); PG8_LDB(B1, 0, 1); PG8_SCHED; PG8_LDA(At, 0, 0); PG8_STAGE(PG8_SA(1, 1), a1 + hstepA, voffA);
;             PG8_WAIT_V(8); PG8_WAIT_L(0); PG8_BAR; PG8_MMA(0, 0, At, B0); PG8_MMA(0, 1, At, B1); PG8_BAR; PG8_SCHED;
;             PG8_LDA(At, 0, 1); PG8_STAGE(PG8_SB(0, 0), b2, voffB); PG8_STAGE(PG8_SB(0, 1), b2 + hstepB, voffB); PG8_STAGE(PG8_SA(0, 0), a2, voffA);
;             PG8_WAIT_V(8); PG8_WAIT_L(0); PG8_BAR; PG8_MMA(1, 0, At, B0); PG8_MMA(1, 1, At, B1); PG8_BAR; PG8_SCHED;
.LBB0_1960:
	s_add_u32 s22, s58, 0xfffc0080
	s_addc_u32 s23, s59, -1
	s_add_i32 s62, 0, 0x10000
	s_cmp_eq_u32 s53, 12
	s_cselect_b32 s61, s11, s23
	s_cselect_b32 s60, s12, s22
	s_cselect_b32 s23, s33, s51
	s_cselect_b32 s22, s34, s35
	s_add_i32 s64, 0, 0x14000
	s_add_i32 m0, s17, 0xc000
	s_nop 0
	global_load_lds_dwordx4 v196, s[58:59]
	s_add_i32 m0, s17, 0xe000
	s_nop 0
	global_load_lds_dwordx4 v198, s[58:59]
	ds_read_b128 v[32:35], v249
	ds_read_b128 v[36:39], v249 offset:1024
	ds_read_b128 v[48:51], v249 offset:2048
	ds_read_b128 v[52:55], v249 offset:3072
	ds_read_b128 v[104:107], v249 offset:16384
	ds_read_b128 v[116:119], v249 offset:17408
	ds_read_b128 v[128:131], v249 offset:18432
	ds_read_b128 v[140:143], v249 offset:19456
	ds_read_b128 v[144:147], v225
	ds_read_b128 v[156:159], v225 offset:1024
	ds_read_b128 v[160:163], v225 offset:2048
	ds_read_b128 v[200:203], v225 offset:3072
	ds_read_b128 v[204:207], v225 offset:4096
	ds_read_b128 v[208:211], v225 offset:5120
	ds_read_b128 v[226:229], v225 offset:6144
	ds_read_b128 v[230:233], v225 offset:7168
	s_waitcnt vmcnt(8) lgkmcnt(0)
	s_barrier
	v_mfma_f32_16x16x32_bf16 v[168:171], v[32:35], v[144:147], v[168:171]
	v_mfma_f32_16x16x32_bf16 v[164:167], v[48:51], v[144:147], v[164:167]
	v_mfma_f32_16x16x32_bf16 v[136:139], v[32:35], v[160:163], v[136:139]
	v_mfma_f32_16x16x32_bf16 v[132:135], v[48:51], v[160:163], v[132:135]
	v_mfma_f32_16x16x32_bf16 v[112:115], v[32:35], v[204:207], v[112:115]
	v_mfma_f32_16x16x32_bf16 v[108:111], v[48:51], v[204:207], v[108:111]
	v_mfma_f32_16x16x32_bf16 v[92:95], v[32:35], v[226:229], v[92:95]
	v_mfma_f32_16x16x32_bf16 v[88:91], v[48:51], v[226:229], v[88:91]
	v_mfma_f32_16x16x32_bf16 v[168:171], v[36:39], v[156:159], v[168:171]
	v_mfma_f32_16x16x32_bf16 v[164:167], v[52:55], v[156:159], v[164:167]
	v_mfma_f32_16x16x32_bf16 v[136:139], v[36:39], v[200:203], v[136:139]
	v_mfma_f32_16x16x32_bf16 v[132:135], v[52:55], v[200:203], v[132:135]
	v_mfma_f32_16x16x32_bf16 v[112:115], v[36:39], v[208:211], v[112:115]
	v_mfma_f32_16x16x32_bf16 v[108:111], v[52:55], v[208:211], v[108:111]
	v_mfma_f32_16x16x32_bf16 v[92:95], v[36:39], v[230:233], v[92:95]
	v_mfma_f32_16x16x32_bf16 v[88:91], v[52:55], v[230:233], v[88:91]
	v_mfma_f32_16x16x32_bf16 v[152:155], v[104:107], v[144:147], v[152:155]
	v_mfma_f32_16x16x32_bf16 v[124:127], v[104:107], v[160:163], v[124:127]
	v_mfma_f32_16x16x32_bf16 v[120:123], v[128:131], v[160:163], v[120:123]
	v_mfma_f32_16x16x32_bf16 v[100:103], v[104:107], v[204:207], v[100:103]
	v_mfma_f32_16x16x32_bf16 v[96:99], v[128:131], v[204:207], v[96:99]
	v_mfma_f32_16x16x32_bf16 v[84:87], v[104:107], v[226:229], v[84:87]
	v_mfma_f32_16x16x32_bf16 v[80:83], v[128:131], v[226:229], v[80:83]
	v_mfma_f32_16x16x32_bf16 v[152:155], v[116:119], v[156:159], v[152:155]
	v_mfma_f32_16x16x32_bf16 v[144:147], v[128:131], v[144:147], v[148:151]
	v_mfma_f32_16x16x32_bf16 v[124:127], v[116:119], v[200:203], v[124:127]
	v_mfma_f32_16x16x32_bf16 v[120:123], v[140:143], v[200:203], v[120:123]
	v_mfma_f32_16x16x32_bf16 v[100:103], v[116:119], v[208:211], v[100:103]
	v_mfma_f32_16x16x32_bf16 v[96:99], v[140:143], v[208:211], v[96:99]
	v_mfma_f32_16x16x32_bf16 v[84:87], v[116:119], v[230:233], v[84:87]
	v_mfma_f32_16x16x32_bf16 v[80:83], v[140:143], v[230:233], v[80:83]
	v_mfma_f32_16x16x32_bf16 v[144:147], v[140:143], v[156:159], v[144:147]
	s_barrier
	s_add_i32 s62, s62, s16
	s_mov_b32 m0, s62
	s_nop 0
	global_load_lds_dwordx4 v172, s[22:23]
	s_add_i32 m0, s62, 0x2000
	s_add_u32 s62, s22, 0x40000
	s_addc_u32 s63, s23, 0
	s_add_i32 s64, s64, s16
	global_load_lds_dwordx4 v194, s[22:23]
	s_mov_b32 m0, s64
	s_nop 0
	global_load_lds_dwordx4 v172, s[62:63]
	s_add_i32 m0, s64, 0x2000
	s_nop 0
	global_load_lds_dwordx4 v194, s[62:63]
	s_add_u32 vcc_lo, s60, 0x80
	s_addc_u32 vcc_hi, s61, 0
	s_mov_b32 m0, s17
	s_nop 0
	global_load_lds_dwordx4 v190, s[60:61]
	s_mov_b32 m0, s18
	s_nop 0
	global_load_lds_dwordx4 v192, s[60:61]
	ds_read_b128 v[148:151], v225 offset:16384
	ds_read_b128 v[156:159], v225 offset:17408
	ds_read_b128 v[160:163], v225 offset:18432
	ds_read_b128 v[200:203], v225 offset:19456
	ds_read_b128 v[204:207], v225 offset:20480
	ds_read_b128 v[208:211], v225 offset:21504
	ds_read_b128 v[226:229], v225 offset:22528
	ds_read_b128 v[230:233], v225 offset:23552
	s_waitcnt vmcnt(8) lgkmcnt(0)
	s_barrier
	v_mfma_f32_16x16x32_bf16 v[76:79], v[32:35], v[148:151], v[76:79]
	v_mfma_f32_16x16x32_bf16 v[72:75], v[48:51], v[148:151], v[72:75]
	v_mfma_f32_16x16x32_bf16 v[60:63], v[32:35], v[160:163], v[60:63]
	v_mfma_f32_16x16x32_bf16 v[56:59], v[48:51], v[160:163], v[56:59]
	v_mfma_f32_16x16x32_bf16 v[28:31], v[32:35], v[204:207], v[28:31]
	v_mfma_f32_16x16x32_bf16 v[24:27], v[48:51], v[204:207], v[24:27]
	v_mfma_f32_16x16x32_bf16 v[12:15], v[32:35], v[226:229], v[12:15]
	v_mfma_f32_16x16x32_bf16 v[8:11], v[48:51], v[226:229], v[8:11]
	v_mfma_f32_16x16x32_bf16 v[76:79], v[36:39], v[156:159], v[76:79]
	v_mfma_f32_16x16x32_bf16 v[72:75], v[52:55], v[156:159], v[72:75]
	v_mfma_f32_16x16x32_bf16 v[60:63], v[36:39], v[200:203], v[60:63]
	v_mfma_f32_16x16x32_bf16 v[56:59], v[52:55], v[200:203], v[56:59]
	v_mfma_f32_16x16x32_bf16 v[28:31], v[36:39], v[208:211], v[28:31]
	v_mfma_f32_16x16x32_bf16 v[24:27], v[52:55], v[208:211], v[24:27]
	v_mfma_f32_16x16x32_bf16 v[12:15], v[36:39], v[230:233], v[12:15]
	v_mfma_f32_16x16x32_bf16 v[8:11], v[52:55], v[230:233], v[8:11]
	v_mfma_f32_16x16x32_bf16 v[44:47], v[104:107], v[160:163], v[44:47]
	v_mfma_f32_16x16x32_bf16 v[40:43], v[128:131], v[160:163], v[40:43]
	v_mfma_f32_16x16x32_bf16 v[20:23], v[104:107], v[204:207], v[20:23]
	v_mfma_f32_16x16x32_bf16 v[16:19], v[128:131], v[204:207], v[16:19]
	v_mfma_f32_16x16x32_bf16 v[4:7], v[104:107], v[226:229], v[4:7]
	v_mfma_f32_16x16x32_bf16 v[0:3], v[128:131], v[226:229], v[0:3]
	v_mfma_f32_16x16x32_bf16 v[32:35], v[104:107], v[148:151], v[68:71]
	v_mfma_f32_16x16x32_bf16 v[36:39], v[128:131], v[148:151], v[64:67]
	v_mfma_f32_16x16x32_bf16 v[44:47], v[116:119], v[200:203], v[44:47]
	v_mfma_f32_16x16x32_bf16 v[40:43], v[140:143], v[200:203], v[40:43]
	v_mfma_f32_16x16x32_bf16 v[20:23], v[116:119], v[208:211], v[20:23]
	v_mfma_f32_16x16x32_bf16 v[16:19], v[140:143], v[208:211], v[16:19]
	v_mfma_f32_16x16x32_bf16 v[4:7], v[116:119], v[230:233], v[4:7]
	v_mfma_f32_16x16x32_bf16 v[0:3], v[140:143], v[230:233], v[0:3]
	v_mfma_f32_16x16x32_bf16 v[32:35], v[116:119], v[156:159], v[32:35]
	v_mfma_f32_16x16x32_bf16 v[36:39], v[140:143], v[156:159], v[36:39]
	s_barrier
; #define PG8_STAGE(bufoff, gbase, voff) do { _Pragma("unroll") for (int _i = 0; _i < 2; ++_i) \
;         __builtin_amdgcn_global_load_lds((const unsigned*)((const char*)(gbase) + (voff)[_i]), (PG8_LAS unsigned*)(lds + (bufoff) + ldsw + _i * 8192), 16, 0, 0); } while (0)
; #define PG8_LDA(dst, b, h) do { _Pragma("unroll") for (int m = 0; m < 4; ++m) _Pragma("unroll") for (int k = 0; k < 2; ++k) dst[m][k] = *(const PG8_LAS bf16x8*)(lds + PG8_SA(b, h) + aoff + m * 2048 + k * 1024); } while (0)
; #define PG8_LDB(dst, b, h) do { _Pragma("unroll") for (int n = 0; n < 2; ++n) _Pragma("unroll") for (int k = 0; k < 2; ++k) dst[n][k] = *(const PG8_LAS bf16x8*)(lds + PG8_SB(b, h) + boff + n * 2048 + k * 1024); } while (0)
; #define PG8_MMA(ai, bj, At, Bt) do { __builtin_amdgcn_s_setprio(1); _Pragma("unroll") for (int m = 0; m < 4; ++m) _Pragma("unroll") for (int n = 0; n < 2; ++n) _Pragma("unroll") for (int k = 0; k < 2; ++k) \
;         acc[ai][bj][m][n] = __builtin_amdgcn_mfma_f32_16x16x32_bf16(Bt[n][k], At[m][k], acc[ai][bj][m][n], 0, 0, 0); __builtin_amdgcn_s_setprio(0); } while (0)
; #define PG8_WAIT_V(n) asm volatile("s_waitcnt vmcnt(" #n ")" ::: "memory")
; #define PG8_WAIT_L(n) asm volatile("s_waitcnt lgkmcnt(" #n ")" ::: "memory")
; #define PG8_BAR __builtin_amdgcn_s_barrier()
; #define PG8_SCHED __builtin_amdgcn_sched_barrier(0)
; template <class Epi, class Sched, bool ALIGN_EPI = false, bool SP2 = false>
; __device__ __forceinline__ void gemm_phase(PG8_LAS unsigned char* lds, const Gemm g, const Sched& S, const Epi& E, const int tid_in) {
;     ...
;             PG8_LDB(B0, 1, 0); PG8_LDB(B1, 1, 1); PG8_SCHED; PG8_LDA(At, 1, 0); PG8_STAGE(PG8_SA(0, 1), a2 + hstepA, voffA);
;             PG8_WAIT_V(8); PG8_WAIT_L(0); PG8_BAR; PG8_MMA(0, 0, At, B0); PG8_MMA(0, 1, At, B1); PG8_BAR; PG8_SCHED;
;             PG8_LDA(At, 1, 1); PG8_STAGE(PG8_SB(1, 0), b3, voffB); PG8_STAGE(PG8_SB(1, 1), b3 + hstepB, voffB); PG8_STAGE(PG8_SA(1, 0), a3, voffA);
;             PG8_WAIT_V(8); PG8_WAIT_L(0); PG8_BAR; PG8_MMA(1, 0, At, B0); PG8_MMA(1, 1, At, B1); PG8_BAR; PG8_SCHED;
;     ...
;         if constexpr (ALIGN_EPI) { if (wr == 0) PG8_BAR; }
	s_add_i32 s62, 0, 0x18000
	s_add_i32 s63, 0, 0x1c000
	s_add_u32 s60, s60, 0x40000
	s_addc_u32 s61, s61, 0
	s_mov_b32 m0, s19
	s_nop 0
	global_load_lds_dwordx4 v190, s[60:61]
	s_mov_b32 m0, s20
	s_nop 0
	global_load_lds_dwordx4 v192, s[60:61]
	ds_read_b128 v[48:51], v249 offset:32768
	ds_read_b128 v[52:55], v249 offset:33792
	ds_read_b128 v[64:67], v249 offset:34816
	ds_read_b128 v[68:71], v249 offset:35840
	ds_read_b128 v[104:107], v249 offset:49152
	ds_read_b128 v[116:119], v249 offset:50176
	ds_read_b128 v[128:131], v249 offset:51200
	ds_read_b128 v[140:143], v249 offset:52224
	ds_read_b128 v[148:151], v225 offset:32768
	ds_read_b128 v[156:159], v225 offset:33792
	ds_read_b128 v[160:163], v225 offset:34816
	ds_read_b128 v[200:203], v225 offset:35840
	ds_read_b128 v[204:207], v225 offset:36864
	ds_read_b128 v[208:211], v225 offset:37888
	ds_read_b128 v[226:229], v225 offset:38912
	ds_read_b128 v[230:233], v225 offset:39936
	s_waitcnt vmcnt(8) lgkmcnt(0)
	s_barrier
	v_mfma_f32_16x16x32_bf16 v[168:171], v[48:51], v[148:151], v[168:171]
	v_mfma_f32_16x16x32_bf16 v[164:167], v[64:67], v[148:151], v[164:167]
	v_mfma_f32_16x16x32_bf16 v[136:139], v[48:51], v[160:163], v[136:139]
	v_mfma_f32_16x16x32_bf16 v[132:135], v[64:67], v[160:163], v[132:135]
	v_mfma_f32_16x16x32_bf16 v[112:115], v[48:51], v[204:207], v[112:115]
	v_mfma_f32_16x16x32_bf16 v[108:111], v[64:67], v[204:207], v[108:111]
	v_mfma_f32_16x16x32_bf16 v[92:95], v[48:51], v[226:229], v[92:95]
	v_mfma_f32_16x16x32_bf16 v[88:91], v[64:67], v[226:229], v[88:91]
	v_mfma_f32_16x16x32_bf16 v[168:171], v[52:55], v[156:159], v[168:171]
	v_mfma_f32_16x16x32_bf16 v[164:167], v[68:71], v[156:159], v[164:167]
	v_mfma_f32_16x16x32_bf16 v[136:139], v[52:55], v[200:203], v[136:139]
	v_mfma_f32_16x16x32_bf16 v[132:135], v[68:71], v[200:203], v[132:135]
	v_mfma_f32_16x16x32_bf16 v[112:115], v[52:55], v[208:211], v[112:115]
	v_mfma_f32_16x16x32_bf16 v[108:111], v[68:71], v[208:211], v[108:111]
	v_mfma_f32_16x16x32_bf16 v[92:95], v[52:55], v[230:233], v[92:95]
	v_mfma_f32_16x16x32_bf16 v[88:91], v[68:71], v[230:233], v[88:91]
	v_mfma_f32_16x16x32_bf16 v[152:155], v[104:107], v[148:151], v[152:155]
	v_mfma_f32_16x16x32_bf16 v[144:147], v[128:131], v[148:151], v[144:147]
	v_mfma_f32_16x16x32_bf16 v[124:127], v[104:107], v[160:163], v[124:127]
	v_mfma_f32_16x16x32_bf16 v[120:123], v[128:131], v[160:163], v[120:123]
	v_mfma_f32_16x16x32_bf16 v[100:103], v[104:107], v[204:207], v[100:103]
	v_mfma_f32_16x16x32_bf16 v[96:99], v[128:131], v[204:207], v[96:99]
	v_mfma_f32_16x16x32_bf16 v[84:87], v[104:107], v[226:229], v[84:87]
	v_mfma_f32_16x16x32_bf16 v[80:83], v[128:131], v[226:229], v[80:83]
	v_mfma_f32_16x16x32_bf16 v[152:155], v[116:119], v[156:159], v[152:155]
	v_mfma_f32_16x16x32_bf16 v[148:151], v[140:143], v[156:159], v[144:147]
	v_mfma_f32_16x16x32_bf16 v[124:127], v[116:119], v[200:203], v[124:127]
	v_mfma_f32_16x16x32_bf16 v[120:123], v[140:143], v[200:203], v[120:123]
	v_mfma_f32_16x16x32_bf16 v[100:103], v[116:119], v[208:211], v[100:103]
	v_mfma_f32_16x16x32_bf16 v[96:99], v[140:143], v[208:211], v[96:99]
	v_mfma_f32_16x16x32_bf16 v[84:87], v[116:119], v[230:233], v[84:87]
	v_mfma_f32_16x16x32_bf16 v[80:83], v[140:143], v[230:233], v[80:83]
	s_barrier
	s_add_i32 s60, s62, s16
	s_mov_b32 m0, s60
	s_add_u32 s100, s22, 0x80
	s_addc_u32 s101, s23, 0
	global_load_lds_dwordx4 v172, s[100:101]
	s_add_i32 m0, s60, 0x2000
	s_add_u32 s22, s22, 0x40080
	s_addc_u32 s23, s23, 0
	s_add_i32 s60, s63, s16
	global_load_lds_dwordx4 v194, s[100:101]
	s_mov_b32 m0, s60
	s_nop 0
	global_load_lds_dwordx4 v172, s[22:23]
	s_add_i32 m0, s60, 0x2000
	s_nop 0
	global_load_lds_dwordx4 v194, s[22:23]
	s_mov_b32 m0, s30
	s_nop 0
	global_load_lds_dwordx4 v190, vcc
	s_mov_b32 m0, s31
	s_nop 0
	global_load_lds_dwordx4 v192, vcc
	ds_read_b128 v[144:147], v225 offset:49152
	ds_read_b128 v[156:159], v225 offset:50176
	ds_read_b128 v[160:163], v225 offset:51200
	ds_read_b128 v[200:203], v225 offset:52224
	ds_read_b128 v[204:207], v225 offset:53248
	ds_read_b128 v[208:211], v225 offset:54272
	ds_read_b128 v[226:229], v225 offset:55296
	ds_read_b128 v[230:233], v225 offset:56320
	s_waitcnt vmcnt(8) lgkmcnt(0)
	s_barrier
	v_mfma_f32_16x16x32_bf16 v[76:79], v[48:51], v[144:147], v[76:79]
	v_mfma_f32_16x16x32_bf16 v[72:75], v[64:67], v[144:147], v[72:75]
	v_mfma_f32_16x16x32_bf16 v[60:63], v[48:51], v[160:163], v[60:63]
	v_mfma_f32_16x16x32_bf16 v[56:59], v[64:67], v[160:163], v[56:59]
	v_mfma_f32_16x16x32_bf16 v[28:31], v[48:51], v[204:207], v[28:31]
	v_mfma_f32_16x16x32_bf16 v[24:27], v[64:67], v[204:207], v[24:27]
	v_mfma_f32_16x16x32_bf16 v[12:15], v[48:51], v[226:229], v[12:15]
	v_mfma_f32_16x16x32_bf16 v[8:11], v[64:67], v[226:229], v[8:11]
	v_mfma_f32_16x16x32_bf16 v[76:79], v[52:55], v[156:159], v[76:79]
	v_mfma_f32_16x16x32_bf16 v[72:75], v[68:71], v[156:159], v[72:75]
	v_mfma_f32_16x16x32_bf16 v[60:63], v[52:55], v[200:203], v[60:63]
	v_mfma_f32_16x16x32_bf16 v[56:59], v[68:71], v[200:203], v[56:59]
	v_mfma_f32_16x16x32_bf16 v[28:31], v[52:55], v[208:211], v[28:31]
	v_mfma_f32_16x16x32_bf16 v[24:27], v[68:71], v[208:211], v[24:27]
	v_mfma_f32_16x16x32_bf16 v[12:15], v[52:55], v[230:233], v[12:15]
	v_mfma_f32_16x16x32_bf16 v[8:11], v[68:71], v[230:233], v[8:11]
	v_mfma_f32_16x16x32_bf16 v[32:35], v[104:107], v[144:147], v[32:35]
	v_mfma_f32_16x16x32_bf16 v[68:71], v[116:119], v[156:159], v[32:35]
	v_mfma_f32_16x16x32_bf16 v[32:35], v[128:131], v[144:147], v[36:39]
	v_mfma_f32_16x16x32_bf16 v[64:67], v[140:143], v[156:159], v[32:35]
	v_mfma_f32_16x16x32_bf16 v[32:35], v[104:107], v[160:163], v[44:47]
	v_mfma_f32_16x16x32_bf16 v[44:47], v[116:119], v[200:203], v[32:35]
	v_mfma_f32_16x16x32_bf16 v[32:35], v[128:131], v[160:163], v[40:43]
	v_mfma_f32_16x16x32_bf16 v[20:23], v[104:107], v[204:207], v[20:23]
	v_mfma_f32_16x16x32_bf16 v[16:19], v[128:131], v[204:207], v[16:19]
	v_mfma_f32_16x16x32_bf16 v[4:7], v[104:107], v[226:229], v[4:7]
	v_mfma_f32_16x16x32_bf16 v[0:3], v[128:131], v[226:229], v[0:3]
	v_mfma_f32_16x16x32_bf16 v[40:43], v[140:143], v[200:203], v[32:35]
	v_mfma_f32_16x16x32_bf16 v[20:23], v[116:119], v[208:211], v[20:23]
	v_mfma_f32_16x16x32_bf16 v[16:19], v[140:143], v[208:211], v[16:19]
	v_mfma_f32_16x16x32_bf16 v[4:7], v[116:119], v[230:233], v[4:7]
	v_mfma_f32_16x16x32_bf16 v[0:3], v[140:143], v[230:233], v[0:3]
	s_barrier
	s_add_i32 s53, s53, 2
	s_add_u32 s58, s58, 0x100
	s_addc_u32 s59, s59, 0
	s_add_u32 s35, s35, 0x100
	s_addc_u32 s51, s51, 0
	s_cmp_gt_u32 s53, 13
	s_cbranch_scc0 .LBB0_1960
	s_and_b64 vcc, exec, s[48:49]
	s_cbranch_vccz .LBB0_1963
	s_barrier

;     __device__ __forceinline__ void a_ready(const Unit& u) const { wait_panel(cnt, u.pm, need, tmo, wave); }
;     __device__ __forceinline__ void a_ready(const Unit& u) const { wait_panel(cnt, u.pm, need, tmo, wave); }
; #define PG8_STAGE(bufoff, gbase, voff) do { _Pragma("unroll") for (int _i = 0; _i < 2; ++_i) \
;         __builtin_amdgcn_global_load_lds((const unsigned*)((const char*)(gbase) + (voff)[_i]), (PG8_LAS unsigned*)(lds + (bufoff) + ldsw + _i * 8192), 16, 0, 0); } while (0)
; #define PG8_LDA(dst, b, h) do { _Pragma("unroll") for (int m = 0; m < 4; ++m) _Pragma("unroll") for (int k = 0; k < 2; ++k) dst[m][k] = *(const PG8_LAS bf16x8*)(lds + PG8_SA(b, h) + aoff + m * 2048 + k * 1024); } while (0)
; #define PG8_LDB(dst, b, h) do { _Pragma("unroll") for (int n = 0; n < 2; ++n) _Pragma("unroll") for (int k = 0; k < 2; ++k) dst[n][k] = *(const PG8_LAS bf16x8*)(lds + PG8_SB(b, h) + boff + n * 2048 + k * 1024); } while (0)
; #define PG8_WAIT_V(n) asm volatile("s_waitcnt vmcnt(" #n ")" ::: "memory")
; #define PG8_WAIT_L(n) asm volatile("s_waitcnt lgkmcnt(" #n ")" ::: "memory")
; #define PG8_BAR __builtin_amdgcn_s_barrier()
; #define PG8_SCHED __builtin_amdgcn_sched_barrier(0)
; template <class Epi, class Sched, bool ALIGN_EPI = false, bool SP2 = false>
; __device__ __forceinline__ void gemm_phase(PG8_LAS unsigned char* lds, const Gemm g, const Sched& S, const Epi& E, const int tid_in) {
;     ...
;             const bool last = (t == nt - 2);
;             const char* a1 = cA + (size_t)(t + 1) * kstep;
;             const char* a2 = last ? nA : cA + (size_t)(t + 2) * kstep; const char* b2 = last ? nB : cB + (size_t)(t + 2) * kstep;
;             const char* a3 = a2 + kstep; const char* b3 = b2 + kstep;
;             if (last && has_next) S.a_ready(nxt);
;             if constexpr (SP2) {
;             PG8_LDB(B0, 0, 0); PG8_LDB(B1, 0, 1); PG8_SCHED; PG8_LDA(At, 0, 0); PG8_STAGE(PG8_SA(1, 1), a1 + hstepA, voffA);
;             PG8_WAIT_V(8); PG8_WAIT_L(0); PG8_BAR; PG8_MMA(0, 0, At, B0); PG8_MMA(0, 1, At, B1); PG8_BAR; PG8_SCHED;
;             PG8_LDA(At, 0, 1); PG8_STAGE(PG8_SB(0, 0), b2, voffB); PG8_STAGE(PG8_SB(0, 1), b2 + hstepB, voffB); PG8_STAGE(PG8_SA(0, 0), a2, voffA);
;             PG8_WAIT_V(8); PG8_WAIT_L(0); PG8_BAR; PG8_MMA(1, 0, At, B0); PG8_MMA(1, 1, At, B1); PG8_BAR; PG8_SCHED;
.LBB0_2041:
	s_add_u32 s22, s58, 0xfff80080
	s_addc_u32 s23, s59, -1
	s_add_i32 s65, 0, 0x10000
	s_cmp_eq_u32 s64, 28
	s_cselect_b32 s61, s38, s23
	s_cselect_b32 s60, s51, s22
	s_cselect_b32 s23, s49, s63
	s_cselect_b32 s22, s57, s62
	s_add_i32 s68, 0, 0x14000
	s_add_i32 m0, s28, 0xc000
	s_nop 0
	global_load_lds_dwordx4 v170, s[58:59]
	s_add_i32 m0, s28, 0xe000
	s_nop 0
	global_load_lds_dwordx4 v190, s[58:59]
	ds_read_b128 v[104:107], v249
	ds_read_b128 v[108:111], v249 offset:1024
	ds_read_b128 v[112:115], v249 offset:2048
	ds_read_b128 v[116:119], v249 offset:3072
	ds_read_b128 v[144:147], v249 offset:16384
	ds_read_b128 v[148:151], v249 offset:17408
	ds_read_b128 v[152:155], v249 offset:18432
	ds_read_b128 v[156:159], v249 offset:19456
	ds_read_b128 v[160:163], v204
	ds_read_b128 v[192:195], v204 offset:1024
	ds_read_b128 v[196:199], v204 offset:2048
	ds_read_b128 v[206:209], v204 offset:3072
	ds_read_b128 v[210:213], v204 offset:4096
	ds_read_b128 v[224:227], v204 offset:5120
	ds_read_b128 v[228:231], v204 offset:6144
	ds_read_b128 v[232:235], v204 offset:7168
	s_waitcnt vmcnt(8) lgkmcnt(0)
	s_barrier
	v_mfma_f32_16x16x32_bf16 v[140:143], v[104:107], v[160:163], v[140:143]
	v_mfma_f32_16x16x32_bf16 v[136:139], v[112:115], v[160:163], v[136:139]
	v_mfma_f32_16x16x32_bf16 v[124:127], v[104:107], v[196:199], v[124:127]
	v_mfma_f32_16x16x32_bf16 v[120:123], v[112:115], v[196:199], v[120:123]
	v_mfma_f32_16x16x32_bf16 v[92:95], v[104:107], v[210:213], v[92:95]
	v_mfma_f32_16x16x32_bf16 v[88:91], v[112:115], v[210:213], v[88:91]
	v_mfma_f32_16x16x32_bf16 v[76:79], v[104:107], v[228:231], v[76:79]
	v_mfma_f32_16x16x32_bf16 v[72:75], v[112:115], v[228:231], v[72:75]
	v_mfma_f32_16x16x32_bf16 v[140:143], v[108:111], v[192:195], v[140:143]
	v_mfma_f32_16x16x32_bf16 v[136:139], v[116:119], v[192:195], v[136:139]
	v_mfma_f32_16x16x32_bf16 v[124:127], v[108:111], v[206:209], v[124:127]
	v_mfma_f32_16x16x32_bf16 v[120:123], v[116:119], v[206:209], v[120:123]
	v_mfma_f32_16x16x32_bf16 v[92:95], v[108:111], v[224:227], v[92:95]
	v_mfma_f32_16x16x32_bf16 v[88:91], v[116:119], v[224:227], v[88:91]
	v_mfma_f32_16x16x32_bf16 v[76:79], v[108:111], v[232:235], v[76:79]
	v_mfma_f32_16x16x32_bf16 v[72:75], v[116:119], v[232:235], v[72:75]
	v_mfma_f32_16x16x32_bf16 v[132:135], v[144:147], v[160:163], v[132:135]
	v_mfma_f32_16x16x32_bf16 v[128:131], v[152:155], v[160:163], v[128:131]
	v_mfma_f32_16x16x32_bf16 v[100:103], v[144:147], v[196:199], v[100:103]
	v_mfma_f32_16x16x32_bf16 v[96:99], v[152:155], v[196:199], v[96:99]
	v_mfma_f32_16x16x32_bf16 v[84:87], v[144:147], v[210:213], v[84:87]
	v_mfma_f32_16x16x32_bf16 v[80:83], v[152:155], v[210:213], v[80:83]
	v_mfma_f32_16x16x32_bf16 v[68:71], v[144:147], v[228:231], v[68:71]
	v_mfma_f32_16x16x32_bf16 v[64:67], v[152:155], v[228:231], v[64:67]
	v_mfma_f32_16x16x32_bf16 v[132:135], v[148:151], v[192:195], v[132:135]
	v_mfma_f32_16x16x32_bf16 v[128:131], v[156:159], v[192:195], v[128:131]
	v_mfma_f32_16x16x32_bf16 v[100:103], v[148:151], v[206:209], v[100:103]
	v_mfma_f32_16x16x32_bf16 v[96:99], v[156:159], v[206:209], v[96:99]
	v_mfma_f32_16x16x32_bf16 v[84:87], v[148:151], v[224:227], v[84:87]
	v_mfma_f32_16x16x32_bf16 v[80:83], v[156:159], v[224:227], v[80:83]
	v_mfma_f32_16x16x32_bf16 v[68:71], v[148:151], v[232:235], v[68:71]
	v_mfma_f32_16x16x32_bf16 v[64:67], v[156:159], v[232:235], v[64:67]
	s_barrier
	s_add_i32 s65, s65, s21
	s_mov_b32 m0, s65
	s_nop 0
	global_load_lds_dwordx4 v172, s[22:23]
	s_add_i32 m0, s65, 0x2000
	s_add_u32 s66, s22, 0x80000
	s_addc_u32 s67, s23, 0
	s_add_i32 s65, s68, s21
	global_load_lds_dwordx4 v168, s[22:23]
	s_mov_b32 m0, s65
	s_nop 0
	global_load_lds_dwordx4 v172, s[66:67]
	s_add_i32 m0, s65, 0x2000
	s_nop 0
	global_load_lds_dwordx4 v168, s[66:67]
	s_add_u32 vcc_lo, s60, 0x80
	s_addc_u32 vcc_hi, s61, 0
	s_mov_b32 m0, s28
	s_nop 0
	global_load_lds_dwordx4 v164, s[60:61]
	s_mov_b32 m0, s29
	s_nop 0
	global_load_lds_dwordx4 v166, s[60:61]
	ds_read_b128 v[160:163], v204 offset:16384
	ds_read_b128 v[192:195], v204 offset:17408
	ds_read_b128 v[196:199], v204 offset:18432
	ds_read_b128 v[206:209], v204 offset:19456
	ds_read_b128 v[210:213], v204 offset:20480
	ds_read_b128 v[224:227], v204 offset:21504
	ds_read_b128 v[228:231], v204 offset:22528
	ds_read_b128 v[232:235], v204 offset:23552
	s_waitcnt vmcnt(8) lgkmcnt(0)
	s_barrier
	v_mfma_f32_16x16x32_bf16 v[60:63], v[104:107], v[160:163], v[60:63]
	v_mfma_f32_16x16x32_bf16 v[56:59], v[112:115], v[160:163], v[56:59]
	v_mfma_f32_16x16x32_bf16 v[44:47], v[104:107], v[196:199], v[44:47]
	v_mfma_f32_16x16x32_bf16 v[40:43], v[112:115], v[196:199], v[40:43]
	v_mfma_f32_16x16x32_bf16 v[28:31], v[104:107], v[210:213], v[28:31]
	v_mfma_f32_16x16x32_bf16 v[24:27], v[112:115], v[210:213], v[24:27]
	v_mfma_f32_16x16x32_bf16 v[12:15], v[104:107], v[228:231], v[12:15]
	v_mfma_f32_16x16x32_bf16 v[8:11], v[112:115], v[228:231], v[8:11]
	v_mfma_f32_16x16x32_bf16 v[60:63], v[108:111], v[192:195], v[60:63]
	v_mfma_f32_16x16x32_bf16 v[56:59], v[116:119], v[192:195], v[56:59]
	v_mfma_f32_16x16x32_bf16 v[44:47], v[108:111], v[206:209], v[44:47]
	v_mfma_f32_16x16x32_bf16 v[40:43], v[116:119], v[206:209], v[40:43]
	v_mfma_f32_16x16x32_bf16 v[28:31], v[108:111], v[224:227], v[28:31]
	v_mfma_f32_16x16x32_bf16 v[24:27], v[116:119], v[224:227], v[24:27]
	v_mfma_f32_16x16x32_bf16 v[12:15], v[108:111], v[232:235], v[12:15]
	v_mfma_f32_16x16x32_bf16 v[8:11], v[116:119], v[232:235], v[8:11]
	v_mfma_f32_16x16x32_bf16 v[52:55], v[144:147], v[160:163], v[52:55]
	v_mfma_f32_16x16x32_bf16 v[48:51], v[152:155], v[160:163], v[48:51]
	v_mfma_f32_16x16x32_bf16 v[36:39], v[144:147], v[196:199], v[36:39]
	v_mfma_f32_16x16x32_bf16 v[32:35], v[152:155], v[196:199], v[32:35]
	v_mfma_f32_16x16x32_bf16 v[20:23], v[144:147], v[210:213], v[20:23]
	v_mfma_f32_16x16x32_bf16 v[16:19], v[152:155], v[210:213], v[16:19]
	v_mfma_f32_16x16x32_bf16 v[4:7], v[144:147], v[228:231], v[4:7]
	v_mfma_f32_16x16x32_bf16 v[0:3], v[152:155], v[228:231], v[0:3]
	v_mfma_f32_16x16x32_bf16 v[52:55], v[148:151], v[192:195], v[52:55]
	v_mfma_f32_16x16x32_bf16 v[48:51], v[156:159], v[192:195], v[48:51]
	v_mfma_f32_16x16x32_bf16 v[36:39], v[148:151], v[206:209], v[36:39]
	v_mfma_f32_16x16x32_bf16 v[32:35], v[156:159], v[206:209], v[32:35]
	v_mfma_f32_16x16x32_bf16 v[20:23], v[148:151], v[224:227], v[20:23]
	v_mfma_f32_16x16x32_bf16 v[16:19], v[156:159], v[224:227], v[16:19]
	v_mfma_f32_16x16x32_bf16 v[4:7], v[148:151], v[232:235], v[4:7]
	v_mfma_f32_16x16x32_bf16 v[0:3], v[156:159], v[232:235], v[0:3]
	s_barrier
; #define PG8_STAGE(bufoff, gbase, voff) do { _Pragma("unroll") for (int _i = 0; _i < 2; ++_i) \
;         __builtin_amdgcn_global_load_lds((const unsigned*)((const char*)(gbase) + (voff)[_i]), (PG8_LAS unsigned*)(lds + (bufoff) + ldsw + _i * 8192), 16, 0, 0); } while (0)
; #define PG8_LDA(dst, b, h) do { _Pragma("unroll") for (int m = 0; m < 4; ++m) _Pragma("unroll") for (int k = 0; k < 2; ++k) dst[m][k] = *(const PG8_LAS bf16x8*)(lds + PG8_SA(b, h) + aoff + m * 2048 + k * 1024); } while (0)
; #define PG8_LDB(dst, b, h) do { _Pragma("unroll") for (int n = 0; n < 2; ++n) _Pragma("unroll") for (int k = 0; k < 2; ++k) dst[n][k] = *(const PG8_LAS bf16x8*)(lds + PG8_SB(b, h) + boff + n * 2048 + k * 1024); } while (0)
; #define PG8_MMA(ai, bj, At, Bt) do { __builtin_amdgcn_s_setprio(1); _Pragma("unroll") for (int m = 0; m < 4; ++m) _Pragma("unroll") for (int n = 0; n < 2; ++n) _Pragma("unroll") for (int k = 0; k < 2; ++k) \
;         acc[ai][bj][m][n] = __builtin_amdgcn_mfma_f32_16x16x32_bf16(Bt[n][k], At[m][k], acc[ai][bj][m][n], 0, 0, 0); __builtin_amdgcn_s_setprio(0); } while (0)
; #define PG8_WAIT_V(n) asm volatile("s_waitcnt vmcnt(" #n ")" ::: "memory")
; #define PG8_WAIT_L(n) asm volatile("s_waitcnt lgkmcnt(" #n ")" ::: "memory")
; #define PG8_BAR __builtin_amdgcn_s_barrier()
; #define PG8_SCHED __builtin_amdgcn_sched_barrier(0)
; template <class Epi, class Sched, bool ALIGN_EPI = false, bool SP2 = false>
; __device__ __forceinline__ void gemm_phase(PG8_LAS unsigned char* lds, const Gemm g, const Sched& S, const Epi& E, const int tid_in) {
;     ...
;             PG8_LDB(B0, 1, 0); PG8_LDB(B1, 1, 1); PG8_SCHED; PG8_LDA(At, 1, 0); PG8_STAGE(PG8_SA(0, 1), a2 + hstepA, voffA);
;             PG8_WAIT_V(8); PG8_WAIT_L(0); PG8_BAR; PG8_MMA(0, 0, At, B0); PG8_MMA(0, 1, At, B1); PG8_BAR; PG8_SCHED;
;             PG8_LDA(At, 1, 1); PG8_STAGE(PG8_SB(1, 0), b3, voffB); PG8_STAGE(PG8_SB(1, 1), b3 + hstepB, voffB); PG8_STAGE(PG8_SA(1, 0), a3, voffA);
;             PG8_WAIT_V(8); PG8_WAIT_L(0); PG8_BAR; PG8_MMA(1, 0, At, B0); PG8_MMA(1, 1, At, B1); PG8_BAR; PG8_SCHED;
;     ...
;         if constexpr (ALIGN_EPI) { if (wr == 0) PG8_BAR; }
	s_add_i32 s65, 0, 0x18000
	s_add_i32 s66, 0, 0x1c000
	s_add_u32 s60, s60, 0x80000
	s_addc_u32 s61, s61, 0
	s_mov_b32 m0, s30
	s_nop 0
	global_load_lds_dwordx4 v164, s[60:61]
	s_mov_b32 m0, s6
	s_nop 0
	global_load_lds_dwordx4 v166, s[60:61]
	ds_read_b128 v[104:107], v249 offset:32768
	ds_read_b128 v[108:111], v249 offset:33792
	ds_read_b128 v[112:115], v249 offset:34816
	ds_read_b128 v[116:119], v249 offset:35840
	ds_read_b128 v[144:147], v249 offset:49152
	ds_read_b128 v[148:151], v249 offset:50176
	ds_read_b128 v[152:155], v249 offset:51200
	ds_read_b128 v[156:159], v249 offset:52224
	ds_read_b128 v[160:163], v204 offset:32768
	ds_read_b128 v[192:195], v204 offset:33792
	ds_read_b128 v[196:199], v204 offset:34816
	ds_read_b128 v[206:209], v204 offset:35840
	ds_read_b128 v[210:213], v204 offset:36864
	ds_read_b128 v[224:227], v204 offset:37888
	ds_read_b128 v[228:231], v204 offset:38912
	ds_read_b128 v[232:235], v204 offset:39936
	s_waitcnt vmcnt(8) lgkmcnt(0)
	s_barrier
	v_mfma_f32_16x16x32_bf16 v[140:143], v[104:107], v[160:163], v[140:143]
	v_mfma_f32_16x16x32_bf16 v[136:139], v[112:115], v[160:163], v[136:139]
	v_mfma_f32_16x16x32_bf16 v[124:127], v[104:107], v[196:199], v[124:127]
	v_mfma_f32_16x16x32_bf16 v[120:123], v[112:115], v[196:199], v[120:123]
	v_mfma_f32_16x16x32_bf16 v[92:95], v[104:107], v[210:213], v[92:95]
	v_mfma_f32_16x16x32_bf16 v[88:91], v[112:115], v[210:213], v[88:91]
	v_mfma_f32_16x16x32_bf16 v[76:79], v[104:107], v[228:231], v[76:79]
	v_mfma_f32_16x16x32_bf16 v[72:75], v[112:115], v[228:231], v[72:75]
	v_mfma_f32_16x16x32_bf16 v[140:143], v[108:111], v[192:195], v[140:143]
	v_mfma_f32_16x16x32_bf16 v[136:139], v[116:119], v[192:195], v[136:139]
	v_mfma_f32_16x16x32_bf16 v[124:127], v[108:111], v[206:209], v[124:127]
	v_mfma_f32_16x16x32_bf16 v[120:123], v[116:119], v[206:209], v[120:123]
	v_mfma_f32_16x16x32_bf16 v[92:95], v[108:111], v[224:227], v[92:95]
	v_mfma_f32_16x16x32_bf16 v[88:91], v[116:119], v[224:227], v[88:91]
	v_mfma_f32_16x16x32_bf16 v[76:79], v[108:111], v[232:235], v[76:79]
	v_mfma_f32_16x16x32_bf16 v[72:75], v[116:119], v[232:235], v[72:75]
	v_mfma_f32_16x16x32_bf16 v[132:135], v[144:147], v[160:163], v[132:135]
	v_mfma_f32_16x16x32_bf16 v[128:131], v[152:155], v[160:163], v[128:131]
	v_mfma_f32_16x16x32_bf16 v[100:103], v[144:147], v[196:199], v[100:103]
	v_mfma_f32_16x16x32_bf16 v[96:99], v[152:155], v[196:199], v[96:99]
	v_mfma_f32_16x16x32_bf16 v[84:87], v[144:147], v[210:213], v[84:87]
	v_mfma_f32_16x16x32_bf16 v[80:83], v[152:155], v[210:213], v[80:83]
	v_mfma_f32_16x16x32_bf16 v[68:71], v[144:147], v[228:231], v[68:71]
	v_mfma_f32_16x16x32_bf16 v[64:67], v[152:155], v[228:231], v[64:67]
	v_mfma_f32_16x16x32_bf16 v[132:135], v[148:151], v[192:195], v[132:135]
	v_mfma_f32_16x16x32_bf16 v[128:131], v[156:159], v[192:195], v[128:131]
	v_mfma_f32_16x16x32_bf16 v[100:103], v[148:151], v[206:209], v[100:103]
	v_mfma_f32_16x16x32_bf16 v[96:99], v[156:159], v[206:209], v[96:99]
	v_mfma_f32_16x16x32_bf16 v[84:87], v[148:151], v[224:227], v[84:87]
	v_mfma_f32_16x16x32_bf16 v[80:83], v[156:159], v[224:227], v[80:83]
	v_mfma_f32_16x16x32_bf16 v[68:71], v[148:151], v[232:235], v[68:71]
	v_mfma_f32_16x16x32_bf16 v[64:67], v[156:159], v[232:235], v[64:67]
	s_barrier
	s_add_i32 s60, s65, s21
	s_mov_b32 m0, s60
	s_add_u32 s100, s22, 0x80
	s_addc_u32 s101, s23, 0
	global_load_lds_dwordx4 v172, s[100:101]
	s_add_i32 m0, s60, 0x2000
	s_add_u32 s22, s22, 0x80080
	s_addc_u32 s23, s23, 0
	s_add_i32 s60, s66, s21
	global_load_lds_dwordx4 v168, s[100:101]
	s_mov_b32 m0, s60
	s_nop 0
	global_load_lds_dwordx4 v172, s[22:23]
	s_add_i32 m0, s60, 0x2000
	s_nop 0
	global_load_lds_dwordx4 v168, s[22:23]
	s_mov_b32 m0, s33
	s_nop 0
	global_load_lds_dwordx4 v164, vcc
	s_mov_b32 m0, s34
	s_nop 0
	global_load_lds_dwordx4 v166, vcc
	ds_read_b128 v[160:163], v204 offset:49152
	ds_read_b128 v[192:195], v204 offset:50176
	ds_read_b128 v[196:199], v204 offset:51200
	ds_read_b128 v[206:209], v204 offset:52224
	ds_read_b128 v[210:213], v204 offset:53248
	ds_read_b128 v[224:227], v204 offset:54272
	ds_read_b128 v[228:231], v204 offset:55296
	ds_read_b128 v[232:235], v204 offset:56320
	s_waitcnt vmcnt(8) lgkmcnt(0)
	s_barrier
	v_mfma_f32_16x16x32_bf16 v[60:63], v[104:107], v[160:163], v[60:63]
	v_mfma_f32_16x16x32_bf16 v[56:59], v[112:115], v[160:163], v[56:59]
	v_mfma_f32_16x16x32_bf16 v[44:47], v[104:107], v[196:199], v[44:47]
	v_mfma_f32_16x16x32_bf16 v[40:43], v[112:115], v[196:199], v[40:43]
	v_mfma_f32_16x16x32_bf16 v[28:31], v[104:107], v[210:213], v[28:31]
	v_mfma_f32_16x16x32_bf16 v[24:27], v[112:115], v[210:213], v[24:27]
	v_mfma_f32_16x16x32_bf16 v[12:15], v[104:107], v[228:231], v[12:15]
	v_mfma_f32_16x16x32_bf16 v[8:11], v[112:115], v[228:231], v[8:11]
	v_mfma_f32_16x16x32_bf16 v[60:63], v[108:111], v[192:195], v[60:63]
	v_mfma_f32_16x16x32_bf16 v[56:59], v[116:119], v[192:195], v[56:59]
	v_mfma_f32_16x16x32_bf16 v[44:47], v[108:111], v[206:209], v[44:47]
	v_mfma_f32_16x16x32_bf16 v[40:43], v[116:119], v[206:209], v[40:43]
	v_mfma_f32_16x16x32_bf16 v[28:31], v[108:111], v[224:227], v[28:31]
	v_mfma_f32_16x16x32_bf16 v[24:27], v[116:119], v[224:227], v[24:27]
	v_mfma_f32_16x16x32_bf16 v[12:15], v[108:111], v[232:235], v[12:15]
	v_mfma_f32_16x16x32_bf16 v[8:11], v[116:119], v[232:235], v[8:11]
	v_mfma_f32_16x16x32_bf16 v[52:55], v[144:147], v[160:163], v[52:55]
	v_mfma_f32_16x16x32_bf16 v[48:51], v[152:155], v[160:163], v[48:51]
	v_mfma_f32_16x16x32_bf16 v[36:39], v[144:147], v[196:199], v[36:39]
	v_mfma_f32_16x16x32_bf16 v[32:35], v[152:155], v[196:199], v[32:35]
	v_mfma_f32_16x16x32_bf16 v[20:23], v[144:147], v[210:213], v[20:23]
	v_mfma_f32_16x16x32_bf16 v[16:19], v[152:155], v[210:213], v[16:19]
	v_mfma_f32_16x16x32_bf16 v[4:7], v[144:147], v[228:231], v[4:7]
	v_mfma_f32_16x16x32_bf16 v[0:3], v[152:155], v[228:231], v[0:3]
	v_mfma_f32_16x16x32_bf16 v[52:55], v[148:151], v[192:195], v[52:55]
	v_mfma_f32_16x16x32_bf16 v[48:51], v[156:159], v[192:195], v[48:51]
	v_mfma_f32_16x16x32_bf16 v[36:39], v[148:151], v[206:209], v[36:39]
	v_mfma_f32_16x16x32_bf16 v[32:35], v[156:159], v[206:209], v[32:35]
	v_mfma_f32_16x16x32_bf16 v[20:23], v[148:151], v[224:227], v[20:23]
	v_mfma_f32_16x16x32_bf16 v[16:19], v[156:159], v[224:227], v[16:19]
	v_mfma_f32_16x16x32_bf16 v[4:7], v[148:151], v[232:235], v[4:7]
	v_mfma_f32_16x16x32_bf16 v[0:3], v[156:159], v[232:235], v[0:3]
	s_barrier
	s_add_i32 s64, s64, 2
	s_add_u32 s58, s58, 0x100
	s_addc_u32 s59, s59, 0
	s_add_u32 s62, s62, 0x100
	s_addc_u32 s63, s63, 0
	s_cmp_gt_u32 s64, 29
	s_cbranch_scc0 .LBB0_2041
	s_and_b64 vcc, exec, s[46:47]
	s_cbranch_vccz .LBB0_2044
	s_barrier

;     __device__ __forceinline__ void a_ready(const Unit& u) const { wait_panel(cnt, u.pm, need, tmo, wave); }
;     __device__ __forceinline__ void a_ready(const Unit& u) const { wait_panel(cnt, u.pm, need, tmo, wave); }
; #define PG8_STAGE(bufoff, gbase, voff) do { _Pragma("unroll") for (int _i = 0; _i < 2; ++_i) \
;         __builtin_amdgcn_global_load_lds((const unsigned*)((const char*)(gbase) + (voff)[_i]), (PG8_LAS unsigned*)(lds + (bufoff) + ldsw + _i * 8192), 16, 0, 0); } while (0)
; #define PG8_LDA(dst, b, h) do { _Pragma("unroll") for (int m = 0; m < 4; ++m) _Pragma("unroll") for (int k = 0; k < 2; ++k) dst[m][k] = *(const PG8_LAS bf16x8*)(lds + PG8_SA(b, h) + aoff + m * 2048 + k * 1024); } while (0)
; #define PG8_LDB(dst, b, h) do { _Pragma("unroll") for (int n = 0; n < 2; ++n) _Pragma("unroll") for (int k = 0; k < 2; ++k) dst[n][k] = *(const PG8_LAS bf16x8*)(lds + PG8_SB(b, h) + boff + n * 2048 + k * 1024); } while (0)
; #define PG8_WAIT_V(n) asm volatile("s_waitcnt vmcnt(" #n ")" ::: "memory")
; #define PG8_WAIT_L(n) asm volatile("s_waitcnt lgkmcnt(" #n ")" ::: "memory")
; #define PG8_BAR __builtin_amdgcn_s_barrier()
; #define PG8_SCHED __builtin_amdgcn_sched_barrier(0)
; template <class Epi, class Sched, bool ALIGN_EPI = false, bool SP2 = false>
; __device__ __forceinline__ void gemm_phase(PG8_LAS unsigned char* lds, const Gemm g, const Sched& S, const Epi& E, const int tid_in) {
;     ...
;             const bool last = (t == nt - 2);
;             const char* a1 = cA + (size_t)(t + 1) * kstep;
;             const char* a2 = last ? nA : cA + (size_t)(t + 2) * kstep; const char* b2 = last ? nB : cB + (size_t)(t + 2) * kstep;
;             const char* a3 = a2 + kstep; const char* b3 = b2 + kstep;
;             if (last && has_next) S.a_ready(nxt);
;             if constexpr (SP2) {
;             PG8_LDB(B0, 0, 0); PG8_LDB(B1, 0, 1); PG8_SCHED; PG8_LDA(At, 0, 0); PG8_STAGE(PG8_SA(1, 1), a1 + hstepA, voffA);
;             PG8_WAIT_V(8); PG8_WAIT_L(0); PG8_BAR; PG8_MMA(0, 0, At, B0); PG8_MMA(0, 1, At, B1); PG8_BAR; PG8_SCHED;
;             PG8_LDA(At, 0, 1); PG8_STAGE(PG8_SB(0, 0), b2, voffB); PG8_STAGE(PG8_SB(0, 1), b2 + hstepB, voffB); PG8_STAGE(PG8_SA(0, 0), a2, voffA);
;             PG8_WAIT_V(8); PG8_WAIT_L(0); PG8_BAR; PG8_MMA(1, 0, At, B0); PG8_MMA(1, 1, At, B1); PG8_BAR; PG8_SCHED;
.LBB0_2059:
	s_add_u32 s22, s62, 0xfff80080
	s_addc_u32 s23, s63, -1
	s_add_i32 s55, 0, 0x10000
	s_cmp_eq_u32 s53, 4
	s_cselect_b32 s65, s61, s23
	s_cselect_b32 s64, s60, s22
	s_cselect_b32 s23, s59, s38
	s_cselect_b32 s22, s58, s35
	s_add_i32 s57, 0, 0x14000
	s_add_i32 m0, s12, 0xc000
	s_nop 0
	global_load_lds_dwordx4 v148, s[62:63]
	s_add_i32 m0, s12, 0xe000
	s_nop 0
	global_load_lds_dwordx4 v146, s[62:63]
	ds_read_b128 v[64:67], v249
	ds_read_b128 v[68:71], v249 offset:1024
	ds_read_b128 v[72:75], v249 offset:2048
	ds_read_b128 v[76:79], v249 offset:3072
	ds_read_b128 v[80:83], v249 offset:16384
	ds_read_b128 v[84:87], v249 offset:17408
	ds_read_b128 v[88:91], v249 offset:18432
	ds_read_b128 v[92:95], v249 offset:19456
	ds_read_b128 v[96:99], v154
	ds_read_b128 v[100:103], v154 offset:1024
	ds_read_b128 v[104:107], v154 offset:2048
	ds_read_b128 v[108:111], v154 offset:3072
	ds_read_b128 v[112:115], v154 offset:4096
	ds_read_b128 v[116:119], v154 offset:5120
	ds_read_b128 v[120:123], v154 offset:6144
	ds_read_b128 v[124:127], v154 offset:7168
	s_waitcnt vmcnt(8) lgkmcnt(0)
	s_barrier
	v_mfma_f32_16x16x32_bf16 v[60:63], v[64:67], v[96:99], v[60:63]
	v_mfma_f32_16x16x32_bf16 v[56:59], v[72:75], v[96:99], v[56:59]
	v_mfma_f32_16x16x32_bf16 v[48:51], v[64:67], v[104:107], v[48:51]
	v_mfma_f32_16x16x32_bf16 v[40:43], v[72:75], v[104:107], v[40:43]
	v_mfma_f32_16x16x32_bf16 v[32:35], v[64:67], v[112:115], v[32:35]
	v_mfma_f32_16x16x32_bf16 v[24:27], v[72:75], v[112:115], v[24:27]
	v_mfma_f32_16x16x32_bf16 v[16:19], v[64:67], v[120:123], v[16:19]
	v_mfma_f32_16x16x32_bf16 v[8:11], v[72:75], v[120:123], v[8:11]
	v_mfma_f32_16x16x32_bf16 v[60:63], v[68:71], v[100:103], v[60:63]
	v_mfma_f32_16x16x32_bf16 v[56:59], v[76:79], v[100:103], v[56:59]
	v_mfma_f32_16x16x32_bf16 v[48:51], v[68:71], v[108:111], v[48:51]
	v_mfma_f32_16x16x32_bf16 v[40:43], v[76:79], v[108:111], v[40:43]
	v_mfma_f32_16x16x32_bf16 v[32:35], v[68:71], v[116:119], v[32:35]
	v_mfma_f32_16x16x32_bf16 v[24:27], v[76:79], v[116:119], v[24:27]
	v_mfma_f32_16x16x32_bf16 v[16:19], v[68:71], v[124:127], v[16:19]
	v_mfma_f32_16x16x32_bf16 v[8:11], v[76:79], v[124:127], v[8:11]
	v_mfma_f32_16x16x32_bf16 v[52:55], v[80:83], v[96:99], v[52:55]
	v_mfma_f32_16x16x32_bf16 v[44:47], v[88:91], v[96:99], v[44:47]
	v_mfma_f32_16x16x32_bf16 v[36:39], v[80:83], v[104:107], v[36:39]
	v_mfma_f32_16x16x32_bf16 v[28:31], v[88:91], v[104:107], v[28:31]
	v_mfma_f32_16x16x32_bf16 v[20:23], v[80:83], v[112:115], v[20:23]
	v_mfma_f32_16x16x32_bf16 v[12:15], v[88:91], v[112:115], v[12:15]
	v_mfma_f32_16x16x32_bf16 v[4:7], v[80:83], v[120:123], v[4:7]
	v_mfma_f32_16x16x32_bf16 v[0:3], v[88:91], v[120:123], v[0:3]
	v_mfma_f32_16x16x32_bf16 v[52:55], v[84:87], v[100:103], v[52:55]
	v_mfma_f32_16x16x32_bf16 v[44:47], v[92:95], v[100:103], v[44:47]
	v_mfma_f32_16x16x32_bf16 v[36:39], v[84:87], v[108:111], v[36:39]
	v_mfma_f32_16x16x32_bf16 v[28:31], v[92:95], v[108:111], v[28:31]
	v_mfma_f32_16x16x32_bf16 v[20:23], v[84:87], v[116:119], v[20:23]
	v_mfma_f32_16x16x32_bf16 v[12:15], v[92:95], v[116:119], v[12:15]
	v_mfma_f32_16x16x32_bf16 v[4:7], v[84:87], v[124:127], v[4:7]
	v_mfma_f32_16x16x32_bf16 v[0:3], v[92:95], v[124:127], v[0:3]
	s_barrier
	s_add_i32 s55, s55, s6
	s_mov_b32 m0, s55
	s_nop 0
	global_load_lds_dwordx4 v172, s[22:23]
	s_add_i32 m0, s55, 0x2000
	s_add_u32 s66, s22, 0x80000
	s_addc_u32 s67, s23, 0
	s_add_i32 s55, s57, s6
	global_load_lds_dwordx4 v128, s[22:23]
	s_mov_b32 m0, s55
	s_nop 0
	global_load_lds_dwordx4 v172, s[66:67]
	s_add_i32 m0, s55, 0x2000
	s_nop 0
	global_load_lds_dwordx4 v128, s[66:67]
	s_mov_b32 m0, s12
	s_nop 0
	global_load_lds_dwordx4 v172, s[64:65]
	s_mov_b32 m0, s20
	s_nop 0
	global_load_lds_dwordx4 v128, s[64:65]
	s_waitcnt vmcnt(8) lgkmcnt(0)
	s_barrier
	s_barrier
; #define PG8_STAGE(bufoff, gbase, voff) do { _Pragma("unroll") for (int _i = 0; _i < 2; ++_i) \
;         __builtin_amdgcn_global_load_lds((const unsigned*)((const char*)(gbase) + (voff)[_i]), (PG8_LAS unsigned*)(lds + (bufoff) + ldsw + _i * 8192), 16, 0, 0); } while (0)
; #define PG8_LDA(dst, b, h) do { _Pragma("unroll") for (int m = 0; m < 4; ++m) _Pragma("unroll") for (int k = 0; k < 2; ++k) dst[m][k] = *(const PG8_LAS bf16x8*)(lds + PG8_SA(b, h) + aoff + m * 2048 + k * 1024); } while (0)
; #define PG8_LDB(dst, b, h) do { _Pragma("unroll") for (int n = 0; n < 2; ++n) _Pragma("unroll") for (int k = 0; k < 2; ++k) dst[n][k] = *(const PG8_LAS bf16x8*)(lds + PG8_SB(b, h) + boff + n * 2048 + k * 1024); } while (0)
; #define PG8_MMA(ai, bj, At, Bt) do { __builtin_amdgcn_s_setprio(1); _Pragma("unroll") for (int m = 0; m < 4; ++m) _Pragma("unroll") for (int n = 0; n < 2; ++n) _Pragma("unroll") for (int k = 0; k < 2; ++k) \
;         acc[ai][bj][m][n] = __builtin_amdgcn_mfma_f32_16x16x32_bf16(Bt[n][k], At[m][k], acc[ai][bj][m][n], 0, 0, 0); __builtin_amdgcn_s_setprio(0); } while (0)
; #define PG8_WAIT_V(n) asm volatile("s_waitcnt vmcnt(" #n ")" ::: "memory")
; #define PG8_WAIT_L(n) asm volatile("s_waitcnt lgkmcnt(" #n ")" ::: "memory")
; #define PG8_BAR __builtin_amdgcn_s_barrier()
; #define PG8_SCHED __builtin_amdgcn_sched_barrier(0)
; template <class Epi, class Sched, bool ALIGN_EPI = false, bool SP2 = false>
; __device__ __forceinline__ void gemm_phase(PG8_LAS unsigned char* lds, const Gemm g, const Sched& S, const Epi& E, const int tid_in) {
;     ...
;             PG8_LDB(B0, 1, 0); PG8_LDB(B1, 1, 1); PG8_SCHED; PG8_LDA(At, 1, 0); PG8_STAGE(PG8_SA(0, 1), a2 + hstepA, voffA);
;             PG8_WAIT_V(8); PG8_WAIT_L(0); PG8_BAR; PG8_MMA(0, 0, At, B0); PG8_MMA(0, 1, At, B1); PG8_BAR; PG8_SCHED;
;             PG8_LDA(At, 1, 1); PG8_STAGE(PG8_SB(1, 0), b3, voffB); PG8_STAGE(PG8_SB(1, 1), b3 + hstepB, voffB); PG8_STAGE(PG8_SA(1, 0), a3, voffA);
;             PG8_WAIT_V(8); PG8_WAIT_L(0); PG8_BAR; PG8_MMA(1, 0, At, B0); PG8_MMA(1, 1, At, B1); PG8_BAR; PG8_SCHED;
;     ...
;         if constexpr (ALIGN_EPI) { if (wr == 0) PG8_BAR; }
	s_add_i32 s55, 0, 0x18000
	s_add_i32 s57, 0, 0x1c000
	s_add_u32 s64, s64, 0x80000
	s_addc_u32 s65, s65, 0
	s_mov_b32 m0, s21
	s_nop 0
	global_load_lds_dwordx4 v172, s[64:65]
	s_mov_b32 m0, s28
	s_nop 0
	global_load_lds_dwordx4 v128, s[64:65]
	ds_read_b128 v[64:67], v249 offset:32768
	ds_read_b128 v[68:71], v249 offset:33792
	ds_read_b128 v[72:75], v249 offset:34816
	ds_read_b128 v[76:79], v249 offset:35840
	ds_read_b128 v[80:83], v249 offset:49152
	ds_read_b128 v[84:87], v249 offset:50176
	ds_read_b128 v[88:91], v249 offset:51200
	ds_read_b128 v[92:95], v249 offset:52224
	ds_read_b128 v[96:99], v154 offset:32768
	ds_read_b128 v[100:103], v154 offset:33792
	ds_read_b128 v[104:107], v154 offset:34816
	ds_read_b128 v[108:111], v154 offset:35840
	ds_read_b128 v[112:115], v154 offset:36864
	ds_read_b128 v[116:119], v154 offset:37888
	ds_read_b128 v[120:123], v154 offset:38912
	ds_read_b128 v[124:127], v154 offset:39936
	s_waitcnt vmcnt(8) lgkmcnt(0)
	s_barrier
	v_mfma_f32_16x16x32_bf16 v[60:63], v[64:67], v[96:99], v[60:63]
	v_mfma_f32_16x16x32_bf16 v[56:59], v[72:75], v[96:99], v[56:59]
	v_mfma_f32_16x16x32_bf16 v[48:51], v[64:67], v[104:107], v[48:51]
	v_mfma_f32_16x16x32_bf16 v[40:43], v[72:75], v[104:107], v[40:43]
	v_mfma_f32_16x16x32_bf16 v[32:35], v[64:67], v[112:115], v[32:35]
	v_mfma_f32_16x16x32_bf16 v[24:27], v[72:75], v[112:115], v[24:27]
	v_mfma_f32_16x16x32_bf16 v[16:19], v[64:67], v[120:123], v[16:19]
	v_mfma_f32_16x16x32_bf16 v[8:11], v[72:75], v[120:123], v[8:11]
	v_mfma_f32_16x16x32_bf16 v[60:63], v[68:71], v[100:103], v[60:63]
	v_mfma_f32_16x16x32_bf16 v[56:59], v[76:79], v[100:103], v[56:59]
	v_mfma_f32_16x16x32_bf16 v[48:51], v[68:71], v[108:111], v[48:51]
	v_mfma_f32_16x16x32_bf16 v[40:43], v[76:79], v[108:111], v[40:43]
	v_mfma_f32_16x16x32_bf16 v[32:35], v[68:71], v[116:119], v[32:35]
	v_mfma_f32_16x16x32_bf16 v[24:27], v[76:79], v[116:119], v[24:27]
	v_mfma_f32_16x16x32_bf16 v[16:19], v[68:71], v[124:127], v[16:19]
	v_mfma_f32_16x16x32_bf16 v[8:11], v[76:79], v[124:127], v[8:11]
	v_mfma_f32_16x16x32_bf16 v[52:55], v[80:83], v[96:99], v[52:55]
	v_mfma_f32_16x16x32_bf16 v[44:47], v[88:91], v[96:99], v[44:47]
	v_mfma_f32_16x16x32_bf16 v[36:39], v[80:83], v[104:107], v[36:39]
	v_mfma_f32_16x16x32_bf16 v[28:31], v[88:91], v[104:107], v[28:31]
	v_mfma_f32_16x16x32_bf16 v[20:23], v[80:83], v[112:115], v[20:23]
	v_mfma_f32_16x16x32_bf16 v[12:15], v[88:91], v[112:115], v[12:15]
	v_mfma_f32_16x16x32_bf16 v[4:7], v[80:83], v[120:123], v[4:7]
	v_mfma_f32_16x16x32_bf16 v[0:3], v[88:91], v[120:123], v[0:3]
	v_mfma_f32_16x16x32_bf16 v[52:55], v[84:87], v[100:103], v[52:55]
	v_mfma_f32_16x16x32_bf16 v[44:47], v[92:95], v[100:103], v[44:47]
	v_mfma_f32_16x16x32_bf16 v[36:39], v[84:87], v[108:111], v[36:39]
	v_mfma_f32_16x16x32_bf16 v[28:31], v[92:95], v[108:111], v[28:31]
	v_mfma_f32_16x16x32_bf16 v[20:23], v[84:87], v[116:119], v[20:23]
	v_mfma_f32_16x16x32_bf16 v[12:15], v[92:95], v[116:119], v[12:15]
	v_mfma_f32_16x16x32_bf16 v[4:7], v[84:87], v[124:127], v[4:7]
	v_mfma_f32_16x16x32_bf16 v[0:3], v[92:95], v[124:127], v[0:3]
	s_barrier
	s_add_i32 s55, s55, s6
	s_mov_b32 m0, s55
	s_nop 0
	s_add_u32 s100, s22, 0x80
	s_addc_u32 s101, s23, 0
	global_load_lds_dwordx4 v172, s[100:101]
	s_add_i32 m0, s55, 0x2000
	s_add_u32 s22, s22, 0x80080
	s_addc_u32 s23, s23, 0
	s_add_i32 s55, s57, s6
	global_load_lds_dwordx4 v128, s[100:101]
	s_mov_b32 m0, s55
	s_nop 0
	global_load_lds_dwordx4 v172, s[22:23]
	s_add_i32 m0, s55, 0x2000
	s_nop 0
	global_load_lds_dwordx4 v128, s[22:23]
	s_mov_b32 m0, s29
	s_nop 0
	s_add_u32 s100, s64, 0xfff80080
	s_addc_u32 s101, s65, -1
	global_load_lds_dwordx4 v172, s[100:101]
	s_mov_b32 m0, s30
	s_nop 0
	global_load_lds_dwordx4 v128, s[100:101]
	s_waitcnt vmcnt(8) lgkmcnt(0)
	s_barrier
	s_barrier
	s_add_i32 s53, s53, 2
	s_add_u32 s62, s62, 0x100
	s_addc_u32 s63, s63, 0
	s_add_u32 s35, s35, 0x100
	s_addc_u32 s38, s38, 0
	s_cmp_gt_u32 s53, 5
	s_cbranch_scc0 .LBB0_2059
	s_and_b64 vcc, exec, s[36:37]
	s_cbranch_vccz .LBB0_2062
	s_barrier

;     __device__ __forceinline__ void a_ready(const Unit& u) const { wait_panel(cnt, u.pm, need, tmo, wave); }
;     __device__ __forceinline__ void a_ready(const Unit& u) const { wait_panel(cnt, u.pm, need, tmo, wave); }
; #define PG8_STAGE(bufoff, gbase, voff) do { _Pragma("unroll") for (int _i = 0; _i < 2; ++_i) \
;         __builtin_amdgcn_global_load_lds((const unsigned*)((const char*)(gbase) + (voff)[_i]), (PG8_LAS unsigned*)(lds + (bufoff) + ldsw + _i * 8192), 16, 0, 0); } while (0)
; #define PG8_LDA(dst, b, h) do { _Pragma("unroll") for (int m = 0; m < 4; ++m) _Pragma("unroll") for (int k = 0; k < 2; ++k) dst[m][k] = *(const PG8_LAS bf16x8*)(lds + PG8_SA(b, h) + aoff + m * 2048 + k * 1024); } while (0)
; #define PG8_LDB(dst, b, h) do { _Pragma("unroll") for (int n = 0; n < 2; ++n) _Pragma("unroll") for (int k = 0; k < 2; ++k) dst[n][k] = *(const PG8_LAS bf16x8*)(lds + PG8_SB(b, h) + boff + n * 2048 + k * 1024); } while (0)
; #define PG8_WAIT_V(n) asm volatile("s_waitcnt vmcnt(" #n ")" ::: "memory")
; #define PG8_WAIT_L(n) asm volatile("s_waitcnt lgkmcnt(" #n ")" ::: "memory")
; #define PG8_BAR __builtin_amdgcn_s_barrier()
; #define PG8_SCHED __builtin_amdgcn_sched_barrier(0)
; template <class Epi, class Sched, bool ALIGN_EPI = false, bool SP2 = false>
; __device__ __forceinline__ void gemm_phase(PG8_LAS unsigned char* lds, const Gemm g, const Sched& S, const Epi& E, const int tid_in) {
;     ...
;             const bool last = (t == nt - 2);
;             const char* a1 = cA + (size_t)(t + 1) * kstep;
;             const char* a2 = last ? nA : cA + (size_t)(t + 2) * kstep; const char* b2 = last ? nB : cB + (size_t)(t + 2) * kstep;
;             const char* a3 = a2 + kstep; const char* b3 = b2 + kstep;
;             if (last && has_next) S.a_ready(nxt);
;             if constexpr (SP2) {
;             PG8_LDB(B0, 0, 0); PG8_LDB(B1, 0, 1); PG8_SCHED; PG8_LDA(At, 0, 0); PG8_STAGE(PG8_SA(1, 1), a1 + hstepA, voffA);
;             PG8_WAIT_V(8); PG8_WAIT_L(0); PG8_BAR; PG8_MMA(0, 0, At, B0); PG8_MMA(0, 1, At, B1); PG8_BAR; PG8_SCHED;
;             PG8_LDA(At, 0, 1); PG8_STAGE(PG8_SB(0, 0), b2, voffB); PG8_STAGE(PG8_SB(0, 1), b2 + hstepB, voffB); PG8_STAGE(PG8_SA(0, 0), a2, voffA);
;             PG8_WAIT_V(8); PG8_WAIT_L(0); PG8_BAR; PG8_MMA(1, 0, At, B0); PG8_MMA(1, 1, At, B1); PG8_BAR; PG8_SCHED;
.LBB0_2312:
	s_add_u32 s22, s64, 0xfff80080
	s_addc_u32 s23, s65, -1
	s_add_i32 s55, 0, 0x10000
	s_cmp_eq_u32 s51, 28
	s_cselect_b32 s67, s6, s23
	s_cselect_b32 s66, s16, s22
	s_cselect_b32 s23, s17, s35
	s_cselect_b32 s22, s33, s34
	s_add_i32 s63, 0, 0x14000
	s_add_i32 m0, s37, 0xc000
	s_nop 0
	global_load_lds_dwordx4 v134, s[64:65]
	s_add_i32 m0, s37, 0xe000
	s_nop 0
	global_load_lds_dwordx4 v136, s[64:65]
	ds_read_b128 v[144:147], v249
	ds_read_b128 v[148:151], v249 offset:1024
	ds_read_b128 v[152:155], v249 offset:2048
	ds_read_b128 v[156:159], v249 offset:3072
	ds_read_b128 v[160:163], v249 offset:16384
	ds_read_b128 v[164:167], v249 offset:17408
	ds_read_b128 v[168:171], v249 offset:18432
	ds_read_b128 v[190:193], v249 offset:19456
	ds_read_b128 v[198:201], v143
	ds_read_b128 v[202:205], v143 offset:1024
	ds_read_b128 v[206:209], v143 offset:2048
	ds_read_b128 v[210:213], v143 offset:3072
	ds_read_b128 v[224:227], v143 offset:4096
	ds_read_b128 v[228:231], v143 offset:5120
	ds_read_b128 v[232:235], v143 offset:6144
	ds_read_b128 v[236:239], v143 offset:7168
	s_waitcnt vmcnt(8) lgkmcnt(0)
	s_barrier
	v_mfma_f32_16x16x32_bf16 v[124:127], v[144:147], v[198:201], v[124:127]
	v_mfma_f32_16x16x32_bf16 v[116:119], v[152:155], v[198:201], v[116:119]
	v_mfma_f32_16x16x32_bf16 v[108:111], v[144:147], v[206:209], v[108:111]
	v_mfma_f32_16x16x32_bf16 v[100:103], v[152:155], v[206:209], v[100:103]
	v_mfma_f32_16x16x32_bf16 v[92:95], v[144:147], v[224:227], v[92:95]
	v_mfma_f32_16x16x32_bf16 v[84:87], v[152:155], v[224:227], v[84:87]
	v_mfma_f32_16x16x32_bf16 v[76:79], v[144:147], v[232:235], v[76:79]
	v_mfma_f32_16x16x32_bf16 v[68:71], v[152:155], v[232:235], v[68:71]
	v_mfma_f32_16x16x32_bf16 v[124:127], v[148:151], v[202:205], v[124:127]
	v_mfma_f32_16x16x32_bf16 v[116:119], v[156:159], v[202:205], v[116:119]
	v_mfma_f32_16x16x32_bf16 v[108:111], v[148:151], v[210:213], v[108:111]
	v_mfma_f32_16x16x32_bf16 v[100:103], v[156:159], v[210:213], v[100:103]
	v_mfma_f32_16x16x32_bf16 v[92:95], v[148:151], v[228:231], v[92:95]
	v_mfma_f32_16x16x32_bf16 v[84:87], v[156:159], v[228:231], v[84:87]
	v_mfma_f32_16x16x32_bf16 v[76:79], v[148:151], v[236:239], v[76:79]
	v_mfma_f32_16x16x32_bf16 v[68:71], v[156:159], v[236:239], v[68:71]
	v_mfma_f32_16x16x32_bf16 v[120:123], v[160:163], v[198:201], v[120:123]
	v_mfma_f32_16x16x32_bf16 v[112:115], v[168:171], v[198:201], v[112:115]
	v_mfma_f32_16x16x32_bf16 v[104:107], v[160:163], v[206:209], v[104:107]
	v_mfma_f32_16x16x32_bf16 v[96:99], v[168:171], v[206:209], v[96:99]
	v_mfma_f32_16x16x32_bf16 v[88:91], v[160:163], v[224:227], v[88:91]
	v_mfma_f32_16x16x32_bf16 v[80:83], v[168:171], v[224:227], v[80:83]
	v_mfma_f32_16x16x32_bf16 v[72:75], v[160:163], v[232:235], v[72:75]
	v_mfma_f32_16x16x32_bf16 v[64:67], v[168:171], v[232:235], v[64:67]
	v_mfma_f32_16x16x32_bf16 v[120:123], v[164:167], v[202:205], v[120:123]
	v_mfma_f32_16x16x32_bf16 v[112:115], v[190:193], v[202:205], v[112:115]
	v_mfma_f32_16x16x32_bf16 v[104:107], v[164:167], v[210:213], v[104:107]
	v_mfma_f32_16x16x32_bf16 v[96:99], v[190:193], v[210:213], v[96:99]
	v_mfma_f32_16x16x32_bf16 v[88:91], v[164:167], v[228:231], v[88:91]
	v_mfma_f32_16x16x32_bf16 v[80:83], v[190:193], v[228:231], v[80:83]
	v_mfma_f32_16x16x32_bf16 v[72:75], v[164:167], v[236:239], v[72:75]
	v_mfma_f32_16x16x32_bf16 v[64:67], v[190:193], v[236:239], v[64:67]
	s_barrier
	s_add_i32 s55, s55, s69
	s_mov_b32 m0, s55
	s_nop 0
	global_load_lds_dwordx4 v172, s[22:23]
	s_add_i32 m0, s55, 0x2000
	s_add_u32 vcc_lo, s22, 0x80000
	s_addc_u32 vcc_hi, s23, 0
	s_add_i32 s55, s63, s69
	global_load_lds_dwordx4 v132, s[22:23]
	s_mov_b32 m0, s55
	s_nop 0
	global_load_lds_dwordx4 v172, vcc
	s_add_i32 m0, s55, 0x2000
	s_nop 0
	global_load_lds_dwordx4 v132, vcc
	s_mov_b32 m0, s37
	s_nop 0
	global_load_lds_dwordx4 v128, s[66:67]
	s_mov_b32 m0, s70
	s_nop 0
	global_load_lds_dwordx4 v130, s[66:67]
	ds_read_b128 v[198:201], v143 offset:16384
	ds_read_b128 v[202:205], v143 offset:17408
	ds_read_b128 v[206:209], v143 offset:18432
	ds_read_b128 v[210:213], v143 offset:19456
	ds_read_b128 v[224:227], v143 offset:20480
	ds_read_b128 v[228:231], v143 offset:21504
	ds_read_b128 v[232:235], v143 offset:22528
	ds_read_b128 v[236:239], v143 offset:23552
	s_waitcnt vmcnt(8) lgkmcnt(0)
	s_barrier
	v_mfma_f32_16x16x32_bf16 v[60:63], v[144:147], v[198:201], v[60:63]
	v_mfma_f32_16x16x32_bf16 v[52:55], v[152:155], v[198:201], v[52:55]
	v_mfma_f32_16x16x32_bf16 v[44:47], v[144:147], v[206:209], v[44:47]
	v_mfma_f32_16x16x32_bf16 v[36:39], v[152:155], v[206:209], v[36:39]
	v_mfma_f32_16x16x32_bf16 v[28:31], v[144:147], v[224:227], v[28:31]
	v_mfma_f32_16x16x32_bf16 v[20:23], v[152:155], v[224:227], v[20:23]
	v_mfma_f32_16x16x32_bf16 v[12:15], v[144:147], v[232:235], v[12:15]
	v_mfma_f32_16x16x32_bf16 v[4:7], v[152:155], v[232:235], v[4:7]
	v_mfma_f32_16x16x32_bf16 v[60:63], v[148:151], v[202:205], v[60:63]
	v_mfma_f32_16x16x32_bf16 v[52:55], v[156:159], v[202:205], v[52:55]
	v_mfma_f32_16x16x32_bf16 v[44:47], v[148:151], v[210:213], v[44:47]
	v_mfma_f32_16x16x32_bf16 v[36:39], v[156:159], v[210:213], v[36:39]
	v_mfma_f32_16x16x32_bf16 v[28:31], v[148:151], v[228:231], v[28:31]
	v_mfma_f32_16x16x32_bf16 v[20:23], v[156:159], v[228:231], v[20:23]
	v_mfma_f32_16x16x32_bf16 v[12:15], v[148:151], v[236:239], v[12:15]
	v_mfma_f32_16x16x32_bf16 v[4:7], v[156:159], v[236:239], v[4:7]
	v_mfma_f32_16x16x32_bf16 v[56:59], v[160:163], v[198:201], v[56:59]
	v_mfma_f32_16x16x32_bf16 v[48:51], v[168:171], v[198:201], v[48:51]
	v_mfma_f32_16x16x32_bf16 v[40:43], v[160:163], v[206:209], v[40:43]
	v_mfma_f32_16x16x32_bf16 v[32:35], v[168:171], v[206:209], v[32:35]
	v_mfma_f32_16x16x32_bf16 v[24:27], v[160:163], v[224:227], v[24:27]
	v_mfma_f32_16x16x32_bf16 v[16:19], v[168:171], v[224:227], v[16:19]
	v_mfma_f32_16x16x32_bf16 v[8:11], v[160:163], v[232:235], v[8:11]
	v_mfma_f32_16x16x32_bf16 v[0:3], v[168:171], v[232:235], v[0:3]
	v_mfma_f32_16x16x32_bf16 v[56:59], v[164:167], v[202:205], v[56:59]
	v_mfma_f32_16x16x32_bf16 v[48:51], v[190:193], v[202:205], v[48:51]
	v_mfma_f32_16x16x32_bf16 v[40:43], v[164:167], v[210:213], v[40:43]
	v_mfma_f32_16x16x32_bf16 v[32:35], v[190:193], v[210:213], v[32:35]
	v_mfma_f32_16x16x32_bf16 v[24:27], v[164:167], v[228:231], v[24:27]
	v_mfma_f32_16x16x32_bf16 v[16:19], v[190:193], v[228:231], v[16:19]
	v_mfma_f32_16x16x32_bf16 v[8:11], v[164:167], v[236:239], v[8:11]
	v_mfma_f32_16x16x32_bf16 v[0:3], v[190:193], v[236:239], v[0:3]
	s_barrier
; #define PG8_STAGE(bufoff, gbase, voff) do { _Pragma("unroll") for (int _i = 0; _i < 2; ++_i) \
;         __builtin_amdgcn_global_load_lds((const unsigned*)((const char*)(gbase) + (voff)[_i]), (PG8_LAS unsigned*)(lds + (bufoff) + ldsw + _i * 8192), 16, 0, 0); } while (0)
; #define PG8_LDA(dst, b, h) do { _Pragma("unroll") for (int m = 0; m < 4; ++m) _Pragma("unroll") for (int k = 0; k < 2; ++k) dst[m][k] = *(const PG8_LAS bf16x8*)(lds + PG8_SA(b, h) + aoff + m * 2048 + k * 1024); } while (0)
; #define PG8_LDB(dst, b, h) do { _Pragma("unroll") for (int n = 0; n < 2; ++n) _Pragma("unroll") for (int k = 0; k < 2; ++k) dst[n][k] = *(const PG8_LAS bf16x8*)(lds + PG8_SB(b, h) + boff + n * 2048 + k * 1024); } while (0)
; #define PG8_MMA(ai, bj, At, Bt) do { __builtin_amdgcn_s_setprio(1); _Pragma("unroll") for (int m = 0; m < 4; ++m) _Pragma("unroll") for (int n = 0; n < 2; ++n) _Pragma("unroll") for (int k = 0; k < 2; ++k) \
;         acc[ai][bj][m][n] = __builtin_amdgcn_mfma_f32_16x16x32_bf16(Bt[n][k], At[m][k], acc[ai][bj][m][n], 0, 0, 0); __builtin_amdgcn_s_setprio(0); } while (0)
; #define PG8_WAIT_V(n) asm volatile("s_waitcnt vmcnt(" #n ")" ::: "memory")
; #define PG8_WAIT_L(n) asm volatile("s_waitcnt lgkmcnt(" #n ")" ::: "memory")
; #define PG8_BAR __builtin_amdgcn_s_barrier()
; #define PG8_SCHED __builtin_amdgcn_sched_barrier(0)
; template <class Epi, class Sched, bool ALIGN_EPI = false, bool SP2 = false>
; __device__ __forceinline__ void gemm_phase(PG8_LAS unsigned char* lds, const Gemm g, const Sched& S, const Epi& E, const int tid_in) {
;     ...
;             PG8_LDB(B0, 1, 0); PG8_LDB(B1, 1, 1); PG8_SCHED; PG8_LDA(At, 1, 0); PG8_STAGE(PG8_SA(0, 1), a2 + hstepA, voffA);
;             PG8_WAIT_V(8); PG8_WAIT_L(0); PG8_BAR; PG8_MMA(0, 0, At, B0); PG8_MMA(0, 1, At, B1); PG8_BAR; PG8_SCHED;
;             PG8_LDA(At, 1, 1); PG8_STAGE(PG8_SB(1, 0), b3, voffB); PG8_STAGE(PG8_SB(1, 1), b3 + hstepB, voffB); PG8_STAGE(PG8_SA(1, 0), a3, voffA);
;             PG8_WAIT_V(8); PG8_WAIT_L(0); PG8_BAR; PG8_MMA(1, 0, At, B0); PG8_MMA(1, 1, At, B1); PG8_BAR; PG8_SCHED;
;     ...
;         if constexpr (ALIGN_EPI) { if (wr == 0) PG8_BAR; }
	s_add_i32 s55, 0, 0x18000
	s_add_i32 s63, 0, 0x1c000
	s_add_u32 s66, s66, 0x80000
	s_addc_u32 s67, s67, 0
	s_mov_b32 m0, s71
	s_nop 0
	global_load_lds_dwordx4 v128, s[66:67]
	s_mov_b32 m0, s72
	s_nop 0
	global_load_lds_dwordx4 v130, s[66:67]
	ds_read_b128 v[144:147], v249 offset:32768
	ds_read_b128 v[148:151], v249 offset:33792
	ds_read_b128 v[152:155], v249 offset:34816
	ds_read_b128 v[156:159], v249 offset:35840
	ds_read_b128 v[160:163], v249 offset:49152
	ds_read_b128 v[164:167], v249 offset:50176
	ds_read_b128 v[168:171], v249 offset:51200
	ds_read_b128 v[190:193], v249 offset:52224
	ds_read_b128 v[198:201], v143 offset:32768
	ds_read_b128 v[202:205], v143 offset:33792
	ds_read_b128 v[206:209], v143 offset:34816
	ds_read_b128 v[210:213], v143 offset:35840
	ds_read_b128 v[224:227], v143 offset:36864
	ds_read_b128 v[228:231], v143 offset:37888
	ds_read_b128 v[232:235], v143 offset:38912
	ds_read_b128 v[236:239], v143 offset:39936
	s_waitcnt vmcnt(8) lgkmcnt(0)
	s_barrier
	v_mfma_f32_16x16x32_bf16 v[124:127], v[144:147], v[198:201], v[124:127]
	v_mfma_f32_16x16x32_bf16 v[116:119], v[152:155], v[198:201], v[116:119]
	v_mfma_f32_16x16x32_bf16 v[108:111], v[144:147], v[206:209], v[108:111]
	v_mfma_f32_16x16x32_bf16 v[100:103], v[152:155], v[206:209], v[100:103]
	v_mfma_f32_16x16x32_bf16 v[92:95], v[144:147], v[224:227], v[92:95]
	v_mfma_f32_16x16x32_bf16 v[84:87], v[152:155], v[224:227], v[84:87]
	v_mfma_f32_16x16x32_bf16 v[76:79], v[144:147], v[232:235], v[76:79]
	v_mfma_f32_16x16x32_bf16 v[68:71], v[152:155], v[232:235], v[68:71]
	v_mfma_f32_16x16x32_bf16 v[124:127], v[148:151], v[202:205], v[124:127]
	v_mfma_f32_16x16x32_bf16 v[116:119], v[156:159], v[202:205], v[116:119]
	v_mfma_f32_16x16x32_bf16 v[108:111], v[148:151], v[210:213], v[108:111]
	v_mfma_f32_16x16x32_bf16 v[100:103], v[156:159], v[210:213], v[100:103]
	v_mfma_f32_16x16x32_bf16 v[92:95], v[148:151], v[228:231], v[92:95]
	v_mfma_f32_16x16x32_bf16 v[84:87], v[156:159], v[228:231], v[84:87]
	v_mfma_f32_16x16x32_bf16 v[76:79], v[148:151], v[236:239], v[76:79]
	v_mfma_f32_16x16x32_bf16 v[68:71], v[156:159], v[236:239], v[68:71]
	v_mfma_f32_16x16x32_bf16 v[120:123], v[160:163], v[198:201], v[120:123]
	v_mfma_f32_16x16x32_bf16 v[112:115], v[168:171], v[198:201], v[112:115]
	v_mfma_f32_16x16x32_bf16 v[104:107], v[160:163], v[206:209], v[104:107]
	v_mfma_f32_16x16x32_bf16 v[96:99], v[168:171], v[206:209], v[96:99]
	v_mfma_f32_16x16x32_bf16 v[88:91], v[160:163], v[224:227], v[88:91]
	v_mfma_f32_16x16x32_bf16 v[80:83], v[168:171], v[224:227], v[80:83]
	v_mfma_f32_16x16x32_bf16 v[72:75], v[160:163], v[232:235], v[72:75]
	v_mfma_f32_16x16x32_bf16 v[64:67], v[168:171], v[232:235], v[64:67]
	v_mfma_f32_16x16x32_bf16 v[120:123], v[164:167], v[202:205], v[120:123]
	v_mfma_f32_16x16x32_bf16 v[112:115], v[190:193], v[202:205], v[112:115]
	v_mfma_f32_16x16x32_bf16 v[104:107], v[164:167], v[210:213], v[104:107]
	v_mfma_f32_16x16x32_bf16 v[96:99], v[190:193], v[210:213], v[96:99]
	v_mfma_f32_16x16x32_bf16 v[88:91], v[164:167], v[228:231], v[88:91]
	v_mfma_f32_16x16x32_bf16 v[80:83], v[190:193], v[228:231], v[80:83]
	v_mfma_f32_16x16x32_bf16 v[72:75], v[164:167], v[236:239], v[72:75]
	v_mfma_f32_16x16x32_bf16 v[64:67], v[190:193], v[236:239], v[64:67]
	s_barrier
	s_add_i32 s55, s55, s69
	s_mov_b32 m0, s55
	s_add_u32 s100, s22, 0x80
	s_addc_u32 s101, s23, 0
	global_load_lds_dwordx4 v172, s[100:101]
	s_add_i32 m0, s55, 0x2000
	s_add_u32 s22, s22, 0x80080
	s_addc_u32 s23, s23, 0
	s_add_i32 s55, s63, s69
	global_load_lds_dwordx4 v132, s[100:101]
	s_mov_b32 m0, s55
	s_nop 0
	global_load_lds_dwordx4 v172, s[22:23]
	s_add_i32 m0, s55, 0x2000
	s_nop 0
	global_load_lds_dwordx4 v132, s[22:23]
	s_mov_b32 m0, s73
	s_nop 0
	s_add_u32 s100, s66, 0xfff80080
	s_addc_u32 s101, s67, -1
	global_load_lds_dwordx4 v128, s[100:101]
	s_mov_b32 m0, s74
	s_nop 0
	global_load_lds_dwordx4 v130, s[100:101]
	ds_read_b128 v[198:201], v143 offset:49152
	ds_read_b128 v[202:205], v143 offset:50176
	ds_read_b128 v[206:209], v143 offset:51200
	ds_read_b128 v[210:213], v143 offset:52224
	ds_read_b128 v[224:227], v143 offset:53248
	ds_read_b128 v[228:231], v143 offset:54272
	ds_read_b128 v[232:235], v143 offset:55296
	ds_read_b128 v[236:239], v143 offset:56320
	s_waitcnt vmcnt(8) lgkmcnt(0)
	s_barrier
	v_mfma_f32_16x16x32_bf16 v[60:63], v[144:147], v[198:201], v[60:63]
	v_mfma_f32_16x16x32_bf16 v[52:55], v[152:155], v[198:201], v[52:55]
	v_mfma_f32_16x16x32_bf16 v[44:47], v[144:147], v[206:209], v[44:47]
	v_mfma_f32_16x16x32_bf16 v[36:39], v[152:155], v[206:209], v[36:39]
	v_mfma_f32_16x16x32_bf16 v[28:31], v[144:147], v[224:227], v[28:31]
	v_mfma_f32_16x16x32_bf16 v[20:23], v[152:155], v[224:227], v[20:23]
	v_mfma_f32_16x16x32_bf16 v[12:15], v[144:147], v[232:235], v[12:15]
	v_mfma_f32_16x16x32_bf16 v[4:7], v[152:155], v[232:235], v[4:7]
	v_mfma_f32_16x16x32_bf16 v[60:63], v[148:151], v[202:205], v[60:63]
	v_mfma_f32_16x16x32_bf16 v[52:55], v[156:159], v[202:205], v[52:55]
	v_mfma_f32_16x16x32_bf16 v[44:47], v[148:151], v[210:213], v[44:47]
	v_mfma_f32_16x16x32_bf16 v[36:39], v[156:159], v[210:213], v[36:39]
	v_mfma_f32_16x16x32_bf16 v[28:31], v[148:151], v[228:231], v[28:31]
	v_mfma_f32_16x16x32_bf16 v[20:23], v[156:159], v[228:231], v[20:23]
	v_mfma_f32_16x16x32_bf16 v[12:15], v[148:151], v[236:239], v[12:15]
	v_mfma_f32_16x16x32_bf16 v[4:7], v[156:159], v[236:239], v[4:7]
	v_mfma_f32_16x16x32_bf16 v[56:59], v[160:163], v[198:201], v[56:59]
	v_mfma_f32_16x16x32_bf16 v[48:51], v[168:171], v[198:201], v[48:51]
	v_mfma_f32_16x16x32_bf16 v[40:43], v[160:163], v[206:209], v[40:43]
	v_mfma_f32_16x16x32_bf16 v[32:35], v[168:171], v[206:209], v[32:35]
	v_mfma_f32_16x16x32_bf16 v[24:27], v[160:163], v[224:227], v[24:27]
	v_mfma_f32_16x16x32_bf16 v[16:19], v[168:171], v[224:227], v[16:19]
	v_mfma_f32_16x16x32_bf16 v[8:11], v[160:163], v[232:235], v[8:11]
	v_mfma_f32_16x16x32_bf16 v[0:3], v[168:171], v[232:235], v[0:3]
	v_mfma_f32_16x16x32_bf16 v[56:59], v[164:167], v[202:205], v[56:59]
	v_mfma_f32_16x16x32_bf16 v[48:51], v[190:193], v[202:205], v[48:51]
	v_mfma_f32_16x16x32_bf16 v[40:43], v[164:167], v[210:213], v[40:43]
	v_mfma_f32_16x16x32_bf16 v[32:35], v[190:193], v[210:213], v[32:35]
	v_mfma_f32_16x16x32_bf16 v[24:27], v[164:167], v[228:231], v[24:27]
	v_mfma_f32_16x16x32_bf16 v[16:19], v[190:193], v[228:231], v[16:19]
	v_mfma_f32_16x16x32_bf16 v[8:11], v[164:167], v[236:239], v[8:11]
	v_mfma_f32_16x16x32_bf16 v[0:3], v[190:193], v[236:239], v[0:3]
	s_barrier
	s_add_i32 s51, s51, 2
	s_add_u32 s64, s64, 0x100
	s_addc_u32 s65, s65, 0
	s_add_u32 s34, s34, 0x100
	s_addc_u32 s35, s35, 0
	s_cmp_gt_u32 s51, 29
	s_cbranch_scc0 .LBB0_2312
	s_and_b64 vcc, exec, s[48:49]
	s_cbranch_vccz .LBB0_2315
	s_barrier

;     __device__ __forceinline__ void a_ready(const Unit& u) const { wait_panel(cnt, u.pm, need, tmo, wave); }
;     __device__ __forceinline__ void a_ready(const Unit& u) const { wait_panel(cnt, u.pm, need, tmo, wave); }
; #define PG8_STAGE(bufoff, gbase, voff) do { _Pragma("unroll") for (int _i = 0; _i < 2; ++_i) \
;         __builtin_amdgcn_global_load_lds((const unsigned*)((const char*)(gbase) + (voff)[_i]), (PG8_LAS unsigned*)(lds + (bufoff) + ldsw + _i * 8192), 16, 0, 0); } while (0)
; #define PG8_LDA(dst, b, h) do { _Pragma("unroll") for (int m = 0; m < 4; ++m) _Pragma("unroll") for (int k = 0; k < 2; ++k) dst[m][k] = *(const PG8_LAS bf16x8*)(lds + PG8_SA(b, h) + aoff + m * 2048 + k * 1024); } while (0)
; #define PG8_LDB(dst, b, h) do { _Pragma("unroll") for (int n = 0; n < 2; ++n) _Pragma("unroll") for (int k = 0; k < 2; ++k) dst[n][k] = *(const PG8_LAS bf16x8*)(lds + PG8_SB(b, h) + boff + n * 2048 + k * 1024); } while (0)
; #define PG8_WAIT_V(n) asm volatile("s_waitcnt vmcnt(" #n ")" ::: "memory")
; #define PG8_WAIT_L(n) asm volatile("s_waitcnt lgkmcnt(" #n ")" ::: "memory")
; #define PG8_BAR __builtin_amdgcn_s_barrier()
; #define PG8_SCHED __builtin_amdgcn_sched_barrier(0)
; template <class Epi, class Sched, bool ALIGN_EPI = false, bool SP2 = false>
; __device__ __forceinline__ void gemm_phase(PG8_LAS unsigned char* lds, const Gemm g, const Sched& S, const Epi& E, const int tid_in) {
;     ...
;             const bool last = (t == nt - 2);
;             const char* a1 = cA + (size_t)(t + 1) * kstep;
;             const char* a2 = last ? nA : cA + (size_t)(t + 2) * kstep; const char* b2 = last ? nB : cB + (size_t)(t + 2) * kstep;
;             const char* a3 = a2 + kstep; const char* b3 = b2 + kstep;
;             if (last && has_next) S.a_ready(nxt);
;             if constexpr (SP2) {
;             PG8_LDB(B0, 0, 0); PG8_LDB(B1, 0, 1); PG8_SCHED; PG8_LDA(At, 0, 0); PG8_STAGE(PG8_SA(1, 1), a1 + hstepA, voffA);
;             PG8_WAIT_V(8); PG8_WAIT_L(0); PG8_BAR; PG8_MMA(0, 0, At, B0); PG8_MMA(0, 1, At, B1); PG8_BAR; PG8_SCHED;
;             PG8_LDA(At, 0, 1); PG8_STAGE(PG8_SB(0, 0), b2, voffB); PG8_STAGE(PG8_SB(0, 1), b2 + hstepB, voffB); PG8_STAGE(PG8_SA(0, 0), a2, voffA);
;             PG8_WAIT_V(8); PG8_WAIT_L(0); PG8_BAR; PG8_MMA(1, 0, At, B0); PG8_MMA(1, 1, At, B1); PG8_BAR; PG8_SCHED;
.LBB0_2372:
	s_lshl_b32 s72, s85, 7
	s_add_u32 s73, s62, s72
	s_addc_u32 s74, s63, 0
	s_add_u32 s75, s73, 0x100
	s_addc_u32 s76, s74, 0
	s_and_b64 s[70:71], s[22:23], exec
	s_cselect_b32 s71, s59, s76
	s_cselect_b32 s70, s58, s75
	s_add_u32 s72, s64, s72
	s_addc_u32 s75, s65, 0
	s_add_u32 s72, s72, 0x100
	s_addc_u32 s75, s75, 0
	s_and_b64 s[22:23], s[22:23], exec
	s_cselect_b32 s23, s61, s75
	s_cselect_b32 s22, s60, s72
	s_add_i32 s75, 0, 0x10000
	s_add_i32 s76, 0, 0x14000
	s_add_u32 s72, s73, 0x150080
	s_addc_u32 s73, s74, 0
	s_add_i32 m0, s21, 0xc000
	s_nop 0
	global_load_lds_dwordx4 v148, s[72:73]
	s_add_i32 m0, s21, 0xe000
	s_nop 0
	global_load_lds_dwordx4 v150, s[72:73]
	ds_read_b128 v[128:131], v249
	ds_read_b128 v[132:135], v249 offset:1024
	ds_read_b128 v[136:139], v249 offset:2048
	ds_read_b128 v[140:143], v249 offset:3072
	ds_read_b128 v[144:147], v249 offset:16384
	ds_read_b128 v[154:157], v249 offset:17408
	ds_read_b128 v[158:161], v249 offset:18432
	ds_read_b128 v[162:165], v249 offset:19456
	ds_read_b128 v[166:169], v200
	ds_read_b128 v[190:193], v200 offset:1024
	ds_read_b128 v[202:205], v200 offset:2048
	ds_read_b128 v[206:209], v200 offset:3072
	ds_read_b128 v[210:213], v200 offset:4096
	ds_read_b128 v[224:227], v200 offset:5120
	ds_read_b128 v[228:231], v200 offset:6144
	ds_read_b128 v[232:235], v200 offset:7168
	s_waitcnt vmcnt(8) lgkmcnt(0)
	s_barrier
	v_mfma_f32_16x16x32_bf16 v[124:127], v[128:131], v[166:169], v[124:127]
	v_mfma_f32_16x16x32_bf16 v[120:123], v[136:139], v[166:169], v[120:123]
	v_mfma_f32_16x16x32_bf16 v[108:111], v[128:131], v[202:205], v[108:111]
	v_mfma_f32_16x16x32_bf16 v[104:107], v[136:139], v[202:205], v[104:107]
	v_mfma_f32_16x16x32_bf16 v[92:95], v[128:131], v[210:213], v[92:95]
	v_mfma_f32_16x16x32_bf16 v[88:91], v[136:139], v[210:213], v[88:91]
	v_mfma_f32_16x16x32_bf16 v[76:79], v[128:131], v[228:231], v[76:79]
	v_mfma_f32_16x16x32_bf16 v[72:75], v[136:139], v[228:231], v[72:75]
	v_mfma_f32_16x16x32_bf16 v[124:127], v[132:135], v[190:193], v[124:127]
	v_mfma_f32_16x16x32_bf16 v[120:123], v[140:143], v[190:193], v[120:123]
	v_mfma_f32_16x16x32_bf16 v[108:111], v[132:135], v[206:209], v[108:111]
	v_mfma_f32_16x16x32_bf16 v[104:107], v[140:143], v[206:209], v[104:107]
	v_mfma_f32_16x16x32_bf16 v[92:95], v[132:135], v[224:227], v[92:95]
	v_mfma_f32_16x16x32_bf16 v[88:91], v[140:143], v[224:227], v[88:91]
	v_mfma_f32_16x16x32_bf16 v[76:79], v[132:135], v[232:235], v[76:79]
	v_mfma_f32_16x16x32_bf16 v[72:75], v[140:143], v[232:235], v[72:75]
	v_mfma_f32_16x16x32_bf16 v[116:119], v[144:147], v[166:169], v[116:119]
	v_mfma_f32_16x16x32_bf16 v[112:115], v[158:161], v[166:169], v[112:115]
	v_mfma_f32_16x16x32_bf16 v[100:103], v[144:147], v[202:205], v[100:103]
	v_mfma_f32_16x16x32_bf16 v[96:99], v[158:161], v[202:205], v[96:99]
	v_mfma_f32_16x16x32_bf16 v[84:87], v[144:147], v[210:213], v[84:87]
	v_mfma_f32_16x16x32_bf16 v[80:83], v[158:161], v[210:213], v[80:83]
	v_mfma_f32_16x16x32_bf16 v[68:71], v[144:147], v[228:231], v[68:71]
	v_mfma_f32_16x16x32_bf16 v[64:67], v[158:161], v[228:231], v[64:67]
	v_mfma_f32_16x16x32_bf16 v[116:119], v[154:157], v[190:193], v[116:119]
	v_mfma_f32_16x16x32_bf16 v[112:115], v[162:165], v[190:193], v[112:115]
	v_mfma_f32_16x16x32_bf16 v[100:103], v[154:157], v[206:209], v[100:103]
	v_mfma_f32_16x16x32_bf16 v[96:99], v[162:165], v[206:209], v[96:99]
	v_mfma_f32_16x16x32_bf16 v[84:87], v[154:157], v[224:227], v[84:87]
	v_mfma_f32_16x16x32_bf16 v[80:83], v[162:165], v[224:227], v[80:83]
	v_mfma_f32_16x16x32_bf16 v[68:71], v[154:157], v[232:235], v[68:71]
	v_mfma_f32_16x16x32_bf16 v[64:67], v[162:165], v[232:235], v[64:67]
	s_barrier
	s_add_i32 s72, s75, s20
	s_mov_b32 m0, s72
	s_nop 0
	global_load_lds_dwordx4 v172, s[22:23]
	s_add_i32 m0, s72, 0x2000
	s_add_u32 s72, s22, 0x150000
	s_addc_u32 s73, s23, 0
	s_add_i32 s74, s76, s20
	global_load_lds_dwordx4 v152, s[22:23]
	s_mov_b32 m0, s74
	s_nop 0
	global_load_lds_dwordx4 v172, s[72:73]
	s_add_i32 m0, s74, 0x2000
	s_nop 0
	global_load_lds_dwordx4 v152, s[72:73]
	s_add_u32 vcc_lo, s70, 0x80
	s_addc_u32 vcc_hi, s71, 0
	s_mov_b32 m0, s21
	s_nop 0
	global_load_lds_dwordx4 v148, s[70:71]
	s_mov_b32 m0, s6
	s_nop 0
	global_load_lds_dwordx4 v150, s[70:71]
	ds_read_b128 v[166:169], v200 offset:16384
	ds_read_b128 v[190:193], v200 offset:17408
	ds_read_b128 v[202:205], v200 offset:18432
	ds_read_b128 v[206:209], v200 offset:19456
	ds_read_b128 v[210:213], v200 offset:20480
	ds_read_b128 v[224:227], v200 offset:21504
	ds_read_b128 v[228:231], v200 offset:22528
	ds_read_b128 v[232:235], v200 offset:23552
	s_waitcnt vmcnt(8) lgkmcnt(0)
	s_barrier
; #define PG8_STAGE(bufoff, gbase, voff) do { _Pragma("unroll") for (int _i = 0; _i < 2; ++_i) \
;         __builtin_amdgcn_global_load_lds((const unsigned*)((const char*)(gbase) + (voff)[_i]), (PG8_LAS unsigned*)(lds + (bufoff) + ldsw + _i * 8192), 16, 0, 0); } while (0)
; #define PG8_LDA(dst, b, h) do { _Pragma("unroll") for (int m = 0; m < 4; ++m) _Pragma("unroll") for (int k = 0; k < 2; ++k) dst[m][k] = *(const PG8_LAS bf16x8*)(lds + PG8_SA(b, h) + aoff + m * 2048 + k * 1024); } while (0)
; #define PG8_LDB(dst, b, h) do { _Pragma("unroll") for (int n = 0; n < 2; ++n) _Pragma("unroll") for (int k = 0; k < 2; ++k) dst[n][k] = *(const PG8_LAS bf16x8*)(lds + PG8_SB(b, h) + boff + n * 2048 + k * 1024); } while (0)
; #define PG8_MMA(ai, bj, At, Bt) do { __builtin_amdgcn_s_setprio(1); _Pragma("unroll") for (int m = 0; m < 4; ++m) _Pragma("unroll") for (int n = 0; n < 2; ++n) _Pragma("unroll") for (int k = 0; k < 2; ++k) \
;         acc[ai][bj][m][n] = __builtin_amdgcn_mfma_f32_16x16x32_bf16(Bt[n][k], At[m][k], acc[ai][bj][m][n], 0, 0, 0); __builtin_amdgcn_s_setprio(0); } while (0)
; #define PG8_WAIT_V(n) asm volatile("s_waitcnt vmcnt(" #n ")" ::: "memory")
; #define PG8_WAIT_L(n) asm volatile("s_waitcnt lgkmcnt(" #n ")" ::: "memory")
; #define PG8_BAR __builtin_amdgcn_s_barrier()
; #define PG8_SCHED __builtin_amdgcn_sched_barrier(0)
; template <class Epi, class Sched, bool ALIGN_EPI = false, bool SP2 = false>
; __device__ __forceinline__ void gemm_phase(PG8_LAS unsigned char* lds, const Gemm g, const Sched& S, const Epi& E, const int tid_in) {
;     ...
;             PG8_WAIT_V(8); PG8_WAIT_L(0); PG8_BAR; PG8_MMA(1, 0, At, B0); PG8_MMA(1, 1, At, B1); PG8_BAR; PG8_SCHED;
;             PG8_LDB(B0, 1, 0); PG8_LDB(B1, 1, 1); PG8_SCHED; PG8_LDA(At, 1, 0); PG8_STAGE(PG8_SA(0, 1), a2 + hstepA, voffA);
;             PG8_WAIT_V(8); PG8_WAIT_L(0); PG8_BAR; PG8_MMA(0, 0, At, B0); PG8_MMA(0, 1, At, B1); PG8_BAR; PG8_SCHED;
	v_mfma_f32_16x16x32_bf16 v[60:63], v[128:131], v[166:169], v[60:63]
	v_mfma_f32_16x16x32_bf16 v[56:59], v[136:139], v[166:169], v[56:59]
	v_mfma_f32_16x16x32_bf16 v[44:47], v[128:131], v[202:205], v[44:47]
	v_mfma_f32_16x16x32_bf16 v[40:43], v[136:139], v[202:205], v[40:43]
	v_mfma_f32_16x16x32_bf16 v[28:31], v[128:131], v[210:213], v[28:31]
	v_mfma_f32_16x16x32_bf16 v[24:27], v[136:139], v[210:213], v[24:27]
	v_mfma_f32_16x16x32_bf16 v[12:15], v[128:131], v[228:231], v[12:15]
	v_mfma_f32_16x16x32_bf16 v[8:11], v[136:139], v[228:231], v[8:11]
	v_mfma_f32_16x16x32_bf16 v[60:63], v[132:135], v[190:193], v[60:63]
	v_mfma_f32_16x16x32_bf16 v[56:59], v[140:143], v[190:193], v[56:59]
	v_mfma_f32_16x16x32_bf16 v[44:47], v[132:135], v[206:209], v[44:47]
	v_mfma_f32_16x16x32_bf16 v[40:43], v[140:143], v[206:209], v[40:43]
	v_mfma_f32_16x16x32_bf16 v[28:31], v[132:135], v[224:227], v[28:31]
	v_mfma_f32_16x16x32_bf16 v[24:27], v[140:143], v[224:227], v[24:27]
	v_mfma_f32_16x16x32_bf16 v[12:15], v[132:135], v[232:235], v[12:15]
	v_mfma_f32_16x16x32_bf16 v[8:11], v[140:143], v[232:235], v[8:11]
	v_mfma_f32_16x16x32_bf16 v[52:55], v[144:147], v[166:169], v[52:55]
	v_mfma_f32_16x16x32_bf16 v[48:51], v[158:161], v[166:169], v[48:51]
	v_mfma_f32_16x16x32_bf16 v[36:39], v[144:147], v[202:205], v[36:39]
	v_mfma_f32_16x16x32_bf16 v[32:35], v[158:161], v[202:205], v[32:35]
	v_mfma_f32_16x16x32_bf16 v[20:23], v[144:147], v[210:213], v[20:23]
	v_mfma_f32_16x16x32_bf16 v[16:19], v[158:161], v[210:213], v[16:19]
	v_mfma_f32_16x16x32_bf16 v[4:7], v[144:147], v[228:231], v[4:7]
	v_mfma_f32_16x16x32_bf16 v[0:3], v[158:161], v[228:231], v[0:3]
	v_mfma_f32_16x16x32_bf16 v[52:55], v[154:157], v[190:193], v[52:55]
	v_mfma_f32_16x16x32_bf16 v[48:51], v[162:165], v[190:193], v[48:51]
	v_mfma_f32_16x16x32_bf16 v[36:39], v[154:157], v[206:209], v[36:39]
	v_mfma_f32_16x16x32_bf16 v[32:35], v[162:165], v[206:209], v[32:35]
	v_mfma_f32_16x16x32_bf16 v[20:23], v[154:157], v[224:227], v[20:23]
	v_mfma_f32_16x16x32_bf16 v[16:19], v[162:165], v[224:227], v[16:19]
	v_mfma_f32_16x16x32_bf16 v[4:7], v[154:157], v[232:235], v[4:7]
	v_mfma_f32_16x16x32_bf16 v[0:3], v[162:165], v[232:235], v[0:3]
	s_barrier
	s_add_i32 s72, 0, 0x18000
	s_add_i32 s73, 0, 0x1c000
	s_add_u32 s70, s70, 0x150000
	s_addc_u32 s71, s71, 0
	s_mov_b32 m0, s34
	s_nop 0
	global_load_lds_dwordx4 v148, s[70:71]
	s_mov_b32 m0, s35
	s_nop 0
	global_load_lds_dwordx4 v150, s[70:71]
	ds_read_b128 v[128:131], v249 offset:32768
	ds_read_b128 v[132:135], v249 offset:33792
	ds_read_b128 v[136:139], v249 offset:34816
	ds_read_b128 v[140:143], v249 offset:35840
	ds_read_b128 v[144:147], v249 offset:49152
	ds_read_b128 v[154:157], v249 offset:50176
	ds_read_b128 v[158:161], v249 offset:51200
	ds_read_b128 v[162:165], v249 offset:52224
	ds_read_b128 v[166:169], v200 offset:32768
	ds_read_b128 v[190:193], v200 offset:33792
	ds_read_b128 v[202:205], v200 offset:34816
	ds_read_b128 v[206:209], v200 offset:35840
	ds_read_b128 v[210:213], v200 offset:36864
	ds_read_b128 v[224:227], v200 offset:37888
	ds_read_b128 v[228:231], v200 offset:38912
	ds_read_b128 v[232:235], v200 offset:39936
	s_waitcnt vmcnt(8) lgkmcnt(0)
	s_barrier
	v_mfma_f32_16x16x32_bf16 v[124:127], v[128:131], v[166:169], v[124:127]
	v_mfma_f32_16x16x32_bf16 v[120:123], v[136:139], v[166:169], v[120:123]
	v_mfma_f32_16x16x32_bf16 v[108:111], v[128:131], v[202:205], v[108:111]
	v_mfma_f32_16x16x32_bf16 v[104:107], v[136:139], v[202:205], v[104:107]
	v_mfma_f32_16x16x32_bf16 v[92:95], v[128:131], v[210:213], v[92:95]
	v_mfma_f32_16x16x32_bf16 v[88:91], v[136:139], v[210:213], v[88:91]
	v_mfma_f32_16x16x32_bf16 v[76:79], v[128:131], v[228:231], v[76:79]
	v_mfma_f32_16x16x32_bf16 v[72:75], v[136:139], v[228:231], v[72:75]
	v_mfma_f32_16x16x32_bf16 v[124:127], v[132:135], v[190:193], v[124:127]
	v_mfma_f32_16x16x32_bf16 v[120:123], v[140:143], v[190:193], v[120:123]
	v_mfma_f32_16x16x32_bf16 v[108:111], v[132:135], v[206:209], v[108:111]
	v_mfma_f32_16x16x32_bf16 v[104:107], v[140:143], v[206:209], v[104:107]
	v_mfma_f32_16x16x32_bf16 v[92:95], v[132:135], v[224:227], v[92:95]
	v_mfma_f32_16x16x32_bf16 v[88:91], v[140:143], v[224:227], v[88:91]
	v_mfma_f32_16x16x32_bf16 v[76:79], v[132:135], v[232:235], v[76:79]
	v_mfma_f32_16x16x32_bf16 v[72:75], v[140:143], v[232:235], v[72:75]
	v_mfma_f32_16x16x32_bf16 v[116:119], v[144:147], v[166:169], v[116:119]
	v_mfma_f32_16x16x32_bf16 v[112:115], v[158:161], v[166:169], v[112:115]
	v_mfma_f32_16x16x32_bf16 v[100:103], v[144:147], v[202:205], v[100:103]
	v_mfma_f32_16x16x32_bf16 v[96:99], v[158:161], v[202:205], v[96:99]
	v_mfma_f32_16x16x32_bf16 v[84:87], v[144:147], v[210:213], v[84:87]
	v_mfma_f32_16x16x32_bf16 v[80:83], v[158:161], v[210:213], v[80:83]
	v_mfma_f32_16x16x32_bf16 v[68:71], v[144:147], v[228:231], v[68:71]
	v_mfma_f32_16x16x32_bf16 v[64:67], v[158:161], v[228:231], v[64:67]
	v_mfma_f32_16x16x32_bf16 v[116:119], v[154:157], v[190:193], v[116:119]
	v_mfma_f32_16x16x32_bf16 v[112:115], v[162:165], v[190:193], v[112:115]
	v_mfma_f32_16x16x32_bf16 v[100:103], v[154:157], v[206:209], v[100:103]
	v_mfma_f32_16x16x32_bf16 v[96:99], v[162:165], v[206:209], v[96:99]
	v_mfma_f32_16x16x32_bf16 v[84:87], v[154:157], v[224:227], v[84:87]
	v_mfma_f32_16x16x32_bf16 v[80:83], v[162:165], v[224:227], v[80:83]
	v_mfma_f32_16x16x32_bf16 v[68:71], v[154:157], v[232:235], v[68:71]
	v_mfma_f32_16x16x32_bf16 v[64:67], v[162:165], v[232:235], v[64:67]
	s_barrier
; #define PG8_STAGE(bufoff, gbase, voff) do { _Pragma("unroll") for (int _i = 0; _i < 2; ++_i) \
;         __builtin_amdgcn_global_load_lds((const unsigned*)((const char*)(gbase) + (voff)[_i]), (PG8_LAS unsigned*)(lds + (bufoff) + ldsw + _i * 8192), 16, 0, 0); } while (0)
; #define PG8_LDA(dst, b, h) do { _Pragma("unroll") for (int m = 0; m < 4; ++m) _Pragma("unroll") for (int k = 0; k < 2; ++k) dst[m][k] = *(const PG8_LAS bf16x8*)(lds + PG8_SA(b, h) + aoff + m * 2048 + k * 1024); } while (0)
; #define PG8_MMA(ai, bj, At, Bt) do { __builtin_amdgcn_s_setprio(1); _Pragma("unroll") for (int m = 0; m < 4; ++m) _Pragma("unroll") for (int n = 0; n < 2; ++n) _Pragma("unroll") for (int k = 0; k < 2; ++k) \
;         acc[ai][bj][m][n] = __builtin_amdgcn_mfma_f32_16x16x32_bf16(Bt[n][k], At[m][k], acc[ai][bj][m][n], 0, 0, 0); __builtin_amdgcn_s_setprio(0); } while (0)
; #define PG8_WAIT_V(n) asm volatile("s_waitcnt vmcnt(" #n ")" ::: "memory")
; #define PG8_WAIT_L(n) asm volatile("s_waitcnt lgkmcnt(" #n ")" ::: "memory")
; #define PG8_BAR __builtin_amdgcn_s_barrier()
; #define PG8_SCHED __builtin_amdgcn_sched_barrier(0)
; template <class Epi, class Sched, bool ALIGN_EPI = false, bool SP2 = false>
; __device__ __forceinline__ void gemm_phase(PG8_LAS unsigned char* lds, const Gemm g, const Sched& S, const Epi& E, const int tid_in) {
;     ...
;         for (int t = 0; t < nt; t += 2) {
;     ...
;             PG8_LDA(At, 1, 1); PG8_STAGE(PG8_SB(1, 0), b3, voffB); PG8_STAGE(PG8_SB(1, 1), b3 + hstepB, voffB); PG8_STAGE(PG8_SA(1, 0), a3, voffA);
;             PG8_WAIT_V(8); PG8_WAIT_L(0); PG8_BAR; PG8_MMA(1, 0, At, B0); PG8_MMA(1, 1, At, B1); PG8_BAR; PG8_SCHED;
	s_add_i32 s70, s72, s20
	s_mov_b32 m0, s70
	s_add_u32 s100, s22, 0x80
	s_addc_u32 s101, s23, 0
	global_load_lds_dwordx4 v172, s[100:101]
	s_add_i32 m0, s70, 0x2000
	s_add_u32 s22, s22, 0x150080
	s_addc_u32 s23, s23, 0
	s_add_i32 s70, s73, s20
	global_load_lds_dwordx4 v152, s[100:101]
	s_mov_b32 m0, s70
	s_nop 0
	global_load_lds_dwordx4 v172, s[22:23]
	s_add_i32 m0, s70, 0x2000
	s_nop 0
	global_load_lds_dwordx4 v152, s[22:23]
	s_mov_b32 m0, s93
	s_nop 0
	global_load_lds_dwordx4 v148, vcc
	s_mov_b32 m0, s94
	s_nop 0
	global_load_lds_dwordx4 v150, vcc
	ds_read_b128 v[166:169], v200 offset:49152
	ds_read_b128 v[190:193], v200 offset:50176
	ds_read_b128 v[202:205], v200 offset:51200
	ds_read_b128 v[206:209], v200 offset:52224
	ds_read_b128 v[210:213], v200 offset:53248
	ds_read_b128 v[224:227], v200 offset:54272
	ds_read_b128 v[228:231], v200 offset:55296
	ds_read_b128 v[232:235], v200 offset:56320
	s_waitcnt vmcnt(8) lgkmcnt(0)
	s_barrier
	v_mfma_f32_16x16x32_bf16 v[60:63], v[128:131], v[166:169], v[60:63]
	v_mfma_f32_16x16x32_bf16 v[56:59], v[136:139], v[166:169], v[56:59]
	v_mfma_f32_16x16x32_bf16 v[44:47], v[128:131], v[202:205], v[44:47]
	v_mfma_f32_16x16x32_bf16 v[40:43], v[136:139], v[202:205], v[40:43]
	v_mfma_f32_16x16x32_bf16 v[28:31], v[128:131], v[210:213], v[28:31]
	v_mfma_f32_16x16x32_bf16 v[24:27], v[136:139], v[210:213], v[24:27]
	v_mfma_f32_16x16x32_bf16 v[12:15], v[128:131], v[228:231], v[12:15]
	v_mfma_f32_16x16x32_bf16 v[8:11], v[136:139], v[228:231], v[8:11]
	v_mfma_f32_16x16x32_bf16 v[60:63], v[132:135], v[190:193], v[60:63]
	v_mfma_f32_16x16x32_bf16 v[56:59], v[140:143], v[190:193], v[56:59]
	v_mfma_f32_16x16x32_bf16 v[44:47], v[132:135], v[206:209], v[44:47]
	v_mfma_f32_16x16x32_bf16 v[40:43], v[140:143], v[206:209], v[40:43]
	v_mfma_f32_16x16x32_bf16 v[28:31], v[132:135], v[224:227], v[28:31]
	v_mfma_f32_16x16x32_bf16 v[24:27], v[140:143], v[224:227], v[24:27]
	v_mfma_f32_16x16x32_bf16 v[12:15], v[132:135], v[232:235], v[12:15]
	v_mfma_f32_16x16x32_bf16 v[8:11], v[140:143], v[232:235], v[8:11]
	v_mfma_f32_16x16x32_bf16 v[52:55], v[144:147], v[166:169], v[52:55]
	v_mfma_f32_16x16x32_bf16 v[48:51], v[158:161], v[166:169], v[48:51]
	v_mfma_f32_16x16x32_bf16 v[36:39], v[144:147], v[202:205], v[36:39]
	v_mfma_f32_16x16x32_bf16 v[32:35], v[158:161], v[202:205], v[32:35]
	v_mfma_f32_16x16x32_bf16 v[20:23], v[144:147], v[210:213], v[20:23]
	v_mfma_f32_16x16x32_bf16 v[16:19], v[158:161], v[210:213], v[16:19]
	v_mfma_f32_16x16x32_bf16 v[4:7], v[144:147], v[228:231], v[4:7]
	v_mfma_f32_16x16x32_bf16 v[0:3], v[158:161], v[228:231], v[0:3]
	v_mfma_f32_16x16x32_bf16 v[52:55], v[154:157], v[190:193], v[52:55]
	v_mfma_f32_16x16x32_bf16 v[48:51], v[162:165], v[190:193], v[48:51]
	v_mfma_f32_16x16x32_bf16 v[36:39], v[154:157], v[206:209], v[36:39]
	v_mfma_f32_16x16x32_bf16 v[32:35], v[162:165], v[206:209], v[32:35]
	v_mfma_f32_16x16x32_bf16 v[20:23], v[154:157], v[224:227], v[20:23]
	v_mfma_f32_16x16x32_bf16 v[16:19], v[162:165], v[224:227], v[16:19]
	v_mfma_f32_16x16x32_bf16 v[4:7], v[154:157], v[232:235], v[4:7]
	v_mfma_f32_16x16x32_bf16 v[0:3], v[162:165], v[232:235], v[0:3]
	s_barrier
	s_add_i32 s22, s85, 2
	s_cmpk_gt_u32 s85, 0x51
	s_mov_b32 s85, s22
	s_cbranch_scc1 .LBB0_2387

;     __device__ __forceinline__ void a_ready(const Unit& u) const { wait_panel(cnt, u.pm, need, tmo, wave); }
;     __device__ __forceinline__ void a_ready(const Unit& u) const { wait_panel(cnt, u.pm, need, tmo, wave); }
; #define PG8_STAGE(bufoff, gbase, voff) do { _Pragma("unroll") for (int _i = 0; _i < 2; ++_i) \
;         __builtin_amdgcn_global_load_lds((const unsigned*)((const char*)(gbase) + (voff)[_i]), (PG8_LAS unsigned*)(lds + (bufoff) + ldsw + _i * 8192), 16, 0, 0); } while (0)
; #define PG8_LDA(dst, b, h) do { _Pragma("unroll") for (int m = 0; m < 4; ++m) _Pragma("unroll") for (int k = 0; k < 2; ++k) dst[m][k] = *(const PG8_LAS bf16x8*)(lds + PG8_SA(b, h) + aoff + m * 2048 + k * 1024); } while (0)
; #define PG8_LDB(dst, b, h) do { _Pragma("unroll") for (int n = 0; n < 2; ++n) _Pragma("unroll") for (int k = 0; k < 2; ++k) dst[n][k] = *(const PG8_LAS bf16x8*)(lds + PG8_SB(b, h) + boff + n * 2048 + k * 1024); } while (0)
; #define PG8_WAIT_V(n) asm volatile("s_waitcnt vmcnt(" #n ")" ::: "memory")
; #define PG8_WAIT_L(n) asm volatile("s_waitcnt lgkmcnt(" #n ")" ::: "memory")
; #define PG8_BAR __builtin_amdgcn_s_barrier()
; #define PG8_SCHED __builtin_amdgcn_sched_barrier(0)
; template <class Epi, class Sched, bool ALIGN_EPI = false, bool SP2 = false>
; __device__ __forceinline__ void gemm_phase(PG8_LAS unsigned char* lds, const Gemm g, const Sched& S, const Epi& E, const int tid_in) {
;     ...
;             const bool last = (t == nt - 2);
;             const char* a1 = cA + (size_t)(t + 1) * kstep;
;             const char* a2 = last ? nA : cA + (size_t)(t + 2) * kstep; const char* b2 = last ? nB : cB + (size_t)(t + 2) * kstep;
;             const char* a3 = a2 + kstep; const char* b3 = b2 + kstep;
;             if (last && has_next) S.a_ready(nxt);
;             if constexpr (SP2) {
;             PG8_LDB(B0, 0, 0); PG8_LDB(B1, 0, 1); PG8_SCHED; PG8_LDA(At, 0, 0); PG8_STAGE(PG8_SA(1, 1), a1 + hstepA, voffA);
;             PG8_WAIT_V(8); PG8_WAIT_L(0); PG8_BAR; PG8_MMA(0, 0, At, B0); PG8_MMA(0, 1, At, B1); PG8_BAR; PG8_SCHED;
;             PG8_LDA(At, 0, 1); PG8_STAGE(PG8_SB(0, 0), b2, voffB); PG8_STAGE(PG8_SB(0, 1), b2 + hstepB, voffB); PG8_STAGE(PG8_SA(0, 0), a2, voffA);
;             PG8_WAIT_V(8); PG8_WAIT_L(0); PG8_BAR; PG8_MMA(1, 0, At, B0); PG8_MMA(1, 1, At, B1); PG8_BAR; PG8_SCHED;
.LBB0_2427:
	s_lshl_b32 s74, s37, 7
	s_add_u32 s75, s62, s74
	s_addc_u32 s76, s63, 0
	s_add_u32 s77, s75, 0x100
	s_addc_u32 s85, s76, 0
	s_and_b64 s[72:73], s[22:23], exec
	s_cselect_b32 s73, s65, s85
	s_cselect_b32 s72, s64, s77
	s_add_u32 s74, s66, s74
	s_addc_u32 s77, s67, 0
	s_add_u32 s74, s74, 0x100
	s_addc_u32 s77, s77, 0
	s_and_b64 s[22:23], s[22:23], exec
	s_cselect_b32 s23, s69, s77
	s_cselect_b32 s22, s68, s74
	s_add_i32 s77, 0, 0x10000
	s_add_i32 s85, 0, 0x14000
	s_add_u32 s74, s75, 0x150080
	s_addc_u32 s75, s76, 0
	s_add_i32 m0, s17, 0xc000
	s_nop 0
	global_load_lds_dwordx4 v172, s[74:75]
	s_add_i32 m0, s17, 0xe000
	s_nop 0
	global_load_lds_dwordx4 v128, s[74:75]
	ds_read_b128 v[64:67], v249
	ds_read_b128 v[68:71], v249 offset:1024
	ds_read_b128 v[72:75], v249 offset:2048
	ds_read_b128 v[76:79], v249 offset:3072
	ds_read_b128 v[80:83], v249 offset:16384
	ds_read_b128 v[84:87], v249 offset:17408
	ds_read_b128 v[88:91], v249 offset:18432
	ds_read_b128 v[92:95], v249 offset:19456
	ds_read_b128 v[96:99], v150
	ds_read_b128 v[100:103], v150 offset:1024
	ds_read_b128 v[104:107], v150 offset:2048
	ds_read_b128 v[108:111], v150 offset:3072
	ds_read_b128 v[112:115], v150 offset:4096
	ds_read_b128 v[116:119], v150 offset:5120
	ds_read_b128 v[120:123], v150 offset:6144
	ds_read_b128 v[124:127], v150 offset:7168
	s_waitcnt vmcnt(8) lgkmcnt(0)
	s_barrier
	v_mfma_f32_16x16x32_bf16 v[60:63], v[64:67], v[96:99], v[60:63]
	v_mfma_f32_16x16x32_bf16 v[56:59], v[72:75], v[96:99], v[56:59]
	v_mfma_f32_16x16x32_bf16 v[44:47], v[64:67], v[104:107], v[44:47]
	v_mfma_f32_16x16x32_bf16 v[40:43], v[72:75], v[104:107], v[40:43]
	v_mfma_f32_16x16x32_bf16 v[32:35], v[64:67], v[112:115], v[32:35]
	v_mfma_f32_16x16x32_bf16 v[24:27], v[72:75], v[112:115], v[24:27]
	v_mfma_f32_16x16x32_bf16 v[16:19], v[64:67], v[120:123], v[16:19]
	v_mfma_f32_16x16x32_bf16 v[8:11], v[72:75], v[120:123], v[8:11]
	v_mfma_f32_16x16x32_bf16 v[60:63], v[68:71], v[100:103], v[60:63]
	v_mfma_f32_16x16x32_bf16 v[56:59], v[76:79], v[100:103], v[56:59]
	v_mfma_f32_16x16x32_bf16 v[44:47], v[68:71], v[108:111], v[44:47]
	v_mfma_f32_16x16x32_bf16 v[40:43], v[76:79], v[108:111], v[40:43]
	v_mfma_f32_16x16x32_bf16 v[32:35], v[68:71], v[116:119], v[32:35]
	v_mfma_f32_16x16x32_bf16 v[24:27], v[76:79], v[116:119], v[24:27]
	v_mfma_f32_16x16x32_bf16 v[16:19], v[68:71], v[124:127], v[16:19]
	v_mfma_f32_16x16x32_bf16 v[8:11], v[76:79], v[124:127], v[8:11]
	v_mfma_f32_16x16x32_bf16 v[52:55], v[80:83], v[96:99], v[52:55]
	v_mfma_f32_16x16x32_bf16 v[48:51], v[88:91], v[96:99], v[48:51]
	v_mfma_f32_16x16x32_bf16 v[36:39], v[80:83], v[104:107], v[36:39]
	v_mfma_f32_16x16x32_bf16 v[28:31], v[88:91], v[104:107], v[28:31]
	v_mfma_f32_16x16x32_bf16 v[20:23], v[80:83], v[112:115], v[20:23]
	v_mfma_f32_16x16x32_bf16 v[12:15], v[88:91], v[112:115], v[12:15]
	v_mfma_f32_16x16x32_bf16 v[4:7], v[80:83], v[120:123], v[4:7]
	v_mfma_f32_16x16x32_bf16 v[0:3], v[88:91], v[120:123], v[0:3]
	v_mfma_f32_16x16x32_bf16 v[52:55], v[84:87], v[100:103], v[52:55]
	v_mfma_f32_16x16x32_bf16 v[48:51], v[92:95], v[100:103], v[48:51]
	v_mfma_f32_16x16x32_bf16 v[36:39], v[84:87], v[108:111], v[36:39]
	v_mfma_f32_16x16x32_bf16 v[28:31], v[92:95], v[108:111], v[28:31]
	v_mfma_f32_16x16x32_bf16 v[20:23], v[84:87], v[116:119], v[20:23]
	v_mfma_f32_16x16x32_bf16 v[12:15], v[92:95], v[116:119], v[12:15]
	v_mfma_f32_16x16x32_bf16 v[4:7], v[84:87], v[124:127], v[4:7]
	v_mfma_f32_16x16x32_bf16 v[0:3], v[92:95], v[124:127], v[0:3]
	s_barrier
	s_add_i32 s74, s77, s16
	s_mov_b32 m0, s74
	s_nop 0
	global_load_lds_dwordx4 v172, s[22:23]
	s_add_i32 m0, s74, 0x2000
	s_add_u32 s74, s22, 0x150000
	s_addc_u32 s75, s23, 0
	s_add_i32 s76, s85, s16
	global_load_lds_dwordx4 v128, s[22:23]
	s_mov_b32 m0, s76
	s_add_u32 vcc_lo, s72, 0x80
	s_addc_u32 vcc_hi, s73, 0
	global_load_lds_dwordx4 v172, s[74:75]
	s_add_i32 m0, s76, 0x2000
	s_nop 0
	global_load_lds_dwordx4 v128, s[74:75]
	s_mov_b32 m0, s17
	s_nop 0
	global_load_lds_dwordx4 v172, s[72:73]
	s_mov_b32 m0, s20
	s_nop 0
	global_load_lds_dwordx4 v128, s[72:73]
	s_waitcnt vmcnt(8) lgkmcnt(0)
	s_barrier
; #define PG8_STAGE(bufoff, gbase, voff) do { _Pragma("unroll") for (int _i = 0; _i < 2; ++_i) \
;         __builtin_amdgcn_global_load_lds((const unsigned*)((const char*)(gbase) + (voff)[_i]), (PG8_LAS unsigned*)(lds + (bufoff) + ldsw + _i * 8192), 16, 0, 0); } while (0)
; #define PG8_LDA(dst, b, h) do { _Pragma("unroll") for (int m = 0; m < 4; ++m) _Pragma("unroll") for (int k = 0; k < 2; ++k) dst[m][k] = *(const PG8_LAS bf16x8*)(lds + PG8_SA(b, h) + aoff + m * 2048 + k * 1024); } while (0)
; #define PG8_LDB(dst, b, h) do { _Pragma("unroll") for (int n = 0; n < 2; ++n) _Pragma("unroll") for (int k = 0; k < 2; ++k) dst[n][k] = *(const PG8_LAS bf16x8*)(lds + PG8_SB(b, h) + boff + n * 2048 + k * 1024); } while (0)
; #define PG8_MMA(ai, bj, At, Bt) do { __builtin_amdgcn_s_setprio(1); _Pragma("unroll") for (int m = 0; m < 4; ++m) _Pragma("unroll") for (int n = 0; n < 2; ++n) _Pragma("unroll") for (int k = 0; k < 2; ++k) \
;         acc[ai][bj][m][n] = __builtin_amdgcn_mfma_f32_16x16x32_bf16(Bt[n][k], At[m][k], acc[ai][bj][m][n], 0, 0, 0); __builtin_amdgcn_s_setprio(0); } while (0)
; #define PG8_WAIT_V(n) asm volatile("s_waitcnt vmcnt(" #n ")" ::: "memory")
; #define PG8_WAIT_L(n) asm volatile("s_waitcnt lgkmcnt(" #n ")" ::: "memory")
; #define PG8_BAR __builtin_amdgcn_s_barrier()
; #define PG8_SCHED __builtin_amdgcn_sched_barrier(0)
; template <class Epi, class Sched, bool ALIGN_EPI = false, bool SP2 = false>
; __device__ __forceinline__ void gemm_phase(PG8_LAS unsigned char* lds, const Gemm g, const Sched& S, const Epi& E, const int tid_in) {
;     ...
;             PG8_LDB(B0, 1, 0); PG8_LDB(B1, 1, 1); PG8_SCHED; PG8_LDA(At, 1, 0); PG8_STAGE(PG8_SA(0, 1), a2 + hstepA, voffA);
;             PG8_WAIT_V(8); PG8_WAIT_L(0); PG8_BAR; PG8_MMA(0, 0, At, B0); PG8_MMA(0, 1, At, B1); PG8_BAR; PG8_SCHED;
;             PG8_LDA(At, 1, 1); PG8_STAGE(PG8_SB(1, 0), b3, voffB); PG8_STAGE(PG8_SB(1, 1), b3 + hstepB, voffB); PG8_STAGE(PG8_SA(1, 0), a3, voffA);
;             PG8_WAIT_V(8); PG8_WAIT_L(0); PG8_BAR; PG8_MMA(1, 0, At, B0); PG8_MMA(1, 1, At, B1); PG8_BAR; PG8_SCHED;
	s_barrier
	s_add_i32 s74, 0, 0x18000
	s_add_i32 s75, 0, 0x1c000
	s_add_u32 s72, s72, 0x150000
	s_addc_u32 s73, s73, 0
	s_mov_b32 m0, s21
	s_nop 0
	global_load_lds_dwordx4 v172, s[72:73]
	s_mov_b32 m0, s31
	s_nop 0
	global_load_lds_dwordx4 v128, s[72:73]
	ds_read_b128 v[64:67], v249 offset:32768
	ds_read_b128 v[68:71], v249 offset:33792
	ds_read_b128 v[72:75], v249 offset:34816
	ds_read_b128 v[76:79], v249 offset:35840
	ds_read_b128 v[80:83], v249 offset:49152
	ds_read_b128 v[84:87], v249 offset:50176
	ds_read_b128 v[88:91], v249 offset:51200
	ds_read_b128 v[92:95], v249 offset:52224
	ds_read_b128 v[96:99], v150 offset:32768
	ds_read_b128 v[100:103], v150 offset:33792
	ds_read_b128 v[104:107], v150 offset:34816
	ds_read_b128 v[108:111], v150 offset:35840
	ds_read_b128 v[112:115], v150 offset:36864
	ds_read_b128 v[116:119], v150 offset:37888
	ds_read_b128 v[120:123], v150 offset:38912
	ds_read_b128 v[124:127], v150 offset:39936
	s_waitcnt vmcnt(8) lgkmcnt(0)
	s_barrier
	v_mfma_f32_16x16x32_bf16 v[60:63], v[64:67], v[96:99], v[60:63]
	v_mfma_f32_16x16x32_bf16 v[56:59], v[72:75], v[96:99], v[56:59]
	v_mfma_f32_16x16x32_bf16 v[44:47], v[64:67], v[104:107], v[44:47]
	v_mfma_f32_16x16x32_bf16 v[40:43], v[72:75], v[104:107], v[40:43]
	v_mfma_f32_16x16x32_bf16 v[32:35], v[64:67], v[112:115], v[32:35]
	v_mfma_f32_16x16x32_bf16 v[24:27], v[72:75], v[112:115], v[24:27]
	v_mfma_f32_16x16x32_bf16 v[16:19], v[64:67], v[120:123], v[16:19]
	v_mfma_f32_16x16x32_bf16 v[8:11], v[72:75], v[120:123], v[8:11]
	v_mfma_f32_16x16x32_bf16 v[60:63], v[68:71], v[100:103], v[60:63]
	v_mfma_f32_16x16x32_bf16 v[56:59], v[76:79], v[100:103], v[56:59]
	v_mfma_f32_16x16x32_bf16 v[44:47], v[68:71], v[108:111], v[44:47]
	v_mfma_f32_16x16x32_bf16 v[40:43], v[76:79], v[108:111], v[40:43]
	v_mfma_f32_16x16x32_bf16 v[32:35], v[68:71], v[116:119], v[32:35]
	v_mfma_f32_16x16x32_bf16 v[24:27], v[76:79], v[116:119], v[24:27]
	v_mfma_f32_16x16x32_bf16 v[16:19], v[68:71], v[124:127], v[16:19]
	v_mfma_f32_16x16x32_bf16 v[8:11], v[76:79], v[124:127], v[8:11]
	v_mfma_f32_16x16x32_bf16 v[52:55], v[80:83], v[96:99], v[52:55]
	v_mfma_f32_16x16x32_bf16 v[48:51], v[88:91], v[96:99], v[48:51]
	v_mfma_f32_16x16x32_bf16 v[36:39], v[80:83], v[104:107], v[36:39]
	v_mfma_f32_16x16x32_bf16 v[28:31], v[88:91], v[104:107], v[28:31]
	v_mfma_f32_16x16x32_bf16 v[20:23], v[80:83], v[112:115], v[20:23]
	v_mfma_f32_16x16x32_bf16 v[12:15], v[88:91], v[112:115], v[12:15]
	v_mfma_f32_16x16x32_bf16 v[4:7], v[80:83], v[120:123], v[4:7]
	v_mfma_f32_16x16x32_bf16 v[0:3], v[88:91], v[120:123], v[0:3]
	v_mfma_f32_16x16x32_bf16 v[52:55], v[84:87], v[100:103], v[52:55]
	v_mfma_f32_16x16x32_bf16 v[48:51], v[92:95], v[100:103], v[48:51]
	v_mfma_f32_16x16x32_bf16 v[36:39], v[84:87], v[108:111], v[36:39]
	v_mfma_f32_16x16x32_bf16 v[28:31], v[92:95], v[108:111], v[28:31]
	v_mfma_f32_16x16x32_bf16 v[20:23], v[84:87], v[116:119], v[20:23]
	v_mfma_f32_16x16x32_bf16 v[12:15], v[92:95], v[116:119], v[12:15]
	v_mfma_f32_16x16x32_bf16 v[4:7], v[84:87], v[124:127], v[4:7]
	v_mfma_f32_16x16x32_bf16 v[0:3], v[92:95], v[124:127], v[0:3]
	s_barrier
	s_add_i32 s72, s74, s16
	s_mov_b32 m0, s72
	s_nop 0
	s_add_u32 s100, s22, 0x80
	s_addc_u32 s101, s23, 0
	global_load_lds_dwordx4 v172, s[100:101]
	s_add_i32 m0, s72, 0x2000
	s_add_u32 s22, s22, 0x150080
	s_addc_u32 s23, s23, 0
	s_add_i32 s72, s75, s16
	global_load_lds_dwordx4 v128, s[100:101]
	s_mov_b32 m0, s72
	s_nop 0
	global_load_lds_dwordx4 v172, s[22:23]
	s_add_i32 m0, s72, 0x2000
	s_nop 0
	global_load_lds_dwordx4 v128, s[22:23]
	s_mov_b32 m0, s33
	s_nop 0
	global_load_lds_dwordx4 v172, vcc
	s_mov_b32 m0, s34
	s_nop 0
	global_load_lds_dwordx4 v128, vcc
	s_waitcnt vmcnt(8) lgkmcnt(0)
	s_barrier
	s_barrier
	s_add_i32 s22, s37, 2
	s_cmp_gt_u32 s37, 9
	s_mov_b32 s37, s22
	s_cbranch_scc1 .LBB0_2442
